# K-loops: fragment waits coalesced to one s_waitcnt lgkmcnt per fragment group (3 per stage instead of 11; 2 instead of 7 in BRANCH)
# speedup vs baseline: 1.0057x; 1.0057x over previous
; #define BLOAD(A_, B_, kt) do { _Pragma("unroll") for (int i = 0; i < 4; ++i) { \
;     A_[i] = *(const u32x4*)((const char*)Ap + (aoff + (unsigned)(32 * i * lda + (kt) * 64) * 2u)); B_[i] = *(const u32x4*)((const char*)Wt + (woff + (unsigned)(32 * i * K + (kt) * 64) * 2u)); } } while (0)
; #define BLOAD(A_, B_, kt) do { _Pragma("unroll") for (int i = 0; i < 4; ++i) { \
;     A_[i] = *(const u32x4*)((const char*)Ap + (aoff + (unsigned)(32 * i * lda + (kt) * 64) * 2u)); B_[i] = *(const u32x4*)((const char*)Wt + (woff + (unsigned)(32 * i * K + (kt) * 64) * 2u)); } } while (0)
; #define BSTORE(A_, B_, buf) do { _Pragma("unroll") for (int i = 0; i < 4; ++i) { \
;     *(u32x4*)&As[(buf) * GBUF + (srow + 32 * i) * LDT + sc8] = A_[i]; \
;     *(u32x4*)&Bs[(buf) * GBUF + (srow + 32 * i) * LDT + sc8] = B_[i]; } } while (0)
; template <int NK>
; DI void gemm_run(PF& pf, const u16* __restrict__ Ap, int lda, const u16* __restrict__ Wt, f32x16 (&acc)[2][2], char* smem) {
;     ...
;   __builtin_amdgcn_s_setprio(0);
;   __syncthreads();
;   BSTORE(pf.a0, pf.b0, 0);
;   BLOAD(pf.a0, pf.b0, 2);
;   __syncthreads();
; #pragma unroll
;   for (int kt = 0; kt < nk; kt += 2) {
;     BCOMP(0);
;     BSTORE(pf.a1, pf.b1, 1);
;     if (kt + 3 < nk) BLOAD(pf.a1, pf.b1, kt + 3);
;     __syncthreads();
;     BCOMP(1);
;     if (kt + 2 < nk) { BSTORE(pf.a0, pf.b0, 0); if (kt + 4 < nk) BLOAD(pf.a0, pf.b0, kt + 4); }
;     __syncthreads();
; DI void tile_ffn2(const Params& p, int l, const Chunk& ck, int tile, int next, PF& pf, char* smem) {
;     ...
;   { const u16* Ap; const u16* Wt; ffn2_ptrs(p, l, tile, Ap, Wt); gemm_run<64>(pf, Ap, 4096, Wt, acc, smem); }
.Lffn2_kloop:
	s_waitcnt vmcnt(6)
	s_barrier
	ds_read_b128 v[224:227], v126 offset:0
	ds_read_b128 v[240:243], v128 offset:0
	ds_read_b128 v[244:247], v128 offset:1024
	ds_read_b128 v[248:251], v128 offset:2048
	ds_read_b128 v[156:159], v128 offset:3072
	s_add_u32 m0, s16, 0xc000
	s_add_u32 s42, s42, 0x100000
	s_addc_u32 s43, s43, 0
	global_load_lds_dwordx4 v137, s[42:43]
	global_load_lds_dwordx4 v150, s[42:43] offset:1024
	s_add_u32 m0, s0, 0xc000
	s_add_u32 s30, s30, 0x10000
	s_addc_u32 s31, s31, 0
	global_load_lds_dwordx4 v151, s[30:31]
	global_load_lds_dwordx4 v152, s[30:31] offset:1024
	global_load_lds_dwordx4 v153, s[30:31] offset:2048
	global_load_lds_dwordx4 v154, s[30:31] offset:3072
	ds_read_b128 v[228:231], v126 offset:1024
	ds_read_b128 v[232:235], v126 offset:2048
	ds_read_b128 v[236:239], v126 offset:3072
	ds_read_b128 v[160:163], v128 offset:8192
	ds_read_b128 v[164:167], v128 offset:9216
	ds_read_b128 v[168:171], v128 offset:10240
	ds_read_b128 v[122:125], v128 offset:11264
	s_waitcnt lgkmcnt(7)
	v_mfma_f32_16x16x32_bf16 v[2:5], v[240:243], v[224:227], v[2:5]
	v_mfma_f32_16x16x32_bf16 v[6:9], v[244:247], v[224:227], v[6:9]
	v_mfma_f32_16x16x32_bf16 v[10:13], v[248:251], v[224:227], v[10:13]
	v_mfma_f32_16x16x32_bf16 v[14:17], v[156:159], v[224:227], v[14:17]
	s_waitcnt lgkmcnt(4)
	v_mfma_f32_16x16x32_bf16 v[18:21], v[240:243], v[228:231], v[18:21]
	v_mfma_f32_16x16x32_bf16 v[22:25], v[244:247], v[228:231], v[22:25]
	v_mfma_f32_16x16x32_bf16 v[26:29], v[248:251], v[228:231], v[26:29]
	v_mfma_f32_16x16x32_bf16 v[30:33], v[156:159], v[228:231], v[30:33]
	v_mfma_f32_16x16x32_bf16 v[34:37], v[240:243], v[232:235], v[34:37]
	v_mfma_f32_16x16x32_bf16 v[38:41], v[244:247], v[232:235], v[38:41]
	v_mfma_f32_16x16x32_bf16 v[42:45], v[248:251], v[232:235], v[42:45]
	v_mfma_f32_16x16x32_bf16 v[46:49], v[156:159], v[232:235], v[46:49]
	v_mfma_f32_16x16x32_bf16 v[50:53], v[240:243], v[236:239], v[50:53]
	v_mfma_f32_16x16x32_bf16 v[54:57], v[244:247], v[236:239], v[54:57]
	v_mfma_f32_16x16x32_bf16 v[58:61], v[248:251], v[236:239], v[58:61]
	v_mfma_f32_16x16x32_bf16 v[62:65], v[156:159], v[236:239], v[62:65]
	s_waitcnt lgkmcnt(0)
	v_mfma_f32_16x16x32_bf16 v[74:77], v[160:163], v[224:227], v[74:77]
	v_mfma_f32_16x16x32_bf16 v[78:81], v[164:167], v[224:227], v[78:81]
	v_mfma_f32_16x16x32_bf16 v[82:85], v[168:171], v[224:227], v[82:85]
	v_mfma_f32_16x16x32_bf16 v[86:89], v[122:125], v[224:227], v[86:89]
	v_mfma_f32_16x16x32_bf16 v[90:93], v[160:163], v[228:231], v[90:93]
	v_mfma_f32_16x16x32_bf16 v[94:97], v[164:167], v[228:231], v[94:97]
	v_mfma_f32_16x16x32_bf16 v[98:101], v[168:171], v[228:231], v[98:101]
	v_mfma_f32_16x16x32_bf16 v[102:105], v[122:125], v[228:231], v[102:105]
	v_mfma_f32_16x16x32_bf16 v[106:109], v[160:163], v[232:235], v[106:109]
	v_mfma_f32_16x16x32_bf16 v[110:113], v[164:167], v[232:235], v[110:113]
	v_mfma_f32_16x16x32_bf16 v[114:117], v[168:171], v[232:235], v[114:117]
	v_mfma_f32_16x16x32_bf16 v[118:121], v[122:125], v[232:235], v[118:121]
	v_mfma_f32_16x16x32_bf16 v[208:211], v[160:163], v[236:239], v[208:211]
	v_mfma_f32_16x16x32_bf16 v[212:215], v[164:167], v[236:239], v[212:215]
	v_mfma_f32_16x16x32_bf16 v[216:219], v[168:171], v[236:239], v[216:219]
	v_mfma_f32_16x16x32_bf16 v[220:223], v[122:125], v[236:239], v[220:223]
	s_waitcnt vmcnt(6)
	s_barrier
	ds_read_b128 v[224:227], v126 offset:24576
	ds_read_b128 v[240:243], v128 offset:24576
	ds_read_b128 v[244:247], v128 offset:25600
	ds_read_b128 v[248:251], v128 offset:26624
	ds_read_b128 v[156:159], v128 offset:27648
	s_add_u32 m0, s16, 0x0
	s_add_u32 s42, s42, 0x100000
	s_addc_u32 s43, s43, 0
	global_load_lds_dwordx4 v137, s[42:43]
	global_load_lds_dwordx4 v150, s[42:43] offset:1024
	s_add_u32 m0, s0, 0x0
	s_add_u32 s30, s30, 0x10000
	s_addc_u32 s31, s31, 0
	global_load_lds_dwordx4 v151, s[30:31]
	global_load_lds_dwordx4 v152, s[30:31] offset:1024
	global_load_lds_dwordx4 v153, s[30:31] offset:2048
	global_load_lds_dwordx4 v154, s[30:31] offset:3072
	ds_read_b128 v[228:231], v126 offset:25600
	ds_read_b128 v[232:235], v126 offset:26624
	ds_read_b128 v[236:239], v126 offset:27648
	ds_read_b128 v[160:163], v128 offset:32768
	ds_read_b128 v[164:167], v128 offset:33792
	ds_read_b128 v[168:171], v128 offset:34816
	ds_read_b128 v[122:125], v128 offset:35840
	s_waitcnt lgkmcnt(7)
	v_mfma_f32_16x16x32_bf16 v[2:5], v[240:243], v[224:227], v[2:5]
	v_mfma_f32_16x16x32_bf16 v[6:9], v[244:247], v[224:227], v[6:9]
	v_mfma_f32_16x16x32_bf16 v[10:13], v[248:251], v[224:227], v[10:13]
	v_mfma_f32_16x16x32_bf16 v[14:17], v[156:159], v[224:227], v[14:17]
	s_waitcnt lgkmcnt(4)
	v_mfma_f32_16x16x32_bf16 v[18:21], v[240:243], v[228:231], v[18:21]
	v_mfma_f32_16x16x32_bf16 v[22:25], v[244:247], v[228:231], v[22:25]
	v_mfma_f32_16x16x32_bf16 v[26:29], v[248:251], v[228:231], v[26:29]
	v_mfma_f32_16x16x32_bf16 v[30:33], v[156:159], v[228:231], v[30:33]
	v_mfma_f32_16x16x32_bf16 v[34:37], v[240:243], v[232:235], v[34:37]
	v_mfma_f32_16x16x32_bf16 v[38:41], v[244:247], v[232:235], v[38:41]
	v_mfma_f32_16x16x32_bf16 v[42:45], v[248:251], v[232:235], v[42:45]
	v_mfma_f32_16x16x32_bf16 v[46:49], v[156:159], v[232:235], v[46:49]
	v_mfma_f32_16x16x32_bf16 v[50:53], v[240:243], v[236:239], v[50:53]
	v_mfma_f32_16x16x32_bf16 v[54:57], v[244:247], v[236:239], v[54:57]
	v_mfma_f32_16x16x32_bf16 v[58:61], v[248:251], v[236:239], v[58:61]
	v_mfma_f32_16x16x32_bf16 v[62:65], v[156:159], v[236:239], v[62:65]
	s_waitcnt lgkmcnt(0)
	v_mfma_f32_16x16x32_bf16 v[74:77], v[160:163], v[224:227], v[74:77]
	v_mfma_f32_16x16x32_bf16 v[78:81], v[164:167], v[224:227], v[78:81]
	v_mfma_f32_16x16x32_bf16 v[82:85], v[168:171], v[224:227], v[82:85]
	v_mfma_f32_16x16x32_bf16 v[86:89], v[122:125], v[224:227], v[86:89]
	v_mfma_f32_16x16x32_bf16 v[90:93], v[160:163], v[228:231], v[90:93]
	v_mfma_f32_16x16x32_bf16 v[94:97], v[164:167], v[228:231], v[94:97]
	v_mfma_f32_16x16x32_bf16 v[98:101], v[168:171], v[228:231], v[98:101]
	v_mfma_f32_16x16x32_bf16 v[102:105], v[122:125], v[228:231], v[102:105]
	v_mfma_f32_16x16x32_bf16 v[106:109], v[160:163], v[232:235], v[106:109]
	v_mfma_f32_16x16x32_bf16 v[110:113], v[164:167], v[232:235], v[110:113]
	v_mfma_f32_16x16x32_bf16 v[114:117], v[168:171], v[232:235], v[114:117]
	v_mfma_f32_16x16x32_bf16 v[118:121], v[122:125], v[232:235], v[118:121]
	v_mfma_f32_16x16x32_bf16 v[208:211], v[160:163], v[236:239], v[208:211]
	v_mfma_f32_16x16x32_bf16 v[212:215], v[164:167], v[236:239], v[212:215]
	v_mfma_f32_16x16x32_bf16 v[216:219], v[168:171], v[236:239], v[216:219]
	v_mfma_f32_16x16x32_bf16 v[220:223], v[122:125], v[236:239], v[220:223]
	s_waitcnt vmcnt(6)
	s_barrier
; #define BLOAD(A_, B_, kt) do { _Pragma("unroll") for (int i = 0; i < 4; ++i) { \
;     A_[i] = *(const u32x4*)((const char*)Ap + (aoff + (unsigned)(32 * i * lda + (kt) * 64) * 2u)); B_[i] = *(const u32x4*)((const char*)Wt + (woff + (unsigned)(32 * i * K + (kt) * 64) * 2u)); } } while (0)
; #define BLOAD(A_, B_, kt) do { _Pragma("unroll") for (int i = 0; i < 4; ++i) { \
;     A_[i] = *(const u32x4*)((const char*)Ap + (aoff + (unsigned)(32 * i * lda + (kt) * 64) * 2u)); B_[i] = *(const u32x4*)((const char*)Wt + (woff + (unsigned)(32 * i * K + (kt) * 64) * 2u)); } } while (0)
; #define BSTORE(A_, B_, buf) do { _Pragma("unroll") for (int i = 0; i < 4; ++i) { \
;     *(u32x4*)&As[(buf) * GBUF + (srow + 32 * i) * LDT + sc8] = A_[i]; \
;     *(u32x4*)&Bs[(buf) * GBUF + (srow + 32 * i) * LDT + sc8] = B_[i]; } } while (0)
; template <int NK>
; DI void gemm_run(PF& pf, const u16* __restrict__ Ap, int lda, const u16* __restrict__ Wt, f32x16 (&acc)[2][2], char* smem) {
;     ...
;   __builtin_amdgcn_s_setprio(0);
;   __syncthreads();
;   BSTORE(pf.a0, pf.b0, 0);
;   BLOAD(pf.a0, pf.b0, 2);
;   __syncthreads();
; #pragma unroll
;   for (int kt = 0; kt < nk; kt += 2) {
;     BCOMP(0);
;     BSTORE(pf.a1, pf.b1, 1);
;     if (kt + 3 < nk) BLOAD(pf.a1, pf.b1, kt + 3);
;     __syncthreads();
;     BCOMP(1);
;     if (kt + 2 < nk) { BSTORE(pf.a0, pf.b0, 0); if (kt + 4 < nk) BLOAD(pf.a0, pf.b0, kt + 4); }
;     __syncthreads();
	ds_read_b128 v[224:227], v126 offset:49152
	ds_read_b128 v[240:243], v128 offset:49152
	ds_read_b128 v[244:247], v128 offset:50176
	ds_read_b128 v[248:251], v128 offset:51200
	ds_read_b128 v[156:159], v128 offset:52224
	s_add_u32 m0, s16, 0x6000
	s_add_u32 s42, s42, 0x100000
	s_addc_u32 s43, s43, 0
	global_load_lds_dwordx4 v137, s[42:43]
	global_load_lds_dwordx4 v150, s[42:43] offset:1024
	s_add_u32 m0, s0, 0x6000
	s_add_u32 s30, s30, 0x10000
	s_addc_u32 s31, s31, 0
	global_load_lds_dwordx4 v151, s[30:31]
	global_load_lds_dwordx4 v152, s[30:31] offset:1024
	global_load_lds_dwordx4 v153, s[30:31] offset:2048
	global_load_lds_dwordx4 v154, s[30:31] offset:3072
	ds_read_b128 v[228:231], v126 offset:50176
	ds_read_b128 v[232:235], v126 offset:51200
	ds_read_b128 v[236:239], v126 offset:52224
	ds_read_b128 v[160:163], v128 offset:57344
	ds_read_b128 v[164:167], v128 offset:58368
	ds_read_b128 v[168:171], v128 offset:59392
	ds_read_b128 v[122:125], v128 offset:60416
	s_waitcnt lgkmcnt(7)
	v_mfma_f32_16x16x32_bf16 v[2:5], v[240:243], v[224:227], v[2:5]
	v_mfma_f32_16x16x32_bf16 v[6:9], v[244:247], v[224:227], v[6:9]
	v_mfma_f32_16x16x32_bf16 v[10:13], v[248:251], v[224:227], v[10:13]
	v_mfma_f32_16x16x32_bf16 v[14:17], v[156:159], v[224:227], v[14:17]
	s_waitcnt lgkmcnt(4)
	v_mfma_f32_16x16x32_bf16 v[18:21], v[240:243], v[228:231], v[18:21]
	v_mfma_f32_16x16x32_bf16 v[22:25], v[244:247], v[228:231], v[22:25]
	v_mfma_f32_16x16x32_bf16 v[26:29], v[248:251], v[228:231], v[26:29]
	v_mfma_f32_16x16x32_bf16 v[30:33], v[156:159], v[228:231], v[30:33]
	v_mfma_f32_16x16x32_bf16 v[34:37], v[240:243], v[232:235], v[34:37]
	v_mfma_f32_16x16x32_bf16 v[38:41], v[244:247], v[232:235], v[38:41]
	v_mfma_f32_16x16x32_bf16 v[42:45], v[248:251], v[232:235], v[42:45]
	v_mfma_f32_16x16x32_bf16 v[46:49], v[156:159], v[232:235], v[46:49]
	v_mfma_f32_16x16x32_bf16 v[50:53], v[240:243], v[236:239], v[50:53]
	v_mfma_f32_16x16x32_bf16 v[54:57], v[244:247], v[236:239], v[54:57]
	v_mfma_f32_16x16x32_bf16 v[58:61], v[248:251], v[236:239], v[58:61]
	v_mfma_f32_16x16x32_bf16 v[62:65], v[156:159], v[236:239], v[62:65]
	s_waitcnt lgkmcnt(0)
	v_mfma_f32_16x16x32_bf16 v[74:77], v[160:163], v[224:227], v[74:77]
	v_mfma_f32_16x16x32_bf16 v[78:81], v[164:167], v[224:227], v[78:81]
	v_mfma_f32_16x16x32_bf16 v[82:85], v[168:171], v[224:227], v[82:85]
	v_mfma_f32_16x16x32_bf16 v[86:89], v[122:125], v[224:227], v[86:89]
	v_mfma_f32_16x16x32_bf16 v[90:93], v[160:163], v[228:231], v[90:93]
	v_mfma_f32_16x16x32_bf16 v[94:97], v[164:167], v[228:231], v[94:97]
	v_mfma_f32_16x16x32_bf16 v[98:101], v[168:171], v[228:231], v[98:101]
	v_mfma_f32_16x16x32_bf16 v[102:105], v[122:125], v[228:231], v[102:105]
	v_mfma_f32_16x16x32_bf16 v[106:109], v[160:163], v[232:235], v[106:109]
	v_mfma_f32_16x16x32_bf16 v[110:113], v[164:167], v[232:235], v[110:113]
	v_mfma_f32_16x16x32_bf16 v[114:117], v[168:171], v[232:235], v[114:117]
	v_mfma_f32_16x16x32_bf16 v[118:121], v[122:125], v[232:235], v[118:121]
	v_mfma_f32_16x16x32_bf16 v[208:211], v[160:163], v[236:239], v[208:211]
	v_mfma_f32_16x16x32_bf16 v[212:215], v[164:167], v[236:239], v[212:215]
	v_mfma_f32_16x16x32_bf16 v[216:219], v[168:171], v[236:239], v[216:219]
	v_mfma_f32_16x16x32_bf16 v[220:223], v[122:125], v[236:239], v[220:223]
	s_sub_u32 s46, s46, 1
	s_cmp_lg_u32 s46, 0
	s_cbranch_scc1 .Lffn2_kloop
	s_waitcnt vmcnt(6)
	s_barrier
; #define BLOAD(A_, B_, kt) do { _Pragma("unroll") for (int i = 0; i < 4; ++i) { \
;     A_[i] = *(const u32x4*)((const char*)Ap + (aoff + (unsigned)(32 * i * lda + (kt) * 64) * 2u)); B_[i] = *(const u32x4*)((const char*)Wt + (woff + (unsigned)(32 * i * K + (kt) * 64) * 2u)); } } while (0)
; #define BLOAD(A_, B_, kt) do { _Pragma("unroll") for (int i = 0; i < 4; ++i) { \
;     A_[i] = *(const u32x4*)((const char*)Ap + (aoff + (unsigned)(32 * i * lda + (kt) * 64) * 2u)); B_[i] = *(const u32x4*)((const char*)Wt + (woff + (unsigned)(32 * i * K + (kt) * 64) * 2u)); } } while (0)
; #define BSTORE(A_, B_, buf) do { _Pragma("unroll") for (int i = 0; i < 4; ++i) { \
;     *(u32x4*)&As[(buf) * GBUF + (srow + 32 * i) * LDT + sc8] = A_[i]; \
;     *(u32x4*)&Bs[(buf) * GBUF + (srow + 32 * i) * LDT + sc8] = B_[i]; } } while (0)
; template <int NK>
; DI void gemm_run(PF& pf, const u16* __restrict__ Ap, int lda, const u16* __restrict__ Wt, f32x16 (&acc)[2][2], char* smem) {
;     ...
; #pragma unroll
;   for (int kt = 0; kt < nk; kt += 2) {
;     BCOMP(0);
;     BSTORE(pf.a1, pf.b1, 1);
;     if (kt + 3 < nk) BLOAD(pf.a1, pf.b1, kt + 3);
;     __syncthreads();
;     BCOMP(1);
;     if (kt + 2 < nk) { BSTORE(pf.a0, pf.b0, 0); if (kt + 4 < nk) BLOAD(pf.a0, pf.b0, kt + 4); }
;     __syncthreads();
;   }
	ds_read_b128 v[224:227], v126 offset:0
	ds_read_b128 v[240:243], v128 offset:0
	ds_read_b128 v[244:247], v128 offset:1024
	ds_read_b128 v[248:251], v128 offset:2048
	ds_read_b128 v[156:159], v128 offset:3072
	ds_read_b128 v[228:231], v126 offset:1024
	ds_read_b128 v[232:235], v126 offset:2048
	ds_read_b128 v[236:239], v126 offset:3072
	ds_read_b128 v[160:163], v128 offset:8192
	ds_read_b128 v[164:167], v128 offset:9216
	ds_read_b128 v[168:171], v128 offset:10240
	ds_read_b128 v[122:125], v128 offset:11264
	s_waitcnt lgkmcnt(7)
	v_mfma_f32_16x16x32_bf16 v[2:5], v[240:243], v[224:227], v[2:5]
	v_mfma_f32_16x16x32_bf16 v[6:9], v[244:247], v[224:227], v[6:9]
	v_mfma_f32_16x16x32_bf16 v[10:13], v[248:251], v[224:227], v[10:13]
	v_mfma_f32_16x16x32_bf16 v[14:17], v[156:159], v[224:227], v[14:17]
	s_waitcnt lgkmcnt(4)
	v_mfma_f32_16x16x32_bf16 v[18:21], v[240:243], v[228:231], v[18:21]
	v_mfma_f32_16x16x32_bf16 v[22:25], v[244:247], v[228:231], v[22:25]
	v_mfma_f32_16x16x32_bf16 v[26:29], v[248:251], v[228:231], v[26:29]
	v_mfma_f32_16x16x32_bf16 v[30:33], v[156:159], v[228:231], v[30:33]
	v_mfma_f32_16x16x32_bf16 v[34:37], v[240:243], v[232:235], v[34:37]
	v_mfma_f32_16x16x32_bf16 v[38:41], v[244:247], v[232:235], v[38:41]
	v_mfma_f32_16x16x32_bf16 v[42:45], v[248:251], v[232:235], v[42:45]
	v_mfma_f32_16x16x32_bf16 v[46:49], v[156:159], v[232:235], v[46:49]
	v_mfma_f32_16x16x32_bf16 v[50:53], v[240:243], v[236:239], v[50:53]
	v_mfma_f32_16x16x32_bf16 v[54:57], v[244:247], v[236:239], v[54:57]
	v_mfma_f32_16x16x32_bf16 v[58:61], v[248:251], v[236:239], v[58:61]
	v_mfma_f32_16x16x32_bf16 v[62:65], v[156:159], v[236:239], v[62:65]
	s_waitcnt lgkmcnt(0)
	v_mfma_f32_16x16x32_bf16 v[74:77], v[160:163], v[224:227], v[74:77]
	v_mfma_f32_16x16x32_bf16 v[78:81], v[164:167], v[224:227], v[78:81]
	v_mfma_f32_16x16x32_bf16 v[82:85], v[168:171], v[224:227], v[82:85]
	v_mfma_f32_16x16x32_bf16 v[86:89], v[122:125], v[224:227], v[86:89]
	v_mfma_f32_16x16x32_bf16 v[90:93], v[160:163], v[228:231], v[90:93]
	v_mfma_f32_16x16x32_bf16 v[94:97], v[164:167], v[228:231], v[94:97]
	v_mfma_f32_16x16x32_bf16 v[98:101], v[168:171], v[228:231], v[98:101]
	v_mfma_f32_16x16x32_bf16 v[102:105], v[122:125], v[228:231], v[102:105]
	v_mfma_f32_16x16x32_bf16 v[106:109], v[160:163], v[232:235], v[106:109]
	v_mfma_f32_16x16x32_bf16 v[110:113], v[164:167], v[232:235], v[110:113]
	v_mfma_f32_16x16x32_bf16 v[114:117], v[168:171], v[232:235], v[114:117]
	v_mfma_f32_16x16x32_bf16 v[118:121], v[122:125], v[232:235], v[118:121]
	v_mfma_f32_16x16x32_bf16 v[208:211], v[160:163], v[236:239], v[208:211]
	v_mfma_f32_16x16x32_bf16 v[212:215], v[164:167], v[236:239], v[212:215]
	v_mfma_f32_16x16x32_bf16 v[216:219], v[168:171], v[236:239], v[216:219]
	v_mfma_f32_16x16x32_bf16 v[220:223], v[122:125], v[236:239], v[220:223]
	s_waitcnt vmcnt(0)
	s_barrier
	ds_read_b128 v[224:227], v126 offset:24576
	ds_read_b128 v[240:243], v128 offset:24576
	ds_read_b128 v[244:247], v128 offset:25600
	ds_read_b128 v[248:251], v128 offset:26624
	ds_read_b128 v[156:159], v128 offset:27648
	ds_read_b128 v[228:231], v126 offset:25600
	ds_read_b128 v[232:235], v126 offset:26624
	ds_read_b128 v[236:239], v126 offset:27648
	ds_read_b128 v[160:163], v128 offset:32768
	ds_read_b128 v[164:167], v128 offset:33792
	ds_read_b128 v[168:171], v128 offset:34816
	ds_read_b128 v[122:125], v128 offset:35840
	s_waitcnt lgkmcnt(7)
	v_mfma_f32_16x16x32_bf16 v[2:5], v[240:243], v[224:227], v[2:5]
	v_mfma_f32_16x16x32_bf16 v[6:9], v[244:247], v[224:227], v[6:9]
	v_mfma_f32_16x16x32_bf16 v[10:13], v[248:251], v[224:227], v[10:13]
	v_mfma_f32_16x16x32_bf16 v[14:17], v[156:159], v[224:227], v[14:17]
	s_waitcnt lgkmcnt(4)
	v_mfma_f32_16x16x32_bf16 v[18:21], v[240:243], v[228:231], v[18:21]
	v_mfma_f32_16x16x32_bf16 v[22:25], v[244:247], v[228:231], v[22:25]
	v_mfma_f32_16x16x32_bf16 v[26:29], v[248:251], v[228:231], v[26:29]
	v_mfma_f32_16x16x32_bf16 v[30:33], v[156:159], v[228:231], v[30:33]
	v_mfma_f32_16x16x32_bf16 v[34:37], v[240:243], v[232:235], v[34:37]
	v_mfma_f32_16x16x32_bf16 v[38:41], v[244:247], v[232:235], v[38:41]
	v_mfma_f32_16x16x32_bf16 v[42:45], v[248:251], v[232:235], v[42:45]
	v_mfma_f32_16x16x32_bf16 v[46:49], v[156:159], v[232:235], v[46:49]
	v_mfma_f32_16x16x32_bf16 v[50:53], v[240:243], v[236:239], v[50:53]
	v_mfma_f32_16x16x32_bf16 v[54:57], v[244:247], v[236:239], v[54:57]
	v_mfma_f32_16x16x32_bf16 v[58:61], v[248:251], v[236:239], v[58:61]
	v_mfma_f32_16x16x32_bf16 v[62:65], v[156:159], v[236:239], v[62:65]
	s_waitcnt lgkmcnt(0)
	v_mfma_f32_16x16x32_bf16 v[74:77], v[160:163], v[224:227], v[74:77]
	v_mfma_f32_16x16x32_bf16 v[78:81], v[164:167], v[224:227], v[78:81]
	v_mfma_f32_16x16x32_bf16 v[82:85], v[168:171], v[224:227], v[82:85]
	v_mfma_f32_16x16x32_bf16 v[86:89], v[122:125], v[224:227], v[86:89]
	v_mfma_f32_16x16x32_bf16 v[90:93], v[160:163], v[228:231], v[90:93]
	v_mfma_f32_16x16x32_bf16 v[94:97], v[164:167], v[228:231], v[94:97]
	v_mfma_f32_16x16x32_bf16 v[98:101], v[168:171], v[228:231], v[98:101]
	v_mfma_f32_16x16x32_bf16 v[102:105], v[122:125], v[228:231], v[102:105]
	v_mfma_f32_16x16x32_bf16 v[106:109], v[160:163], v[232:235], v[106:109]
	v_mfma_f32_16x16x32_bf16 v[110:113], v[164:167], v[232:235], v[110:113]
	v_mfma_f32_16x16x32_bf16 v[114:117], v[168:171], v[232:235], v[114:117]
	v_mfma_f32_16x16x32_bf16 v[118:121], v[122:125], v[232:235], v[118:121]
	v_mfma_f32_16x16x32_bf16 v[208:211], v[160:163], v[236:239], v[208:211]
	v_mfma_f32_16x16x32_bf16 v[212:215], v[164:167], v[236:239], v[212:215]
	v_mfma_f32_16x16x32_bf16 v[216:219], v[168:171], v[236:239], v[216:219]
	v_mfma_f32_16x16x32_bf16 v[220:223], v[122:125], v[236:239], v[220:223]
	s_barrier
	s_mov_b32 s16, 0

; #define BLOAD(A_, B_, kt) do { _Pragma("unroll") for (int i = 0; i < 4; ++i) { \
;     A_[i] = *(const u32x4*)((const char*)Ap + (aoff + (unsigned)(32 * i * lda + (kt) * 64) * 2u)); B_[i] = *(const u32x4*)((const char*)Wt + (woff + (unsigned)(32 * i * K + (kt) * 64) * 2u)); } } while (0)
; #define BLOAD(A_, B_, kt) do { _Pragma("unroll") for (int i = 0; i < 4; ++i) { \
;     A_[i] = *(const u32x4*)((const char*)Ap + (aoff + (unsigned)(32 * i * lda + (kt) * 64) * 2u)); B_[i] = *(const u32x4*)((const char*)Wt + (woff + (unsigned)(32 * i * K + (kt) * 64) * 2u)); } } while (0)
; #define BSTORE(A_, B_, buf) do { _Pragma("unroll") for (int i = 0; i < 4; ++i) { \
;     *(u32x4*)&As[(buf) * GBUF + (srow + 32 * i) * LDT + sc8] = A_[i]; \
;     *(u32x4*)&Bs[(buf) * GBUF + (srow + 32 * i) * LDT + sc8] = B_[i]; } } while (0)
; template <int NK>
; DI void gemm_run(PF& pf, const u16* __restrict__ Ap, int lda, const u16* __restrict__ Wt, f32x16 (&acc)[2][2], char* smem) {
;     ...
;   __builtin_amdgcn_s_setprio(0);
;   __syncthreads();
;   BSTORE(pf.a0, pf.b0, 0);
;   BLOAD(pf.a0, pf.b0, 2);
;   __syncthreads();
; #pragma unroll
;   for (int kt = 0; kt < nk; kt += 2) {
;     BCOMP(0);
;     BSTORE(pf.a1, pf.b1, 1);
;     if (kt + 3 < nk) BLOAD(pf.a1, pf.b1, kt + 3);
;     __syncthreads();
;     BCOMP(1);
;     if (kt + 2 < nk) { BSTORE(pf.a0, pf.b0, 0); if (kt + 4 < nk) BLOAD(pf.a0, pf.b0, kt + 4); }
;     __syncthreads();
; DI void tile_ffn1(const Params& p, int l, const Chunk& ck, int tile, int next, PF& pf, char* smem) {
;     ...
;   { const u16* Ap; const u16* Wt; ffn1_ptrs(p, l, tile, Ap, Wt); gemm_run<16>(pf, Ap, 1024, Wt, acc, smem); }
.Lffn1_kloop:
	s_waitcnt vmcnt(6)
	s_barrier
	ds_read_b128 v[208:211], v138 offset:0
	ds_read_b128 v[224:227], v140 offset:0
	ds_read_b128 v[228:231], v140 offset:1024
	ds_read_b128 v[232:235], v140 offset:2048
	ds_read_b128 v[236:239], v140 offset:3072
	s_add_u32 m0, s42, 0xc000
	s_add_u32 s28, s28, 0x100000
	s_addc_u32 s29, s29, 0
	global_load_lds_dwordx4 v142, s[28:29]
	global_load_lds_dwordx4 v143, s[28:29] offset:1024
	s_add_u32 m0, s43, 0xc000
	s_add_u32 s30, s30, 0x40000
	s_addc_u32 s31, s31, 0
	global_load_lds_dwordx4 v144, s[30:31]
	global_load_lds_dwordx4 v145, s[30:31] offset:1024
	global_load_lds_dwordx4 v146, s[30:31] offset:2048
	global_load_lds_dwordx4 v147, s[30:31] offset:3072
	ds_read_b128 v[212:215], v138 offset:1024
	ds_read_b128 v[216:219], v138 offset:2048
	ds_read_b128 v[220:223], v138 offset:3072
	ds_read_b128 v[240:243], v140 offset:8192
	ds_read_b128 v[244:247], v140 offset:9216
	ds_read_b128 v[248:251], v140 offset:10240
	ds_read_b128 v[156:159], v140 offset:11264
	s_waitcnt lgkmcnt(7)
	v_mfma_f32_16x16x32_bf16 v[2:5], v[224:227], v[208:211], v[2:5]
	v_mfma_f32_16x16x32_bf16 v[6:9], v[228:231], v[208:211], v[6:9]
	v_mfma_f32_16x16x32_bf16 v[10:13], v[232:235], v[208:211], v[10:13]
	v_mfma_f32_16x16x32_bf16 v[14:17], v[236:239], v[208:211], v[14:17]
	s_waitcnt lgkmcnt(4)
	v_mfma_f32_16x16x32_bf16 v[18:21], v[224:227], v[212:215], v[18:21]
	v_mfma_f32_16x16x32_bf16 v[22:25], v[228:231], v[212:215], v[22:25]
	v_mfma_f32_16x16x32_bf16 v[26:29], v[232:235], v[212:215], v[26:29]
	v_mfma_f32_16x16x32_bf16 v[30:33], v[236:239], v[212:215], v[30:33]
	v_mfma_f32_16x16x32_bf16 v[34:37], v[224:227], v[216:219], v[34:37]
	v_mfma_f32_16x16x32_bf16 v[38:41], v[228:231], v[216:219], v[38:41]
	v_mfma_f32_16x16x32_bf16 v[42:45], v[232:235], v[216:219], v[42:45]
	v_mfma_f32_16x16x32_bf16 v[46:49], v[236:239], v[216:219], v[46:49]
	v_mfma_f32_16x16x32_bf16 v[50:53], v[224:227], v[220:223], v[50:53]
	v_mfma_f32_16x16x32_bf16 v[54:57], v[228:231], v[220:223], v[54:57]
	v_mfma_f32_16x16x32_bf16 v[58:61], v[232:235], v[220:223], v[58:61]
	v_mfma_f32_16x16x32_bf16 v[62:65], v[236:239], v[220:223], v[62:65]
	s_waitcnt lgkmcnt(0)
	v_mfma_f32_16x16x32_bf16 v[74:77], v[240:243], v[208:211], v[74:77]
	v_mfma_f32_16x16x32_bf16 v[78:81], v[244:247], v[208:211], v[78:81]
	v_mfma_f32_16x16x32_bf16 v[82:85], v[248:251], v[208:211], v[82:85]
	v_mfma_f32_16x16x32_bf16 v[86:89], v[156:159], v[208:211], v[86:89]
	v_mfma_f32_16x16x32_bf16 v[90:93], v[240:243], v[212:215], v[90:93]
	v_mfma_f32_16x16x32_bf16 v[94:97], v[244:247], v[212:215], v[94:97]
	v_mfma_f32_16x16x32_bf16 v[98:101], v[248:251], v[212:215], v[98:101]
	v_mfma_f32_16x16x32_bf16 v[102:105], v[156:159], v[212:215], v[102:105]
	v_mfma_f32_16x16x32_bf16 v[106:109], v[240:243], v[216:219], v[106:109]
	v_mfma_f32_16x16x32_bf16 v[110:113], v[244:247], v[216:219], v[110:113]
	v_mfma_f32_16x16x32_bf16 v[114:117], v[248:251], v[216:219], v[114:117]
	v_mfma_f32_16x16x32_bf16 v[118:121], v[156:159], v[216:219], v[118:121]
	v_mfma_f32_16x16x32_bf16 v[122:125], v[240:243], v[220:223], v[122:125]
	v_mfma_f32_16x16x32_bf16 v[126:129], v[244:247], v[220:223], v[126:129]
	v_mfma_f32_16x16x32_bf16 v[130:133], v[248:251], v[220:223], v[130:133]
	v_mfma_f32_16x16x32_bf16 v[134:137], v[156:159], v[220:223], v[134:137]
	s_waitcnt vmcnt(6)
	s_barrier
	ds_read_b128 v[208:211], v138 offset:24576
	ds_read_b128 v[224:227], v140 offset:24576
	ds_read_b128 v[228:231], v140 offset:25600
	ds_read_b128 v[232:235], v140 offset:26624
	ds_read_b128 v[236:239], v140 offset:27648
	s_add_u32 m0, s42, 0x0
	s_add_u32 s28, s28, 0x100000
	s_addc_u32 s29, s29, 0
	global_load_lds_dwordx4 v142, s[28:29]
	global_load_lds_dwordx4 v143, s[28:29] offset:1024
	s_add_u32 m0, s43, 0x0
	s_add_u32 s30, s30, 0x40000
	s_addc_u32 s31, s31, 0
	global_load_lds_dwordx4 v144, s[30:31]
	global_load_lds_dwordx4 v145, s[30:31] offset:1024
	global_load_lds_dwordx4 v146, s[30:31] offset:2048
	global_load_lds_dwordx4 v147, s[30:31] offset:3072
	ds_read_b128 v[212:215], v138 offset:25600
	ds_read_b128 v[216:219], v138 offset:26624
	ds_read_b128 v[220:223], v138 offset:27648
	ds_read_b128 v[240:243], v140 offset:32768
	ds_read_b128 v[244:247], v140 offset:33792
	ds_read_b128 v[248:251], v140 offset:34816
	ds_read_b128 v[156:159], v140 offset:35840
	s_waitcnt lgkmcnt(7)
	v_mfma_f32_16x16x32_bf16 v[2:5], v[224:227], v[208:211], v[2:5]
	v_mfma_f32_16x16x32_bf16 v[6:9], v[228:231], v[208:211], v[6:9]
	v_mfma_f32_16x16x32_bf16 v[10:13], v[232:235], v[208:211], v[10:13]
	v_mfma_f32_16x16x32_bf16 v[14:17], v[236:239], v[208:211], v[14:17]
	s_waitcnt lgkmcnt(4)
	v_mfma_f32_16x16x32_bf16 v[18:21], v[224:227], v[212:215], v[18:21]
	v_mfma_f32_16x16x32_bf16 v[22:25], v[228:231], v[212:215], v[22:25]
	v_mfma_f32_16x16x32_bf16 v[26:29], v[232:235], v[212:215], v[26:29]
	v_mfma_f32_16x16x32_bf16 v[30:33], v[236:239], v[212:215], v[30:33]
	v_mfma_f32_16x16x32_bf16 v[34:37], v[224:227], v[216:219], v[34:37]
	v_mfma_f32_16x16x32_bf16 v[38:41], v[228:231], v[216:219], v[38:41]
	v_mfma_f32_16x16x32_bf16 v[42:45], v[232:235], v[216:219], v[42:45]
	v_mfma_f32_16x16x32_bf16 v[46:49], v[236:239], v[216:219], v[46:49]
	v_mfma_f32_16x16x32_bf16 v[50:53], v[224:227], v[220:223], v[50:53]
	v_mfma_f32_16x16x32_bf16 v[54:57], v[228:231], v[220:223], v[54:57]
	v_mfma_f32_16x16x32_bf16 v[58:61], v[232:235], v[220:223], v[58:61]
	v_mfma_f32_16x16x32_bf16 v[62:65], v[236:239], v[220:223], v[62:65]
	s_waitcnt lgkmcnt(0)
	v_mfma_f32_16x16x32_bf16 v[74:77], v[240:243], v[208:211], v[74:77]
	v_mfma_f32_16x16x32_bf16 v[78:81], v[244:247], v[208:211], v[78:81]
	v_mfma_f32_16x16x32_bf16 v[82:85], v[248:251], v[208:211], v[82:85]
	v_mfma_f32_16x16x32_bf16 v[86:89], v[156:159], v[208:211], v[86:89]
	v_mfma_f32_16x16x32_bf16 v[90:93], v[240:243], v[212:215], v[90:93]
	v_mfma_f32_16x16x32_bf16 v[94:97], v[244:247], v[212:215], v[94:97]
	v_mfma_f32_16x16x32_bf16 v[98:101], v[248:251], v[212:215], v[98:101]
	v_mfma_f32_16x16x32_bf16 v[102:105], v[156:159], v[212:215], v[102:105]
	v_mfma_f32_16x16x32_bf16 v[106:109], v[240:243], v[216:219], v[106:109]
	v_mfma_f32_16x16x32_bf16 v[110:113], v[244:247], v[216:219], v[110:113]
	v_mfma_f32_16x16x32_bf16 v[114:117], v[248:251], v[216:219], v[114:117]
	v_mfma_f32_16x16x32_bf16 v[118:121], v[156:159], v[216:219], v[118:121]
	v_mfma_f32_16x16x32_bf16 v[122:125], v[240:243], v[220:223], v[122:125]
	v_mfma_f32_16x16x32_bf16 v[126:129], v[244:247], v[220:223], v[126:129]
	v_mfma_f32_16x16x32_bf16 v[130:133], v[248:251], v[220:223], v[130:133]
	v_mfma_f32_16x16x32_bf16 v[134:137], v[156:159], v[220:223], v[134:137]
	s_waitcnt vmcnt(6)
	s_barrier
; #define BLOAD(A_, B_, kt) do { _Pragma("unroll") for (int i = 0; i < 4; ++i) { \
;     A_[i] = *(const u32x4*)((const char*)Ap + (aoff + (unsigned)(32 * i * lda + (kt) * 64) * 2u)); B_[i] = *(const u32x4*)((const char*)Wt + (woff + (unsigned)(32 * i * K + (kt) * 64) * 2u)); } } while (0)
; #define BLOAD(A_, B_, kt) do { _Pragma("unroll") for (int i = 0; i < 4; ++i) { \
;     A_[i] = *(const u32x4*)((const char*)Ap + (aoff + (unsigned)(32 * i * lda + (kt) * 64) * 2u)); B_[i] = *(const u32x4*)((const char*)Wt + (woff + (unsigned)(32 * i * K + (kt) * 64) * 2u)); } } while (0)
; #define BSTORE(A_, B_, buf) do { _Pragma("unroll") for (int i = 0; i < 4; ++i) { \
;     *(u32x4*)&As[(buf) * GBUF + (srow + 32 * i) * LDT + sc8] = A_[i]; \
;     *(u32x4*)&Bs[(buf) * GBUF + (srow + 32 * i) * LDT + sc8] = B_[i]; } } while (0)
; template <int NK>
; DI void gemm_run(PF& pf, const u16* __restrict__ Ap, int lda, const u16* __restrict__ Wt, f32x16 (&acc)[2][2], char* smem) {
;     ...
;   __builtin_amdgcn_s_setprio(0);
;   __syncthreads();
;   BSTORE(pf.a0, pf.b0, 0);
;   BLOAD(pf.a0, pf.b0, 2);
;   __syncthreads();
; #pragma unroll
;   for (int kt = 0; kt < nk; kt += 2) {
;     BCOMP(0);
;     BSTORE(pf.a1, pf.b1, 1);
;     if (kt + 3 < nk) BLOAD(pf.a1, pf.b1, kt + 3);
;     __syncthreads();
;     BCOMP(1);
;     if (kt + 2 < nk) { BSTORE(pf.a0, pf.b0, 0); if (kt + 4 < nk) BLOAD(pf.a0, pf.b0, kt + 4); }
;     __syncthreads();
	ds_read_b128 v[208:211], v138 offset:49152
	ds_read_b128 v[224:227], v140 offset:49152
	ds_read_b128 v[228:231], v140 offset:50176
	ds_read_b128 v[232:235], v140 offset:51200
	ds_read_b128 v[236:239], v140 offset:52224
	s_add_u32 m0, s42, 0x6000
	s_add_u32 s28, s28, 0x100000
	s_addc_u32 s29, s29, 0
	global_load_lds_dwordx4 v142, s[28:29]
	global_load_lds_dwordx4 v143, s[28:29] offset:1024
	s_add_u32 m0, s43, 0x6000
	s_add_u32 s30, s30, 0x40000
	s_addc_u32 s31, s31, 0
	global_load_lds_dwordx4 v144, s[30:31]
	global_load_lds_dwordx4 v145, s[30:31] offset:1024
	global_load_lds_dwordx4 v146, s[30:31] offset:2048
	global_load_lds_dwordx4 v147, s[30:31] offset:3072
	ds_read_b128 v[212:215], v138 offset:50176
	ds_read_b128 v[216:219], v138 offset:51200
	ds_read_b128 v[220:223], v138 offset:52224
	ds_read_b128 v[240:243], v140 offset:57344
	ds_read_b128 v[244:247], v140 offset:58368
	ds_read_b128 v[248:251], v140 offset:59392
	ds_read_b128 v[156:159], v140 offset:60416
	s_waitcnt lgkmcnt(7)
	v_mfma_f32_16x16x32_bf16 v[2:5], v[224:227], v[208:211], v[2:5]
	v_mfma_f32_16x16x32_bf16 v[6:9], v[228:231], v[208:211], v[6:9]
	v_mfma_f32_16x16x32_bf16 v[10:13], v[232:235], v[208:211], v[10:13]
	v_mfma_f32_16x16x32_bf16 v[14:17], v[236:239], v[208:211], v[14:17]
	s_waitcnt lgkmcnt(4)
	v_mfma_f32_16x16x32_bf16 v[18:21], v[224:227], v[212:215], v[18:21]
	v_mfma_f32_16x16x32_bf16 v[22:25], v[228:231], v[212:215], v[22:25]
	v_mfma_f32_16x16x32_bf16 v[26:29], v[232:235], v[212:215], v[26:29]
	v_mfma_f32_16x16x32_bf16 v[30:33], v[236:239], v[212:215], v[30:33]
	v_mfma_f32_16x16x32_bf16 v[34:37], v[224:227], v[216:219], v[34:37]
	v_mfma_f32_16x16x32_bf16 v[38:41], v[228:231], v[216:219], v[38:41]
	v_mfma_f32_16x16x32_bf16 v[42:45], v[232:235], v[216:219], v[42:45]
	v_mfma_f32_16x16x32_bf16 v[46:49], v[236:239], v[216:219], v[46:49]
	v_mfma_f32_16x16x32_bf16 v[50:53], v[224:227], v[220:223], v[50:53]
	v_mfma_f32_16x16x32_bf16 v[54:57], v[228:231], v[220:223], v[54:57]
	v_mfma_f32_16x16x32_bf16 v[58:61], v[232:235], v[220:223], v[58:61]
	v_mfma_f32_16x16x32_bf16 v[62:65], v[236:239], v[220:223], v[62:65]
	s_waitcnt lgkmcnt(0)
	v_mfma_f32_16x16x32_bf16 v[74:77], v[240:243], v[208:211], v[74:77]
	v_mfma_f32_16x16x32_bf16 v[78:81], v[244:247], v[208:211], v[78:81]
	v_mfma_f32_16x16x32_bf16 v[82:85], v[248:251], v[208:211], v[82:85]
	v_mfma_f32_16x16x32_bf16 v[86:89], v[156:159], v[208:211], v[86:89]
	v_mfma_f32_16x16x32_bf16 v[90:93], v[240:243], v[212:215], v[90:93]
	v_mfma_f32_16x16x32_bf16 v[94:97], v[244:247], v[212:215], v[94:97]
	v_mfma_f32_16x16x32_bf16 v[98:101], v[248:251], v[212:215], v[98:101]
	v_mfma_f32_16x16x32_bf16 v[102:105], v[156:159], v[212:215], v[102:105]
	v_mfma_f32_16x16x32_bf16 v[106:109], v[240:243], v[216:219], v[106:109]
	v_mfma_f32_16x16x32_bf16 v[110:113], v[244:247], v[216:219], v[110:113]
	v_mfma_f32_16x16x32_bf16 v[114:117], v[248:251], v[216:219], v[114:117]
	v_mfma_f32_16x16x32_bf16 v[118:121], v[156:159], v[216:219], v[118:121]
	v_mfma_f32_16x16x32_bf16 v[122:125], v[240:243], v[220:223], v[122:125]
	v_mfma_f32_16x16x32_bf16 v[126:129], v[244:247], v[220:223], v[126:129]
	v_mfma_f32_16x16x32_bf16 v[130:133], v[248:251], v[220:223], v[130:133]
	v_mfma_f32_16x16x32_bf16 v[134:137], v[156:159], v[220:223], v[134:137]
	s_sub_u32 s46, s46, 1
	s_cmp_lg_u32 s46, 0
	s_cbranch_scc1 .Lffn1_kloop
	s_waitcnt vmcnt(6)
	s_barrier
; #define BLOAD(A_, B_, kt) do { _Pragma("unroll") for (int i = 0; i < 4; ++i) { \
;     A_[i] = *(const u32x4*)((const char*)Ap + (aoff + (unsigned)(32 * i * lda + (kt) * 64) * 2u)); B_[i] = *(const u32x4*)((const char*)Wt + (woff + (unsigned)(32 * i * K + (kt) * 64) * 2u)); } } while (0)
; #define BLOAD(A_, B_, kt) do { _Pragma("unroll") for (int i = 0; i < 4; ++i) { \
;     A_[i] = *(const u32x4*)((const char*)Ap + (aoff + (unsigned)(32 * i * lda + (kt) * 64) * 2u)); B_[i] = *(const u32x4*)((const char*)Wt + (woff + (unsigned)(32 * i * K + (kt) * 64) * 2u)); } } while (0)
; #define BSTORE(A_, B_, buf) do { _Pragma("unroll") for (int i = 0; i < 4; ++i) { \
;     *(u32x4*)&As[(buf) * GBUF + (srow + 32 * i) * LDT + sc8] = A_[i]; \
;     *(u32x4*)&Bs[(buf) * GBUF + (srow + 32 * i) * LDT + sc8] = B_[i]; } } while (0)
; template <int NK>
; DI void gemm_run(PF& pf, const u16* __restrict__ Ap, int lda, const u16* __restrict__ Wt, f32x16 (&acc)[2][2], char* smem) {
;     ...
; #pragma unroll
;   for (int kt = 0; kt < nk; kt += 2) {
;     BCOMP(0);
;     BSTORE(pf.a1, pf.b1, 1);
;     if (kt + 3 < nk) BLOAD(pf.a1, pf.b1, kt + 3);
;     __syncthreads();
;     BCOMP(1);
;     if (kt + 2 < nk) { BSTORE(pf.a0, pf.b0, 0); if (kt + 4 < nk) BLOAD(pf.a0, pf.b0, kt + 4); }
;     __syncthreads();
;   }
	ds_read_b128 v[208:211], v138 offset:0
	ds_read_b128 v[224:227], v140 offset:0
	ds_read_b128 v[228:231], v140 offset:1024
	ds_read_b128 v[232:235], v140 offset:2048
	ds_read_b128 v[236:239], v140 offset:3072
	ds_read_b128 v[212:215], v138 offset:1024
	ds_read_b128 v[216:219], v138 offset:2048
	ds_read_b128 v[220:223], v138 offset:3072
	ds_read_b128 v[240:243], v140 offset:8192
	ds_read_b128 v[244:247], v140 offset:9216
	ds_read_b128 v[248:251], v140 offset:10240
	ds_read_b128 v[156:159], v140 offset:11264
	s_waitcnt lgkmcnt(7)
	v_mfma_f32_16x16x32_bf16 v[2:5], v[224:227], v[208:211], v[2:5]
	v_mfma_f32_16x16x32_bf16 v[6:9], v[228:231], v[208:211], v[6:9]
	v_mfma_f32_16x16x32_bf16 v[10:13], v[232:235], v[208:211], v[10:13]
	v_mfma_f32_16x16x32_bf16 v[14:17], v[236:239], v[208:211], v[14:17]
	s_waitcnt lgkmcnt(4)
	v_mfma_f32_16x16x32_bf16 v[18:21], v[224:227], v[212:215], v[18:21]
	v_mfma_f32_16x16x32_bf16 v[22:25], v[228:231], v[212:215], v[22:25]
	v_mfma_f32_16x16x32_bf16 v[26:29], v[232:235], v[212:215], v[26:29]
	v_mfma_f32_16x16x32_bf16 v[30:33], v[236:239], v[212:215], v[30:33]
	v_mfma_f32_16x16x32_bf16 v[34:37], v[224:227], v[216:219], v[34:37]
	v_mfma_f32_16x16x32_bf16 v[38:41], v[228:231], v[216:219], v[38:41]
	v_mfma_f32_16x16x32_bf16 v[42:45], v[232:235], v[216:219], v[42:45]
	v_mfma_f32_16x16x32_bf16 v[46:49], v[236:239], v[216:219], v[46:49]
	v_mfma_f32_16x16x32_bf16 v[50:53], v[224:227], v[220:223], v[50:53]
	v_mfma_f32_16x16x32_bf16 v[54:57], v[228:231], v[220:223], v[54:57]
	v_mfma_f32_16x16x32_bf16 v[58:61], v[232:235], v[220:223], v[58:61]
	v_mfma_f32_16x16x32_bf16 v[62:65], v[236:239], v[220:223], v[62:65]
	s_waitcnt lgkmcnt(0)
	v_mfma_f32_16x16x32_bf16 v[74:77], v[240:243], v[208:211], v[74:77]
	v_mfma_f32_16x16x32_bf16 v[78:81], v[244:247], v[208:211], v[78:81]
	v_mfma_f32_16x16x32_bf16 v[82:85], v[248:251], v[208:211], v[82:85]
	v_mfma_f32_16x16x32_bf16 v[86:89], v[156:159], v[208:211], v[86:89]
	v_mfma_f32_16x16x32_bf16 v[90:93], v[240:243], v[212:215], v[90:93]
	v_mfma_f32_16x16x32_bf16 v[94:97], v[244:247], v[212:215], v[94:97]
	v_mfma_f32_16x16x32_bf16 v[98:101], v[248:251], v[212:215], v[98:101]
	v_mfma_f32_16x16x32_bf16 v[102:105], v[156:159], v[212:215], v[102:105]
	v_mfma_f32_16x16x32_bf16 v[106:109], v[240:243], v[216:219], v[106:109]
	v_mfma_f32_16x16x32_bf16 v[110:113], v[244:247], v[216:219], v[110:113]
	v_mfma_f32_16x16x32_bf16 v[114:117], v[248:251], v[216:219], v[114:117]
	v_mfma_f32_16x16x32_bf16 v[118:121], v[156:159], v[216:219], v[118:121]
	v_mfma_f32_16x16x32_bf16 v[122:125], v[240:243], v[220:223], v[122:125]
	v_mfma_f32_16x16x32_bf16 v[126:129], v[244:247], v[220:223], v[126:129]
	v_mfma_f32_16x16x32_bf16 v[130:133], v[248:251], v[220:223], v[130:133]
	v_mfma_f32_16x16x32_bf16 v[134:137], v[156:159], v[220:223], v[134:137]
	s_waitcnt vmcnt(0)
	s_barrier
	ds_read_b128 v[208:211], v138 offset:24576
	ds_read_b128 v[224:227], v140 offset:24576
	ds_read_b128 v[228:231], v140 offset:25600
	ds_read_b128 v[232:235], v140 offset:26624
	ds_read_b128 v[236:239], v140 offset:27648
	ds_read_b128 v[212:215], v138 offset:25600
	ds_read_b128 v[216:219], v138 offset:26624
	ds_read_b128 v[220:223], v138 offset:27648
	ds_read_b128 v[240:243], v140 offset:32768
	ds_read_b128 v[244:247], v140 offset:33792
	ds_read_b128 v[248:251], v140 offset:34816
	ds_read_b128 v[156:159], v140 offset:35840
	s_waitcnt lgkmcnt(7)
	v_mfma_f32_16x16x32_bf16 v[2:5], v[224:227], v[208:211], v[2:5]
	v_mfma_f32_16x16x32_bf16 v[6:9], v[228:231], v[208:211], v[6:9]
	v_mfma_f32_16x16x32_bf16 v[10:13], v[232:235], v[208:211], v[10:13]
	v_mfma_f32_16x16x32_bf16 v[14:17], v[236:239], v[208:211], v[14:17]
	s_waitcnt lgkmcnt(4)
	v_mfma_f32_16x16x32_bf16 v[18:21], v[224:227], v[212:215], v[18:21]
	v_mfma_f32_16x16x32_bf16 v[22:25], v[228:231], v[212:215], v[22:25]
	v_mfma_f32_16x16x32_bf16 v[26:29], v[232:235], v[212:215], v[26:29]
	v_mfma_f32_16x16x32_bf16 v[30:33], v[236:239], v[212:215], v[30:33]
	v_mfma_f32_16x16x32_bf16 v[34:37], v[224:227], v[216:219], v[34:37]
	v_mfma_f32_16x16x32_bf16 v[38:41], v[228:231], v[216:219], v[38:41]
	v_mfma_f32_16x16x32_bf16 v[42:45], v[232:235], v[216:219], v[42:45]
	v_mfma_f32_16x16x32_bf16 v[46:49], v[236:239], v[216:219], v[46:49]
	v_mfma_f32_16x16x32_bf16 v[50:53], v[224:227], v[220:223], v[50:53]
	v_mfma_f32_16x16x32_bf16 v[54:57], v[228:231], v[220:223], v[54:57]
	v_mfma_f32_16x16x32_bf16 v[58:61], v[232:235], v[220:223], v[58:61]
	v_mfma_f32_16x16x32_bf16 v[62:65], v[236:239], v[220:223], v[62:65]
	s_waitcnt lgkmcnt(0)
	v_mfma_f32_16x16x32_bf16 v[74:77], v[240:243], v[208:211], v[74:77]
	v_mfma_f32_16x16x32_bf16 v[78:81], v[244:247], v[208:211], v[78:81]
	v_mfma_f32_16x16x32_bf16 v[82:85], v[248:251], v[208:211], v[82:85]
	v_mfma_f32_16x16x32_bf16 v[86:89], v[156:159], v[208:211], v[86:89]
	v_mfma_f32_16x16x32_bf16 v[90:93], v[240:243], v[212:215], v[90:93]
	v_mfma_f32_16x16x32_bf16 v[94:97], v[244:247], v[212:215], v[94:97]
	v_mfma_f32_16x16x32_bf16 v[98:101], v[248:251], v[212:215], v[98:101]
	v_mfma_f32_16x16x32_bf16 v[102:105], v[156:159], v[212:215], v[102:105]
	v_mfma_f32_16x16x32_bf16 v[106:109], v[240:243], v[216:219], v[106:109]
	v_mfma_f32_16x16x32_bf16 v[110:113], v[244:247], v[216:219], v[110:113]
	v_mfma_f32_16x16x32_bf16 v[114:117], v[248:251], v[216:219], v[114:117]
	v_mfma_f32_16x16x32_bf16 v[118:121], v[156:159], v[216:219], v[118:121]
	v_mfma_f32_16x16x32_bf16 v[122:125], v[240:243], v[220:223], v[122:125]
	v_mfma_f32_16x16x32_bf16 v[126:129], v[244:247], v[220:223], v[126:129]
	v_mfma_f32_16x16x32_bf16 v[130:133], v[248:251], v[220:223], v[130:133]
	v_mfma_f32_16x16x32_bf16 v[134:137], v[156:159], v[220:223], v[134:137]
	s_barrier

; #define BLOAD(A_, B_, kt) do { _Pragma("unroll") for (int i = 0; i < 4; ++i) { \
;     A_[i] = *(const u32x4*)((const char*)Ap + (aoff + (unsigned)(32 * i * lda + (kt) * 64) * 2u)); B_[i] = *(const u32x4*)((const char*)Wt + (woff + (unsigned)(32 * i * K + (kt) * 64) * 2u)); } } while (0)
; #define BLOAD(A_, B_, kt) do { _Pragma("unroll") for (int i = 0; i < 4; ++i) { \
;     A_[i] = *(const u32x4*)((const char*)Ap + (aoff + (unsigned)(32 * i * lda + (kt) * 64) * 2u)); B_[i] = *(const u32x4*)((const char*)Wt + (woff + (unsigned)(32 * i * K + (kt) * 64) * 2u)); } } while (0)
; #define BSTORE(A_, B_, buf) do { _Pragma("unroll") for (int i = 0; i < 4; ++i) { \
;     *(u32x4*)&As[(buf) * GBUF + (srow + 32 * i) * LDT + sc8] = A_[i]; \
;     *(u32x4*)&Bs[(buf) * GBUF + (srow + 32 * i) * LDT + sc8] = B_[i]; } } while (0)
; template <int NK>
; DI void gemm_run(PF& pf, const u16* __restrict__ Ap, int lda, const u16* __restrict__ Wt, f32x16 (&acc)[2][2], char* smem) {
;     ...
;   __builtin_amdgcn_s_setprio(0);
;   __syncthreads();
;   BSTORE(pf.a0, pf.b0, 0);
;   BLOAD(pf.a0, pf.b0, 2);
;   __syncthreads();
; #pragma unroll
;   for (int kt = 0; kt < nk; kt += 2) {
;     BCOMP(0);
;     BSTORE(pf.a1, pf.b1, 1);
;     if (kt + 3 < nk) BLOAD(pf.a1, pf.b1, kt + 3);
;     __syncthreads();
;     BCOMP(1);
;     if (kt + 2 < nk) { BSTORE(pf.a0, pf.b0, 0); if (kt + 4 < nk) BLOAD(pf.a0, pf.b0, kt + 4); }
;     __syncthreads();
.Lout_kloop:
	s_waitcnt vmcnt(6)
	s_barrier
	ds_read_b128 v[224:227], v126 offset:0
	ds_read_b128 v[240:243], v128 offset:0
	ds_read_b128 v[244:247], v128 offset:1024
	ds_read_b128 v[248:251], v128 offset:2048
	ds_read_b128 v[156:159], v128 offset:3072
	s_add_u32 m0, s42, 0xc000
	s_add_u32 s28, s28, 0x100000
	s_addc_u32 s29, s29, 0
	global_load_lds_dwordx4 v143, s[28:29]
	global_load_lds_dwordx4 v144, s[28:29] offset:1024
	s_add_u32 m0, s43, 0xc000
	s_add_u32 s30, s30, 0x10000
	s_addc_u32 s31, s31, 0
	global_load_lds_dwordx4 v145, s[30:31]
	global_load_lds_dwordx4 v146, s[30:31] offset:1024
	global_load_lds_dwordx4 v147, s[30:31] offset:2048
	global_load_lds_dwordx4 v148, s[30:31] offset:3072
	ds_read_b128 v[228:231], v126 offset:1024
	ds_read_b128 v[232:235], v126 offset:2048
	ds_read_b128 v[236:239], v126 offset:3072
	ds_read_b128 v[160:163], v128 offset:8192
	ds_read_b128 v[164:167], v128 offset:9216
	ds_read_b128 v[168:171], v128 offset:10240
	ds_read_b128 v[122:125], v128 offset:11264
	s_waitcnt lgkmcnt(7)
	v_mfma_f32_16x16x32_bf16 v[2:5], v[240:243], v[224:227], v[2:5]
	v_mfma_f32_16x16x32_bf16 v[6:9], v[244:247], v[224:227], v[6:9]
	v_mfma_f32_16x16x32_bf16 v[10:13], v[248:251], v[224:227], v[10:13]
	v_mfma_f32_16x16x32_bf16 v[14:17], v[156:159], v[224:227], v[14:17]
	s_waitcnt lgkmcnt(4)
	v_mfma_f32_16x16x32_bf16 v[18:21], v[240:243], v[228:231], v[18:21]
	v_mfma_f32_16x16x32_bf16 v[22:25], v[244:247], v[228:231], v[22:25]
	v_mfma_f32_16x16x32_bf16 v[26:29], v[248:251], v[228:231], v[26:29]
	v_mfma_f32_16x16x32_bf16 v[30:33], v[156:159], v[228:231], v[30:33]
	v_mfma_f32_16x16x32_bf16 v[34:37], v[240:243], v[232:235], v[34:37]
	v_mfma_f32_16x16x32_bf16 v[38:41], v[244:247], v[232:235], v[38:41]
	v_mfma_f32_16x16x32_bf16 v[42:45], v[248:251], v[232:235], v[42:45]
	v_mfma_f32_16x16x32_bf16 v[46:49], v[156:159], v[232:235], v[46:49]
	v_mfma_f32_16x16x32_bf16 v[50:53], v[240:243], v[236:239], v[50:53]
	v_mfma_f32_16x16x32_bf16 v[54:57], v[244:247], v[236:239], v[54:57]
	v_mfma_f32_16x16x32_bf16 v[58:61], v[248:251], v[236:239], v[58:61]
	v_mfma_f32_16x16x32_bf16 v[62:65], v[156:159], v[236:239], v[62:65]
	s_waitcnt lgkmcnt(0)
	v_mfma_f32_16x16x32_bf16 v[74:77], v[160:163], v[224:227], v[74:77]
	v_mfma_f32_16x16x32_bf16 v[78:81], v[164:167], v[224:227], v[78:81]
	v_mfma_f32_16x16x32_bf16 v[82:85], v[168:171], v[224:227], v[82:85]
	v_mfma_f32_16x16x32_bf16 v[86:89], v[122:125], v[224:227], v[86:89]
	v_mfma_f32_16x16x32_bf16 v[90:93], v[160:163], v[228:231], v[90:93]
	v_mfma_f32_16x16x32_bf16 v[94:97], v[164:167], v[228:231], v[94:97]
	v_mfma_f32_16x16x32_bf16 v[98:101], v[168:171], v[228:231], v[98:101]
	v_mfma_f32_16x16x32_bf16 v[102:105], v[122:125], v[228:231], v[102:105]
	v_mfma_f32_16x16x32_bf16 v[106:109], v[160:163], v[232:235], v[106:109]
	v_mfma_f32_16x16x32_bf16 v[110:113], v[164:167], v[232:235], v[110:113]
	v_mfma_f32_16x16x32_bf16 v[114:117], v[168:171], v[232:235], v[114:117]
	v_mfma_f32_16x16x32_bf16 v[118:121], v[122:125], v[232:235], v[118:121]
	v_mfma_f32_16x16x32_bf16 v[208:211], v[160:163], v[236:239], v[208:211]
	v_mfma_f32_16x16x32_bf16 v[212:215], v[164:167], v[236:239], v[212:215]
	v_mfma_f32_16x16x32_bf16 v[216:219], v[168:171], v[236:239], v[216:219]
	v_mfma_f32_16x16x32_bf16 v[220:223], v[122:125], v[236:239], v[220:223]
	s_waitcnt vmcnt(6)
	s_barrier
	ds_read_b128 v[224:227], v126 offset:24576
	ds_read_b128 v[240:243], v128 offset:24576
	ds_read_b128 v[244:247], v128 offset:25600
	ds_read_b128 v[248:251], v128 offset:26624
	ds_read_b128 v[156:159], v128 offset:27648
	s_add_u32 m0, s42, 0x0
	s_add_u32 s28, s28, 0x100000
	s_addc_u32 s29, s29, 0
	global_load_lds_dwordx4 v143, s[28:29]
	global_load_lds_dwordx4 v144, s[28:29] offset:1024
	s_add_u32 m0, s43, 0x0
	s_add_u32 s30, s30, 0x10000
	s_addc_u32 s31, s31, 0
	global_load_lds_dwordx4 v145, s[30:31]
	global_load_lds_dwordx4 v146, s[30:31] offset:1024
	global_load_lds_dwordx4 v147, s[30:31] offset:2048
	global_load_lds_dwordx4 v148, s[30:31] offset:3072
	ds_read_b128 v[228:231], v126 offset:25600
	ds_read_b128 v[232:235], v126 offset:26624
	ds_read_b128 v[236:239], v126 offset:27648
	ds_read_b128 v[160:163], v128 offset:32768
	ds_read_b128 v[164:167], v128 offset:33792
	ds_read_b128 v[168:171], v128 offset:34816
	ds_read_b128 v[122:125], v128 offset:35840
	s_waitcnt lgkmcnt(7)
	v_mfma_f32_16x16x32_bf16 v[2:5], v[240:243], v[224:227], v[2:5]
	v_mfma_f32_16x16x32_bf16 v[6:9], v[244:247], v[224:227], v[6:9]
	v_mfma_f32_16x16x32_bf16 v[10:13], v[248:251], v[224:227], v[10:13]
	v_mfma_f32_16x16x32_bf16 v[14:17], v[156:159], v[224:227], v[14:17]
	s_waitcnt lgkmcnt(4)
	v_mfma_f32_16x16x32_bf16 v[18:21], v[240:243], v[228:231], v[18:21]
	v_mfma_f32_16x16x32_bf16 v[22:25], v[244:247], v[228:231], v[22:25]
	v_mfma_f32_16x16x32_bf16 v[26:29], v[248:251], v[228:231], v[26:29]
	v_mfma_f32_16x16x32_bf16 v[30:33], v[156:159], v[228:231], v[30:33]
	v_mfma_f32_16x16x32_bf16 v[34:37], v[240:243], v[232:235], v[34:37]
	v_mfma_f32_16x16x32_bf16 v[38:41], v[244:247], v[232:235], v[38:41]
	v_mfma_f32_16x16x32_bf16 v[42:45], v[248:251], v[232:235], v[42:45]
	v_mfma_f32_16x16x32_bf16 v[46:49], v[156:159], v[232:235], v[46:49]
	v_mfma_f32_16x16x32_bf16 v[50:53], v[240:243], v[236:239], v[50:53]
	v_mfma_f32_16x16x32_bf16 v[54:57], v[244:247], v[236:239], v[54:57]
	v_mfma_f32_16x16x32_bf16 v[58:61], v[248:251], v[236:239], v[58:61]
	v_mfma_f32_16x16x32_bf16 v[62:65], v[156:159], v[236:239], v[62:65]
	s_waitcnt lgkmcnt(0)
	v_mfma_f32_16x16x32_bf16 v[74:77], v[160:163], v[224:227], v[74:77]
	v_mfma_f32_16x16x32_bf16 v[78:81], v[164:167], v[224:227], v[78:81]
	v_mfma_f32_16x16x32_bf16 v[82:85], v[168:171], v[224:227], v[82:85]
	v_mfma_f32_16x16x32_bf16 v[86:89], v[122:125], v[224:227], v[86:89]
	v_mfma_f32_16x16x32_bf16 v[90:93], v[160:163], v[228:231], v[90:93]
	v_mfma_f32_16x16x32_bf16 v[94:97], v[164:167], v[228:231], v[94:97]
	v_mfma_f32_16x16x32_bf16 v[98:101], v[168:171], v[228:231], v[98:101]
	v_mfma_f32_16x16x32_bf16 v[102:105], v[122:125], v[228:231], v[102:105]
	v_mfma_f32_16x16x32_bf16 v[106:109], v[160:163], v[232:235], v[106:109]
	v_mfma_f32_16x16x32_bf16 v[110:113], v[164:167], v[232:235], v[110:113]
	v_mfma_f32_16x16x32_bf16 v[114:117], v[168:171], v[232:235], v[114:117]
	v_mfma_f32_16x16x32_bf16 v[118:121], v[122:125], v[232:235], v[118:121]
	v_mfma_f32_16x16x32_bf16 v[208:211], v[160:163], v[236:239], v[208:211]
	v_mfma_f32_16x16x32_bf16 v[212:215], v[164:167], v[236:239], v[212:215]
	v_mfma_f32_16x16x32_bf16 v[216:219], v[168:171], v[236:239], v[216:219]
	v_mfma_f32_16x16x32_bf16 v[220:223], v[122:125], v[236:239], v[220:223]
	s_waitcnt vmcnt(6)
	s_barrier
; #define BLOAD(A_, B_, kt) do { _Pragma("unroll") for (int i = 0; i < 4; ++i) { \
;     A_[i] = *(const u32x4*)((const char*)Ap + (aoff + (unsigned)(32 * i * lda + (kt) * 64) * 2u)); B_[i] = *(const u32x4*)((const char*)Wt + (woff + (unsigned)(32 * i * K + (kt) * 64) * 2u)); } } while (0)
; #define BLOAD(A_, B_, kt) do { _Pragma("unroll") for (int i = 0; i < 4; ++i) { \
;     A_[i] = *(const u32x4*)((const char*)Ap + (aoff + (unsigned)(32 * i * lda + (kt) * 64) * 2u)); B_[i] = *(const u32x4*)((const char*)Wt + (woff + (unsigned)(32 * i * K + (kt) * 64) * 2u)); } } while (0)
; #define BSTORE(A_, B_, buf) do { _Pragma("unroll") for (int i = 0; i < 4; ++i) { \
;     *(u32x4*)&As[(buf) * GBUF + (srow + 32 * i) * LDT + sc8] = A_[i]; \
;     *(u32x4*)&Bs[(buf) * GBUF + (srow + 32 * i) * LDT + sc8] = B_[i]; } } while (0)
; template <int NK>
; DI void gemm_run(PF& pf, const u16* __restrict__ Ap, int lda, const u16* __restrict__ Wt, f32x16 (&acc)[2][2], char* smem) {
;     ...
;   __builtin_amdgcn_s_setprio(0);
;   __syncthreads();
;   BSTORE(pf.a0, pf.b0, 0);
;   BLOAD(pf.a0, pf.b0, 2);
;   __syncthreads();
; #pragma unroll
;   for (int kt = 0; kt < nk; kt += 2) {
;     BCOMP(0);
;     BSTORE(pf.a1, pf.b1, 1);
;     if (kt + 3 < nk) BLOAD(pf.a1, pf.b1, kt + 3);
;     __syncthreads();
;     BCOMP(1);
;     if (kt + 2 < nk) { BSTORE(pf.a0, pf.b0, 0); if (kt + 4 < nk) BLOAD(pf.a0, pf.b0, kt + 4); }
;     __syncthreads();
	ds_read_b128 v[224:227], v126 offset:49152
	ds_read_b128 v[240:243], v128 offset:49152
	ds_read_b128 v[244:247], v128 offset:50176
	ds_read_b128 v[248:251], v128 offset:51200
	ds_read_b128 v[156:159], v128 offset:52224
	s_add_u32 m0, s42, 0x6000
	s_add_u32 s28, s28, 0x100000
	s_addc_u32 s29, s29, 0
	global_load_lds_dwordx4 v143, s[28:29]
	global_load_lds_dwordx4 v144, s[28:29] offset:1024
	s_add_u32 m0, s43, 0x6000
	s_add_u32 s30, s30, 0x10000
	s_addc_u32 s31, s31, 0
	global_load_lds_dwordx4 v145, s[30:31]
	global_load_lds_dwordx4 v146, s[30:31] offset:1024
	global_load_lds_dwordx4 v147, s[30:31] offset:2048
	global_load_lds_dwordx4 v148, s[30:31] offset:3072
	ds_read_b128 v[228:231], v126 offset:50176
	ds_read_b128 v[232:235], v126 offset:51200
	ds_read_b128 v[236:239], v126 offset:52224
	ds_read_b128 v[160:163], v128 offset:57344
	ds_read_b128 v[164:167], v128 offset:58368
	ds_read_b128 v[168:171], v128 offset:59392
	ds_read_b128 v[122:125], v128 offset:60416
	s_waitcnt lgkmcnt(7)
	v_mfma_f32_16x16x32_bf16 v[2:5], v[240:243], v[224:227], v[2:5]
	v_mfma_f32_16x16x32_bf16 v[6:9], v[244:247], v[224:227], v[6:9]
	v_mfma_f32_16x16x32_bf16 v[10:13], v[248:251], v[224:227], v[10:13]
	v_mfma_f32_16x16x32_bf16 v[14:17], v[156:159], v[224:227], v[14:17]
	s_waitcnt lgkmcnt(4)
	v_mfma_f32_16x16x32_bf16 v[18:21], v[240:243], v[228:231], v[18:21]
	v_mfma_f32_16x16x32_bf16 v[22:25], v[244:247], v[228:231], v[22:25]
	v_mfma_f32_16x16x32_bf16 v[26:29], v[248:251], v[228:231], v[26:29]
	v_mfma_f32_16x16x32_bf16 v[30:33], v[156:159], v[228:231], v[30:33]
	v_mfma_f32_16x16x32_bf16 v[34:37], v[240:243], v[232:235], v[34:37]
	v_mfma_f32_16x16x32_bf16 v[38:41], v[244:247], v[232:235], v[38:41]
	v_mfma_f32_16x16x32_bf16 v[42:45], v[248:251], v[232:235], v[42:45]
	v_mfma_f32_16x16x32_bf16 v[46:49], v[156:159], v[232:235], v[46:49]
	v_mfma_f32_16x16x32_bf16 v[50:53], v[240:243], v[236:239], v[50:53]
	v_mfma_f32_16x16x32_bf16 v[54:57], v[244:247], v[236:239], v[54:57]
	v_mfma_f32_16x16x32_bf16 v[58:61], v[248:251], v[236:239], v[58:61]
	v_mfma_f32_16x16x32_bf16 v[62:65], v[156:159], v[236:239], v[62:65]
	s_waitcnt lgkmcnt(0)
	v_mfma_f32_16x16x32_bf16 v[74:77], v[160:163], v[224:227], v[74:77]
	v_mfma_f32_16x16x32_bf16 v[78:81], v[164:167], v[224:227], v[78:81]
	v_mfma_f32_16x16x32_bf16 v[82:85], v[168:171], v[224:227], v[82:85]
	v_mfma_f32_16x16x32_bf16 v[86:89], v[122:125], v[224:227], v[86:89]
	v_mfma_f32_16x16x32_bf16 v[90:93], v[160:163], v[228:231], v[90:93]
	v_mfma_f32_16x16x32_bf16 v[94:97], v[164:167], v[228:231], v[94:97]
	v_mfma_f32_16x16x32_bf16 v[98:101], v[168:171], v[228:231], v[98:101]
	v_mfma_f32_16x16x32_bf16 v[102:105], v[122:125], v[228:231], v[102:105]
	v_mfma_f32_16x16x32_bf16 v[106:109], v[160:163], v[232:235], v[106:109]
	v_mfma_f32_16x16x32_bf16 v[110:113], v[164:167], v[232:235], v[110:113]
	v_mfma_f32_16x16x32_bf16 v[114:117], v[168:171], v[232:235], v[114:117]
	v_mfma_f32_16x16x32_bf16 v[118:121], v[122:125], v[232:235], v[118:121]
	v_mfma_f32_16x16x32_bf16 v[208:211], v[160:163], v[236:239], v[208:211]
	v_mfma_f32_16x16x32_bf16 v[212:215], v[164:167], v[236:239], v[212:215]
	v_mfma_f32_16x16x32_bf16 v[216:219], v[168:171], v[236:239], v[216:219]
	v_mfma_f32_16x16x32_bf16 v[220:223], v[122:125], v[236:239], v[220:223]
	s_sub_u32 s46, s46, 1
	s_cmp_lg_u32 s46, 0
	s_cbranch_scc1 .Lout_kloop
	s_waitcnt vmcnt(6)
	s_barrier
	ds_read_b128 v[224:227], v126 offset:0
	ds_read_b128 v[240:243], v128 offset:0
	ds_read_b128 v[244:247], v128 offset:1024
	ds_read_b128 v[248:251], v128 offset:2048
	ds_read_b128 v[156:159], v128 offset:3072
	ds_read_b128 v[228:231], v126 offset:1024
	ds_read_b128 v[232:235], v126 offset:2048
	ds_read_b128 v[236:239], v126 offset:3072
	ds_read_b128 v[160:163], v128 offset:8192
	ds_read_b128 v[164:167], v128 offset:9216
	ds_read_b128 v[168:171], v128 offset:10240
	ds_read_b128 v[122:125], v128 offset:11264
	s_waitcnt lgkmcnt(7)
	v_mfma_f32_16x16x32_bf16 v[2:5], v[240:243], v[224:227], v[2:5]
	v_mfma_f32_16x16x32_bf16 v[6:9], v[244:247], v[224:227], v[6:9]
	v_mfma_f32_16x16x32_bf16 v[10:13], v[248:251], v[224:227], v[10:13]
	v_mfma_f32_16x16x32_bf16 v[14:17], v[156:159], v[224:227], v[14:17]
	s_waitcnt lgkmcnt(4)
	v_mfma_f32_16x16x32_bf16 v[18:21], v[240:243], v[228:231], v[18:21]
	v_mfma_f32_16x16x32_bf16 v[22:25], v[244:247], v[228:231], v[22:25]
	v_mfma_f32_16x16x32_bf16 v[26:29], v[248:251], v[228:231], v[26:29]
	v_mfma_f32_16x16x32_bf16 v[30:33], v[156:159], v[228:231], v[30:33]
	v_mfma_f32_16x16x32_bf16 v[34:37], v[240:243], v[232:235], v[34:37]
	v_mfma_f32_16x16x32_bf16 v[38:41], v[244:247], v[232:235], v[38:41]
	v_mfma_f32_16x16x32_bf16 v[42:45], v[248:251], v[232:235], v[42:45]
	v_mfma_f32_16x16x32_bf16 v[46:49], v[156:159], v[232:235], v[46:49]
	v_mfma_f32_16x16x32_bf16 v[50:53], v[240:243], v[236:239], v[50:53]
	v_mfma_f32_16x16x32_bf16 v[54:57], v[244:247], v[236:239], v[54:57]
	v_mfma_f32_16x16x32_bf16 v[58:61], v[248:251], v[236:239], v[58:61]
	v_mfma_f32_16x16x32_bf16 v[62:65], v[156:159], v[236:239], v[62:65]
	s_waitcnt lgkmcnt(0)
	v_mfma_f32_16x16x32_bf16 v[74:77], v[160:163], v[224:227], v[74:77]
	v_mfma_f32_16x16x32_bf16 v[78:81], v[164:167], v[224:227], v[78:81]
	v_mfma_f32_16x16x32_bf16 v[82:85], v[168:171], v[224:227], v[82:85]
	v_mfma_f32_16x16x32_bf16 v[86:89], v[122:125], v[224:227], v[86:89]
	v_mfma_f32_16x16x32_bf16 v[90:93], v[160:163], v[228:231], v[90:93]
	v_mfma_f32_16x16x32_bf16 v[94:97], v[164:167], v[228:231], v[94:97]
	v_mfma_f32_16x16x32_bf16 v[98:101], v[168:171], v[228:231], v[98:101]
	v_mfma_f32_16x16x32_bf16 v[102:105], v[122:125], v[228:231], v[102:105]
	v_mfma_f32_16x16x32_bf16 v[106:109], v[160:163], v[232:235], v[106:109]
	v_mfma_f32_16x16x32_bf16 v[110:113], v[164:167], v[232:235], v[110:113]
	v_mfma_f32_16x16x32_bf16 v[114:117], v[168:171], v[232:235], v[114:117]
	v_mfma_f32_16x16x32_bf16 v[118:121], v[122:125], v[232:235], v[118:121]
	v_mfma_f32_16x16x32_bf16 v[208:211], v[160:163], v[236:239], v[208:211]
	v_mfma_f32_16x16x32_bf16 v[212:215], v[164:167], v[236:239], v[212:215]
	v_mfma_f32_16x16x32_bf16 v[216:219], v[168:171], v[236:239], v[216:219]
	v_mfma_f32_16x16x32_bf16 v[220:223], v[122:125], v[236:239], v[220:223]
	s_waitcnt vmcnt(0)
	s_barrier
; #define BLOAD(A_, B_, kt) do { _Pragma("unroll") for (int i = 0; i < 4; ++i) { \
;     A_[i] = *(const u32x4*)((const char*)Ap + (aoff + (unsigned)(32 * i * lda + (kt) * 64) * 2u)); B_[i] = *(const u32x4*)((const char*)Wt + (woff + (unsigned)(32 * i * K + (kt) * 64) * 2u)); } } while (0)
; #define BLOAD(A_, B_, kt) do { _Pragma("unroll") for (int i = 0; i < 4; ++i) { \
;     A_[i] = *(const u32x4*)((const char*)Ap + (aoff + (unsigned)(32 * i * lda + (kt) * 64) * 2u)); B_[i] = *(const u32x4*)((const char*)Wt + (woff + (unsigned)(32 * i * K + (kt) * 64) * 2u)); } } while (0)
; #define BSTORE(A_, B_, buf) do { _Pragma("unroll") for (int i = 0; i < 4; ++i) { \
;     *(u32x4*)&As[(buf) * GBUF + (srow + 32 * i) * LDT + sc8] = A_[i]; \
;     *(u32x4*)&Bs[(buf) * GBUF + (srow + 32 * i) * LDT + sc8] = B_[i]; } } while (0)
; template <int NK>
; DI void gemm_run(PF& pf, const u16* __restrict__ Ap, int lda, const u16* __restrict__ Wt, f32x16 (&acc)[2][2], char* smem) {
;     ...
; #pragma unroll
;   for (int kt = 0; kt < nk; kt += 2) {
;     BCOMP(0);
;     BSTORE(pf.a1, pf.b1, 1);
;     if (kt + 3 < nk) BLOAD(pf.a1, pf.b1, kt + 3);
;     __syncthreads();
;     BCOMP(1);
;     if (kt + 2 < nk) { BSTORE(pf.a0, pf.b0, 0); if (kt + 4 < nk) BLOAD(pf.a0, pf.b0, kt + 4); }
;     __syncthreads();
;   }
; DI void tile_outproj(const Params& p, int l, const Chunk& ck, int tile, int next, PF& pf, char* smem) {
;     ...
;   const int row = tid >> 1, half = tid & 1; float ssq = 0.f;
;   u16* xb = (u16*)(p.ws + OFF_XB) + (size_t)(m0 + row) * 1024 + n0 + half * 64;
; #pragma unroll
;   for (int c8 = 0; c8 < 8; ++c8) {
;     float v[8], x[8]; cs_ld8(Cs, row, half * 64 + c8 * 8, v); unpack8(*(const u32x4*)(xb + c8 * 8), x);
	ds_read_b128 v[224:227], v126 offset:24576
	ds_read_b128 v[240:243], v128 offset:24576
	ds_read_b128 v[244:247], v128 offset:25600
	ds_read_b128 v[248:251], v128 offset:26624
	ds_read_b128 v[156:159], v128 offset:27648
	ds_read_b128 v[228:231], v126 offset:25600
	ds_read_b128 v[232:235], v126 offset:26624
	ds_read_b128 v[236:239], v126 offset:27648
	ds_read_b128 v[160:163], v128 offset:32768
	ds_read_b128 v[164:167], v128 offset:33792
	ds_read_b128 v[168:171], v128 offset:34816
	ds_read_b128 v[122:125], v128 offset:35840
	s_waitcnt lgkmcnt(7)
	v_mfma_f32_16x16x32_bf16 v[2:5], v[240:243], v[224:227], v[2:5]
	v_mfma_f32_16x16x32_bf16 v[6:9], v[244:247], v[224:227], v[6:9]
	v_mfma_f32_16x16x32_bf16 v[10:13], v[248:251], v[224:227], v[10:13]
	v_mfma_f32_16x16x32_bf16 v[14:17], v[156:159], v[224:227], v[14:17]
	s_waitcnt lgkmcnt(4)
	v_mfma_f32_16x16x32_bf16 v[18:21], v[240:243], v[228:231], v[18:21]
	v_mfma_f32_16x16x32_bf16 v[22:25], v[244:247], v[228:231], v[22:25]
	v_mfma_f32_16x16x32_bf16 v[26:29], v[248:251], v[228:231], v[26:29]
	v_mfma_f32_16x16x32_bf16 v[30:33], v[156:159], v[228:231], v[30:33]
	v_mfma_f32_16x16x32_bf16 v[34:37], v[240:243], v[232:235], v[34:37]
	v_mfma_f32_16x16x32_bf16 v[38:41], v[244:247], v[232:235], v[38:41]
	v_mfma_f32_16x16x32_bf16 v[42:45], v[248:251], v[232:235], v[42:45]
	v_mfma_f32_16x16x32_bf16 v[46:49], v[156:159], v[232:235], v[46:49]
	v_mfma_f32_16x16x32_bf16 v[50:53], v[240:243], v[236:239], v[50:53]
	v_mfma_f32_16x16x32_bf16 v[54:57], v[244:247], v[236:239], v[54:57]
	v_mfma_f32_16x16x32_bf16 v[58:61], v[248:251], v[236:239], v[58:61]
	v_mfma_f32_16x16x32_bf16 v[62:65], v[156:159], v[236:239], v[62:65]
	s_waitcnt lgkmcnt(0)
	v_mfma_f32_16x16x32_bf16 v[74:77], v[160:163], v[224:227], v[74:77]
	v_mfma_f32_16x16x32_bf16 v[78:81], v[164:167], v[224:227], v[78:81]
	v_mfma_f32_16x16x32_bf16 v[82:85], v[168:171], v[224:227], v[82:85]
	v_mfma_f32_16x16x32_bf16 v[86:89], v[122:125], v[224:227], v[86:89]
	v_mfma_f32_16x16x32_bf16 v[90:93], v[160:163], v[228:231], v[90:93]
	v_mfma_f32_16x16x32_bf16 v[94:97], v[164:167], v[228:231], v[94:97]
	v_mfma_f32_16x16x32_bf16 v[98:101], v[168:171], v[228:231], v[98:101]
	v_mfma_f32_16x16x32_bf16 v[102:105], v[122:125], v[228:231], v[102:105]
	v_mfma_f32_16x16x32_bf16 v[106:109], v[160:163], v[232:235], v[106:109]
	v_mfma_f32_16x16x32_bf16 v[110:113], v[164:167], v[232:235], v[110:113]
	v_mfma_f32_16x16x32_bf16 v[114:117], v[168:171], v[232:235], v[114:117]
	v_mfma_f32_16x16x32_bf16 v[118:121], v[122:125], v[232:235], v[118:121]
	v_mfma_f32_16x16x32_bf16 v[208:211], v[160:163], v[236:239], v[208:211]
	v_mfma_f32_16x16x32_bf16 v[212:215], v[164:167], v[236:239], v[212:215]
	v_mfma_f32_16x16x32_bf16 v[216:219], v[168:171], v[236:239], v[216:219]
	v_mfma_f32_16x16x32_bf16 v[220:223], v[122:125], v[236:239], v[220:223]
	s_barrier
	s_and_b32 s0, s40, 0x3f80
	v_and_b32_e32 v160, 63, v172
	v_lshrrev_b32_e32 v161, 6, v172
	v_and_b32_e32 v162, 15, v160
	v_lshrrev_b32_e32 v163, 4, v160
	v_lshrrev_b32_e32 v167, 1, v161
	v_lshl_add_u32 v167, v167, 6, v162
	v_and_b32_e32 v168, 1, v161
	v_lshlrev_b32_e32 v169, 6, v168
	v_lshl_add_u32 v169, v163, 2, v169
	v_add_u32_e32 v169, s26, v169
	v_add_u32_e32 v170, s0, v167
	v_lshlrev_b32_e32 v164, 6, v170
	v_lshl_add_u32 v164, v163, 3, v164
	v_lshrrev_b32_e32 v122, 5, v169
	v_lshl_add_u32 v164, v122, 20, v164
	v_add_u32_e32 v122, 0x100000, v164
	v_lshlrev_b32_e32 v165, 12, v167
	v_lshl_add_u32 v165, v169, 2, v165
	v_lshlrev_b32_e32 v166, 6, v170
	v_lshl_add_u32 v166, v168, 2, v166
	s_lshr_b32 s0, s26, 4
	s_add_u32 s14, s22, s0
	s_addc_u32 s15, s23, 0
	global_load_dwordx2 v[224:225], v164, s[20:21] offset:0
	global_load_dwordx2 v[226:227], v164, s[20:21] offset:32
	global_load_dwordx2 v[228:229], v122, s[20:21] offset:0
	global_load_dwordx2 v[230:231], v122, s[20:21] offset:32
	global_load_dwordx2 v[232:233], v164, s[20:21] offset:1024
	global_load_dwordx2 v[234:235], v164, s[20:21] offset:1056
	global_load_dwordx2 v[236:237], v122, s[20:21] offset:1024
	global_load_dwordx2 v[238:239], v122, s[20:21] offset:1056
	global_load_dwordx2 v[240:241], v164, s[20:21] offset:2048
	global_load_dwordx2 v[242:243], v164, s[20:21] offset:2080
	global_load_dwordx2 v[244:245], v122, s[20:21] offset:2048
	global_load_dwordx2 v[246:247], v122, s[20:21] offset:2080
	global_load_dwordx2 v[248:249], v164, s[20:21] offset:3072
	global_load_dwordx2 v[250:251], v164, s[20:21] offset:3104
	global_load_dwordx2 v[156:157], v122, s[20:21] offset:3072
	global_load_dwordx2 v[158:159], v122, s[20:21] offset:3104
	s_waitcnt vmcnt(0)
; DI u32x4 pack8(const float (&v)[8]) { u32x4 r = {pk2(v[0], v[1]), pk2(v[2], v[3]), pk2(v[4], v[5]), pk2(v[6], v[7])}; return r; }
; DI void tile_outproj(const Params& p, int l, const Chunk& ck, int tile, int next, PF& pf, char* smem) {
;     ...
;   const int row = tid >> 1, half = tid & 1; float ssq = 0.f;
;   u16* xb = (u16*)(p.ws + OFF_XB) + (size_t)(m0 + row) * 1024 + n0 + half * 64;
; #pragma unroll
;   for (int c8 = 0; c8 < 8; ++c8) {
;     float v[8], x[8]; cs_ld8(Cs, row, half * 64 + c8 * 8, v); unpack8(*(const u32x4*)(xb + c8 * 8), x);
; #pragma unroll
;     for (int j = 0; j < 8; ++j) { v[j] += x[j]; ssq += v[j] * v[j]; }
;     *(u32x4*)(xb + c8 * 8) = pack8(v);
;   }
;   ((float*)(p.ws + OFF_PSMID))[(size_t)(m0 + row) * 16 + ni * 2 + half] = ssq;
	v_mov_b32_e32 v171, 0
	v_lshlrev_b32_e32 v167, 16, v224
	v_and_b32_e32 v168, 0xffff0000, v224
	v_lshlrev_b32_e32 v169, 16, v225
	v_and_b32_e32 v170, 0xffff0000, v225
	v_add_f32_e32 v2, v2, v167
	v_add_f32_e32 v3, v3, v168
	v_add_f32_e32 v4, v4, v169
	v_add_f32_e32 v5, v5, v170
	v_fma_f32 v171, v2, v2, v171
	v_fma_f32 v171, v3, v3, v171
	v_fma_f32 v171, v4, v4, v171
	v_fma_f32 v171, v5, v5, v171
	v_cvt_pk_bf16_f32 v2, v2, v3
	v_cvt_pk_bf16_f32 v3, v4, v5
	global_store_dwordx2 v164, v[2:3], s[20:21]
	v_lshlrev_b32_e32 v167, 16, v226
	v_and_b32_e32 v168, 0xffff0000, v226
	v_lshlrev_b32_e32 v169, 16, v227
	v_and_b32_e32 v170, 0xffff0000, v227
	v_add_f32_e32 v6, v6, v167
	v_add_f32_e32 v7, v7, v168
	v_add_f32_e32 v8, v8, v169
	v_add_f32_e32 v9, v9, v170
	v_fma_f32 v171, v6, v6, v171
	v_fma_f32 v171, v7, v7, v171
	v_fma_f32 v171, v8, v8, v171
	v_fma_f32 v171, v9, v9, v171
	v_cvt_pk_bf16_f32 v6, v6, v7
	v_cvt_pk_bf16_f32 v7, v8, v9
	global_store_dwordx2 v164, v[6:7], s[20:21] offset:32
	v_lshlrev_b32_e32 v167, 16, v228
	v_and_b32_e32 v168, 0xffff0000, v228
	v_lshlrev_b32_e32 v169, 16, v229
	v_and_b32_e32 v170, 0xffff0000, v229
	v_add_f32_e32 v10, v10, v167
	v_add_f32_e32 v11, v11, v168
	v_add_f32_e32 v12, v12, v169
	v_add_f32_e32 v13, v13, v170
	v_fma_f32 v171, v10, v10, v171
	v_fma_f32 v171, v11, v11, v171
	v_fma_f32 v171, v12, v12, v171
	v_fma_f32 v171, v13, v13, v171
	v_cvt_pk_bf16_f32 v10, v10, v11
	v_cvt_pk_bf16_f32 v11, v12, v13
	global_store_dwordx2 v122, v[10:11], s[20:21]
	v_lshlrev_b32_e32 v167, 16, v230
	v_and_b32_e32 v168, 0xffff0000, v230
	v_lshlrev_b32_e32 v169, 16, v231
	v_and_b32_e32 v170, 0xffff0000, v231
	v_add_f32_e32 v14, v14, v167
	v_add_f32_e32 v15, v15, v168
	v_add_f32_e32 v16, v16, v169
	v_add_f32_e32 v17, v17, v170
	v_fma_f32 v171, v14, v14, v171
	v_fma_f32 v171, v15, v15, v171
	v_fma_f32 v171, v16, v16, v171
	v_fma_f32 v171, v17, v17, v171
	v_cvt_pk_bf16_f32 v14, v14, v15
	v_cvt_pk_bf16_f32 v15, v16, v17
	global_store_dwordx2 v122, v[14:15], s[20:21] offset:32
	v_mov_b32_e32 v167, v171
	s_nop 1
	v_permlane32_swap_b32_e32 v171, v167
	v_add_f32_e32 v171, v171, v167
	ds_swizzle_b32 v167, v171 offset:0x401f
	s_waitcnt lgkmcnt(0)
	v_add_f32_e32 v171, v171, v167
	v_cmp_gt_u32_e32 vcc, 16, v160
	s_and_saveexec_b64 s[98:99], vcc
	global_store_dword v166, v171, s[14:15] offset:0
	s_or_b64 exec, exec, s[98:99]
	v_mov_b32_e32 v171, 0
	v_lshlrev_b32_e32 v167, 16, v232
	v_and_b32_e32 v168, 0xffff0000, v232
	v_lshlrev_b32_e32 v169, 16, v233
	v_and_b32_e32 v170, 0xffff0000, v233
	v_add_f32_e32 v18, v18, v167
	v_add_f32_e32 v19, v19, v168
	v_add_f32_e32 v20, v20, v169
	v_add_f32_e32 v21, v21, v170
	v_fma_f32 v171, v18, v18, v171
	v_fma_f32 v171, v19, v19, v171
	v_fma_f32 v171, v20, v20, v171
	v_fma_f32 v171, v21, v21, v171
	v_cvt_pk_bf16_f32 v18, v18, v19
	v_cvt_pk_bf16_f32 v19, v20, v21
	global_store_dwordx2 v164, v[18:19], s[20:21] offset:1024
	v_lshlrev_b32_e32 v167, 16, v234
	v_and_b32_e32 v168, 0xffff0000, v234
	v_lshlrev_b32_e32 v169, 16, v235
	v_and_b32_e32 v170, 0xffff0000, v235
	v_add_f32_e32 v22, v22, v167
	v_add_f32_e32 v23, v23, v168
	v_add_f32_e32 v24, v24, v169
	v_add_f32_e32 v25, v25, v170
	v_fma_f32 v171, v22, v22, v171
	v_fma_f32 v171, v23, v23, v171
	v_fma_f32 v171, v24, v24, v171
	v_fma_f32 v171, v25, v25, v171
	v_cvt_pk_bf16_f32 v22, v22, v23
	v_cvt_pk_bf16_f32 v23, v24, v25
	global_store_dwordx2 v164, v[22:23], s[20:21] offset:1056
	v_lshlrev_b32_e32 v167, 16, v236
	v_and_b32_e32 v168, 0xffff0000, v236
	v_lshlrev_b32_e32 v169, 16, v237
	v_and_b32_e32 v170, 0xffff0000, v237
	v_add_f32_e32 v26, v26, v167
	v_add_f32_e32 v27, v27, v168
	v_add_f32_e32 v28, v28, v169
	v_add_f32_e32 v29, v29, v170
	v_fma_f32 v171, v26, v26, v171
	v_fma_f32 v171, v27, v27, v171
	v_fma_f32 v171, v28, v28, v171
	v_fma_f32 v171, v29, v29, v171
	v_cvt_pk_bf16_f32 v26, v26, v27
	v_cvt_pk_bf16_f32 v27, v28, v29
	global_store_dwordx2 v122, v[26:27], s[20:21] offset:1024
	v_lshlrev_b32_e32 v167, 16, v238
	v_and_b32_e32 v168, 0xffff0000, v238
	v_lshlrev_b32_e32 v169, 16, v239
	v_and_b32_e32 v170, 0xffff0000, v239
	v_add_f32_e32 v30, v30, v167
	v_add_f32_e32 v31, v31, v168
	v_add_f32_e32 v32, v32, v169
	v_add_f32_e32 v33, v33, v170
	v_fma_f32 v171, v30, v30, v171
	v_fma_f32 v171, v31, v31, v171
	v_fma_f32 v171, v32, v32, v171
	v_fma_f32 v171, v33, v33, v171
	v_cvt_pk_bf16_f32 v30, v30, v31
	v_cvt_pk_bf16_f32 v31, v32, v33
	global_store_dwordx2 v122, v[30:31], s[20:21] offset:1056
	v_mov_b32_e32 v167, v171
	s_nop 1
	v_permlane32_swap_b32_e32 v171, v167
	v_add_f32_e32 v171, v171, v167
	ds_swizzle_b32 v167, v171 offset:0x401f
	s_waitcnt lgkmcnt(0)
; DI u32x4 pack8(const float (&v)[8]) { u32x4 r = {pk2(v[0], v[1]), pk2(v[2], v[3]), pk2(v[4], v[5]), pk2(v[6], v[7])}; return r; }
; DI void tile_outproj(const Params& p, int l, const Chunk& ck, int tile, int next, PF& pf, char* smem) {
;     ...
;   const int row = tid >> 1, half = tid & 1; float ssq = 0.f;
;   u16* xb = (u16*)(p.ws + OFF_XB) + (size_t)(m0 + row) * 1024 + n0 + half * 64;
; #pragma unroll
;   for (int c8 = 0; c8 < 8; ++c8) {
;     float v[8], x[8]; cs_ld8(Cs, row, half * 64 + c8 * 8, v); unpack8(*(const u32x4*)(xb + c8 * 8), x);
; #pragma unroll
;     for (int j = 0; j < 8; ++j) { v[j] += x[j]; ssq += v[j] * v[j]; }
;     *(u32x4*)(xb + c8 * 8) = pack8(v);
;   }
;   ((float*)(p.ws + OFF_PSMID))[(size_t)(m0 + row) * 16 + ni * 2 + half] = ssq;
	v_add_f32_e32 v171, v171, v167
	v_cmp_gt_u32_e32 vcc, 16, v160
	s_and_saveexec_b64 s[98:99], vcc
	global_store_dword v166, v171, s[14:15] offset:1024
	s_or_b64 exec, exec, s[98:99]
	v_mov_b32_e32 v171, 0
	v_lshlrev_b32_e32 v167, 16, v240
	v_and_b32_e32 v168, 0xffff0000, v240
	v_lshlrev_b32_e32 v169, 16, v241
	v_and_b32_e32 v170, 0xffff0000, v241
	v_add_f32_e32 v34, v34, v167
	v_add_f32_e32 v35, v35, v168
	v_add_f32_e32 v36, v36, v169
	v_add_f32_e32 v37, v37, v170
	v_fma_f32 v171, v34, v34, v171
	v_fma_f32 v171, v35, v35, v171
	v_fma_f32 v171, v36, v36, v171
	v_fma_f32 v171, v37, v37, v171
	v_cvt_pk_bf16_f32 v34, v34, v35
	v_cvt_pk_bf16_f32 v35, v36, v37
	global_store_dwordx2 v164, v[34:35], s[20:21] offset:2048
	v_lshlrev_b32_e32 v167, 16, v242
	v_and_b32_e32 v168, 0xffff0000, v242
	v_lshlrev_b32_e32 v169, 16, v243
	v_and_b32_e32 v170, 0xffff0000, v243
	v_add_f32_e32 v38, v38, v167
	v_add_f32_e32 v39, v39, v168
	v_add_f32_e32 v40, v40, v169
	v_add_f32_e32 v41, v41, v170
	v_fma_f32 v171, v38, v38, v171
	v_fma_f32 v171, v39, v39, v171
	v_fma_f32 v171, v40, v40, v171
	v_fma_f32 v171, v41, v41, v171
	v_cvt_pk_bf16_f32 v38, v38, v39
	v_cvt_pk_bf16_f32 v39, v40, v41
	global_store_dwordx2 v164, v[38:39], s[20:21] offset:2080
	v_lshlrev_b32_e32 v167, 16, v244
	v_and_b32_e32 v168, 0xffff0000, v244
	v_lshlrev_b32_e32 v169, 16, v245
	v_and_b32_e32 v170, 0xffff0000, v245
	v_add_f32_e32 v42, v42, v167
	v_add_f32_e32 v43, v43, v168
	v_add_f32_e32 v44, v44, v169
	v_add_f32_e32 v45, v45, v170
	v_fma_f32 v171, v42, v42, v171
	v_fma_f32 v171, v43, v43, v171
	v_fma_f32 v171, v44, v44, v171
	v_fma_f32 v171, v45, v45, v171
	v_cvt_pk_bf16_f32 v42, v42, v43
	v_cvt_pk_bf16_f32 v43, v44, v45
	global_store_dwordx2 v122, v[42:43], s[20:21] offset:2048
	v_lshlrev_b32_e32 v167, 16, v246
	v_and_b32_e32 v168, 0xffff0000, v246
	v_lshlrev_b32_e32 v169, 16, v247
	v_and_b32_e32 v170, 0xffff0000, v247
	v_add_f32_e32 v46, v46, v167
	v_add_f32_e32 v47, v47, v168
	v_add_f32_e32 v48, v48, v169
	v_add_f32_e32 v49, v49, v170
	v_fma_f32 v171, v46, v46, v171
	v_fma_f32 v171, v47, v47, v171
	v_fma_f32 v171, v48, v48, v171
	v_fma_f32 v171, v49, v49, v171
	v_cvt_pk_bf16_f32 v46, v46, v47
	v_cvt_pk_bf16_f32 v47, v48, v49
	global_store_dwordx2 v122, v[46:47], s[20:21] offset:2080
	v_mov_b32_e32 v167, v171
	s_nop 1
	v_permlane32_swap_b32_e32 v171, v167
	v_add_f32_e32 v171, v171, v167
	ds_swizzle_b32 v167, v171 offset:0x401f
	s_waitcnt lgkmcnt(0)
	v_add_f32_e32 v171, v171, v167
	v_cmp_gt_u32_e32 vcc, 16, v160
	s_and_saveexec_b64 s[98:99], vcc
	global_store_dword v166, v171, s[14:15] offset:2048
	s_or_b64 exec, exec, s[98:99]
	v_mov_b32_e32 v171, 0
	v_lshlrev_b32_e32 v167, 16, v248
	v_and_b32_e32 v168, 0xffff0000, v248
	v_lshlrev_b32_e32 v169, 16, v249
	v_and_b32_e32 v170, 0xffff0000, v249
	v_add_f32_e32 v50, v50, v167
	v_add_f32_e32 v51, v51, v168
	v_add_f32_e32 v52, v52, v169
	v_add_f32_e32 v53, v53, v170
	v_fma_f32 v171, v50, v50, v171
	v_fma_f32 v171, v51, v51, v171
	v_fma_f32 v171, v52, v52, v171
	v_fma_f32 v171, v53, v53, v171
	v_cvt_pk_bf16_f32 v50, v50, v51
	v_cvt_pk_bf16_f32 v51, v52, v53
	global_store_dwordx2 v164, v[50:51], s[20:21] offset:3072
	v_lshlrev_b32_e32 v167, 16, v250
	v_and_b32_e32 v168, 0xffff0000, v250
	v_lshlrev_b32_e32 v169, 16, v251
	v_and_b32_e32 v170, 0xffff0000, v251
	v_add_f32_e32 v54, v54, v167
	v_add_f32_e32 v55, v55, v168
	v_add_f32_e32 v56, v56, v169
	v_add_f32_e32 v57, v57, v170
	v_fma_f32 v171, v54, v54, v171
	v_fma_f32 v171, v55, v55, v171
	v_fma_f32 v171, v56, v56, v171
	v_fma_f32 v171, v57, v57, v171
	v_cvt_pk_bf16_f32 v54, v54, v55
	v_cvt_pk_bf16_f32 v55, v56, v57
	global_store_dwordx2 v164, v[54:55], s[20:21] offset:3104
	v_lshlrev_b32_e32 v167, 16, v156
	v_and_b32_e32 v168, 0xffff0000, v156
	v_lshlrev_b32_e32 v169, 16, v157
	v_and_b32_e32 v170, 0xffff0000, v157
	v_add_f32_e32 v58, v58, v167
	v_add_f32_e32 v59, v59, v168
	v_add_f32_e32 v60, v60, v169
	v_add_f32_e32 v61, v61, v170
	v_fma_f32 v171, v58, v58, v171
	v_fma_f32 v171, v59, v59, v171
	v_fma_f32 v171, v60, v60, v171
	v_fma_f32 v171, v61, v61, v171
	v_cvt_pk_bf16_f32 v58, v58, v59
	v_cvt_pk_bf16_f32 v59, v60, v61
	global_store_dwordx2 v122, v[58:59], s[20:21] offset:3072
	v_lshlrev_b32_e32 v167, 16, v158
	v_and_b32_e32 v168, 0xffff0000, v158
	v_lshlrev_b32_e32 v169, 16, v159
	v_and_b32_e32 v170, 0xffff0000, v159
	v_add_f32_e32 v62, v62, v167
	v_add_f32_e32 v63, v63, v168
	v_add_f32_e32 v64, v64, v169
	v_add_f32_e32 v65, v65, v170
	v_fma_f32 v171, v62, v62, v171
	v_fma_f32 v171, v63, v63, v171
	v_fma_f32 v171, v64, v64, v171
	v_fma_f32 v171, v65, v65, v171
	v_cvt_pk_bf16_f32 v62, v62, v63
	v_cvt_pk_bf16_f32 v63, v64, v65
	global_store_dwordx2 v122, v[62:63], s[20:21] offset:3104
	v_mov_b32_e32 v167, v171
	s_nop 1
	v_permlane32_swap_b32_e32 v171, v167
	v_add_f32_e32 v171, v171, v167
	ds_swizzle_b32 v167, v171 offset:0x401f
	s_waitcnt lgkmcnt(0)
	v_add_f32_e32 v171, v171, v167
	v_cmp_gt_u32_e32 vcc, 16, v160
	s_and_saveexec_b64 s[98:99], vcc
	global_store_dword v166, v171, s[14:15] offset:3072
	s_or_b64 exec, exec, s[98:99]
	v_add_u32_e32 v164, 0x400000, v164
	v_add_u32_e32 v122, 0x400000, v122
	global_load_dwordx2 v[224:225], v164, s[20:21] offset:0
	global_load_dwordx2 v[226:227], v164, s[20:21] offset:32
	global_load_dwordx2 v[228:229], v122, s[20:21] offset:0
	global_load_dwordx2 v[230:231], v122, s[20:21] offset:32
	global_load_dwordx2 v[232:233], v164, s[20:21] offset:1024
	global_load_dwordx2 v[234:235], v164, s[20:21] offset:1056
	global_load_dwordx2 v[236:237], v122, s[20:21] offset:1024
	global_load_dwordx2 v[238:239], v122, s[20:21] offset:1056
	global_load_dwordx2 v[240:241], v164, s[20:21] offset:2048
	global_load_dwordx2 v[242:243], v164, s[20:21] offset:2080
	global_load_dwordx2 v[244:245], v122, s[20:21] offset:2048
	global_load_dwordx2 v[246:247], v122, s[20:21] offset:2080
	global_load_dwordx2 v[248:249], v164, s[20:21] offset:3072
	global_load_dwordx2 v[250:251], v164, s[20:21] offset:3104
	global_load_dwordx2 v[156:157], v122, s[20:21] offset:3072
	global_load_dwordx2 v[158:159], v122, s[20:21] offset:3104
	s_waitcnt vmcnt(0)
; DI u32x4 pack8(const float (&v)[8]) { u32x4 r = {pk2(v[0], v[1]), pk2(v[2], v[3]), pk2(v[4], v[5]), pk2(v[6], v[7])}; return r; }
; DI void tile_outproj(const Params& p, int l, const Chunk& ck, int tile, int next, PF& pf, char* smem) {
;     ...
;   const int row = tid >> 1, half = tid & 1; float ssq = 0.f;
;   u16* xb = (u16*)(p.ws + OFF_XB) + (size_t)(m0 + row) * 1024 + n0 + half * 64;
; #pragma unroll
;   for (int c8 = 0; c8 < 8; ++c8) {
;     float v[8], x[8]; cs_ld8(Cs, row, half * 64 + c8 * 8, v); unpack8(*(const u32x4*)(xb + c8 * 8), x);
; #pragma unroll
;     for (int j = 0; j < 8; ++j) { v[j] += x[j]; ssq += v[j] * v[j]; }
;     *(u32x4*)(xb + c8 * 8) = pack8(v);
;   }
;   ((float*)(p.ws + OFF_PSMID))[(size_t)(m0 + row) * 16 + ni * 2 + half] = ssq;
	v_mov_b32_e32 v171, 0
	v_lshlrev_b32_e32 v167, 16, v224
	v_and_b32_e32 v168, 0xffff0000, v224
	v_lshlrev_b32_e32 v169, 16, v225
	v_and_b32_e32 v170, 0xffff0000, v225
	v_add_f32_e32 v74, v74, v167
	v_add_f32_e32 v75, v75, v168
	v_add_f32_e32 v76, v76, v169
	v_add_f32_e32 v77, v77, v170
	v_fma_f32 v171, v74, v74, v171
	v_fma_f32 v171, v75, v75, v171
	v_fma_f32 v171, v76, v76, v171
	v_fma_f32 v171, v77, v77, v171
	v_cvt_pk_bf16_f32 v74, v74, v75
	v_cvt_pk_bf16_f32 v75, v76, v77
	global_store_dwordx2 v164, v[74:75], s[20:21]
	v_lshlrev_b32_e32 v167, 16, v226
	v_and_b32_e32 v168, 0xffff0000, v226
	v_lshlrev_b32_e32 v169, 16, v227
	v_and_b32_e32 v170, 0xffff0000, v227
	v_add_f32_e32 v78, v78, v167
	v_add_f32_e32 v79, v79, v168
	v_add_f32_e32 v80, v80, v169
	v_add_f32_e32 v81, v81, v170
	v_fma_f32 v171, v78, v78, v171
	v_fma_f32 v171, v79, v79, v171
	v_fma_f32 v171, v80, v80, v171
	v_fma_f32 v171, v81, v81, v171
	v_cvt_pk_bf16_f32 v78, v78, v79
	v_cvt_pk_bf16_f32 v79, v80, v81
	global_store_dwordx2 v164, v[78:79], s[20:21] offset:32
	v_lshlrev_b32_e32 v167, 16, v228
	v_and_b32_e32 v168, 0xffff0000, v228
	v_lshlrev_b32_e32 v169, 16, v229
	v_and_b32_e32 v170, 0xffff0000, v229
	v_add_f32_e32 v82, v82, v167
	v_add_f32_e32 v83, v83, v168
	v_add_f32_e32 v84, v84, v169
	v_add_f32_e32 v85, v85, v170
	v_fma_f32 v171, v82, v82, v171
	v_fma_f32 v171, v83, v83, v171
	v_fma_f32 v171, v84, v84, v171
	v_fma_f32 v171, v85, v85, v171
	v_cvt_pk_bf16_f32 v82, v82, v83
	v_cvt_pk_bf16_f32 v83, v84, v85
	global_store_dwordx2 v122, v[82:83], s[20:21]
	v_lshlrev_b32_e32 v167, 16, v230
	v_and_b32_e32 v168, 0xffff0000, v230
	v_lshlrev_b32_e32 v169, 16, v231
	v_and_b32_e32 v170, 0xffff0000, v231
	v_add_f32_e32 v86, v86, v167
	v_add_f32_e32 v87, v87, v168
	v_add_f32_e32 v88, v88, v169
	v_add_f32_e32 v89, v89, v170
	v_fma_f32 v171, v86, v86, v171
	v_fma_f32 v171, v87, v87, v171
	v_fma_f32 v171, v88, v88, v171
	v_fma_f32 v171, v89, v89, v171
	v_cvt_pk_bf16_f32 v86, v86, v87
	v_cvt_pk_bf16_f32 v87, v88, v89
	global_store_dwordx2 v122, v[86:87], s[20:21] offset:32
	v_mov_b32_e32 v167, v171
	s_nop 1
	v_permlane32_swap_b32_e32 v171, v167
	v_add_f32_e32 v171, v171, v167
	ds_swizzle_b32 v167, v171 offset:0x401f
	s_waitcnt lgkmcnt(0)
	v_add_f32_e32 v171, v171, v167
	v_cmp_gt_u32_e32 vcc, 16, v160
	s_and_saveexec_b64 s[98:99], vcc
	global_store_dword v166, v171, s[14:15] offset:8
	s_or_b64 exec, exec, s[98:99]
	v_mov_b32_e32 v171, 0
	v_lshlrev_b32_e32 v167, 16, v232
	v_and_b32_e32 v168, 0xffff0000, v232
	v_lshlrev_b32_e32 v169, 16, v233
	v_and_b32_e32 v170, 0xffff0000, v233
	v_add_f32_e32 v90, v90, v167
	v_add_f32_e32 v91, v91, v168
	v_add_f32_e32 v92, v92, v169
	v_add_f32_e32 v93, v93, v170
	v_fma_f32 v171, v90, v90, v171
	v_fma_f32 v171, v91, v91, v171
	v_fma_f32 v171, v92, v92, v171
	v_fma_f32 v171, v93, v93, v171
	v_cvt_pk_bf16_f32 v90, v90, v91
	v_cvt_pk_bf16_f32 v91, v92, v93
	global_store_dwordx2 v164, v[90:91], s[20:21] offset:1024
	v_lshlrev_b32_e32 v167, 16, v234
	v_and_b32_e32 v168, 0xffff0000, v234
	v_lshlrev_b32_e32 v169, 16, v235
	v_and_b32_e32 v170, 0xffff0000, v235
	v_add_f32_e32 v94, v94, v167
	v_add_f32_e32 v95, v95, v168
	v_add_f32_e32 v96, v96, v169
	v_add_f32_e32 v97, v97, v170
	v_fma_f32 v171, v94, v94, v171
	v_fma_f32 v171, v95, v95, v171
	v_fma_f32 v171, v96, v96, v171
	v_fma_f32 v171, v97, v97, v171
	v_cvt_pk_bf16_f32 v94, v94, v95
	v_cvt_pk_bf16_f32 v95, v96, v97
	global_store_dwordx2 v164, v[94:95], s[20:21] offset:1056
	v_lshlrev_b32_e32 v167, 16, v236
	v_and_b32_e32 v168, 0xffff0000, v236
	v_lshlrev_b32_e32 v169, 16, v237
	v_and_b32_e32 v170, 0xffff0000, v237
	v_add_f32_e32 v98, v98, v167
	v_add_f32_e32 v99, v99, v168
	v_add_f32_e32 v100, v100, v169
	v_add_f32_e32 v101, v101, v170
	v_fma_f32 v171, v98, v98, v171
	v_fma_f32 v171, v99, v99, v171
	v_fma_f32 v171, v100, v100, v171
	v_fma_f32 v171, v101, v101, v171
	v_cvt_pk_bf16_f32 v98, v98, v99
	v_cvt_pk_bf16_f32 v99, v100, v101
	global_store_dwordx2 v122, v[98:99], s[20:21] offset:1024
	v_lshlrev_b32_e32 v167, 16, v238
	v_and_b32_e32 v168, 0xffff0000, v238
	v_lshlrev_b32_e32 v169, 16, v239
	v_and_b32_e32 v170, 0xffff0000, v239
	v_add_f32_e32 v102, v102, v167
	v_add_f32_e32 v103, v103, v168
	v_add_f32_e32 v104, v104, v169
	v_add_f32_e32 v105, v105, v170
	v_fma_f32 v171, v102, v102, v171
	v_fma_f32 v171, v103, v103, v171
	v_fma_f32 v171, v104, v104, v171
	v_fma_f32 v171, v105, v105, v171
	v_cvt_pk_bf16_f32 v102, v102, v103
	v_cvt_pk_bf16_f32 v103, v104, v105
	global_store_dwordx2 v122, v[102:103], s[20:21] offset:1056
	v_mov_b32_e32 v167, v171
	s_nop 1
	v_permlane32_swap_b32_e32 v171, v167
	v_add_f32_e32 v171, v171, v167
	ds_swizzle_b32 v167, v171 offset:0x401f
	s_waitcnt lgkmcnt(0)
; DI u32x4 pack8(const float (&v)[8]) { u32x4 r = {pk2(v[0], v[1]), pk2(v[2], v[3]), pk2(v[4], v[5]), pk2(v[6], v[7])}; return r; }
; DI void tile_outproj(const Params& p, int l, const Chunk& ck, int tile, int next, PF& pf, char* smem) {
;     ...
;   const int row = tid >> 1, half = tid & 1; float ssq = 0.f;
;   u16* xb = (u16*)(p.ws + OFF_XB) + (size_t)(m0 + row) * 1024 + n0 + half * 64;
; #pragma unroll
;   for (int c8 = 0; c8 < 8; ++c8) {
;     float v[8], x[8]; cs_ld8(Cs, row, half * 64 + c8 * 8, v); unpack8(*(const u32x4*)(xb + c8 * 8), x);
; #pragma unroll
;     for (int j = 0; j < 8; ++j) { v[j] += x[j]; ssq += v[j] * v[j]; }
;     *(u32x4*)(xb + c8 * 8) = pack8(v);
;   }
;   ((float*)(p.ws + OFF_PSMID))[(size_t)(m0 + row) * 16 + ni * 2 + half] = ssq;
	v_add_f32_e32 v171, v171, v167
	v_cmp_gt_u32_e32 vcc, 16, v160
	s_and_saveexec_b64 s[98:99], vcc
	global_store_dword v166, v171, s[14:15] offset:1032
	s_or_b64 exec, exec, s[98:99]
	v_mov_b32_e32 v171, 0
	v_lshlrev_b32_e32 v167, 16, v240
	v_and_b32_e32 v168, 0xffff0000, v240
	v_lshlrev_b32_e32 v169, 16, v241
	v_and_b32_e32 v170, 0xffff0000, v241
	v_add_f32_e32 v106, v106, v167
	v_add_f32_e32 v107, v107, v168
	v_add_f32_e32 v108, v108, v169
	v_add_f32_e32 v109, v109, v170
	v_fma_f32 v171, v106, v106, v171
	v_fma_f32 v171, v107, v107, v171
	v_fma_f32 v171, v108, v108, v171
	v_fma_f32 v171, v109, v109, v171
	v_cvt_pk_bf16_f32 v106, v106, v107
	v_cvt_pk_bf16_f32 v107, v108, v109
	global_store_dwordx2 v164, v[106:107], s[20:21] offset:2048
	v_lshlrev_b32_e32 v167, 16, v242
	v_and_b32_e32 v168, 0xffff0000, v242
	v_lshlrev_b32_e32 v169, 16, v243
	v_and_b32_e32 v170, 0xffff0000, v243
	v_add_f32_e32 v110, v110, v167
	v_add_f32_e32 v111, v111, v168
	v_add_f32_e32 v112, v112, v169
	v_add_f32_e32 v113, v113, v170
	v_fma_f32 v171, v110, v110, v171
	v_fma_f32 v171, v111, v111, v171
	v_fma_f32 v171, v112, v112, v171
	v_fma_f32 v171, v113, v113, v171
	v_cvt_pk_bf16_f32 v110, v110, v111
	v_cvt_pk_bf16_f32 v111, v112, v113
	global_store_dwordx2 v164, v[110:111], s[20:21] offset:2080
	v_lshlrev_b32_e32 v167, 16, v244
	v_and_b32_e32 v168, 0xffff0000, v244
	v_lshlrev_b32_e32 v169, 16, v245
	v_and_b32_e32 v170, 0xffff0000, v245
	v_add_f32_e32 v114, v114, v167
	v_add_f32_e32 v115, v115, v168
	v_add_f32_e32 v116, v116, v169
	v_add_f32_e32 v117, v117, v170
	v_fma_f32 v171, v114, v114, v171
	v_fma_f32 v171, v115, v115, v171
	v_fma_f32 v171, v116, v116, v171
	v_fma_f32 v171, v117, v117, v171
	v_cvt_pk_bf16_f32 v114, v114, v115
	v_cvt_pk_bf16_f32 v115, v116, v117
	global_store_dwordx2 v122, v[114:115], s[20:21] offset:2048
	v_lshlrev_b32_e32 v167, 16, v246
	v_and_b32_e32 v168, 0xffff0000, v246
	v_lshlrev_b32_e32 v169, 16, v247
	v_and_b32_e32 v170, 0xffff0000, v247
	v_add_f32_e32 v118, v118, v167
	v_add_f32_e32 v119, v119, v168
	v_add_f32_e32 v120, v120, v169
	v_add_f32_e32 v121, v121, v170
	v_fma_f32 v171, v118, v118, v171
	v_fma_f32 v171, v119, v119, v171
	v_fma_f32 v171, v120, v120, v171
	v_fma_f32 v171, v121, v121, v171
	v_cvt_pk_bf16_f32 v118, v118, v119
	v_cvt_pk_bf16_f32 v119, v120, v121
	global_store_dwordx2 v122, v[118:119], s[20:21] offset:2080
	v_mov_b32_e32 v167, v171
	s_nop 1
	v_permlane32_swap_b32_e32 v171, v167
	v_add_f32_e32 v171, v171, v167
	ds_swizzle_b32 v167, v171 offset:0x401f
	s_waitcnt lgkmcnt(0)
	v_add_f32_e32 v171, v171, v167
	v_cmp_gt_u32_e32 vcc, 16, v160
	s_and_saveexec_b64 s[98:99], vcc
	global_store_dword v166, v171, s[14:15] offset:2056
	s_or_b64 exec, exec, s[98:99]
	v_mov_b32_e32 v171, 0
	v_lshlrev_b32_e32 v167, 16, v248
	v_and_b32_e32 v168, 0xffff0000, v248
	v_lshlrev_b32_e32 v169, 16, v249
	v_and_b32_e32 v170, 0xffff0000, v249
	v_add_f32_e32 v208, v208, v167
	v_add_f32_e32 v209, v209, v168
	v_add_f32_e32 v210, v210, v169
	v_add_f32_e32 v211, v211, v170
	v_fma_f32 v171, v208, v208, v171
	v_fma_f32 v171, v209, v209, v171
	v_fma_f32 v171, v210, v210, v171
	v_fma_f32 v171, v211, v211, v171
	v_cvt_pk_bf16_f32 v208, v208, v209
	v_cvt_pk_bf16_f32 v209, v210, v211
	global_store_dwordx2 v164, v[208:209], s[20:21] offset:3072
	v_lshlrev_b32_e32 v167, 16, v250
	v_and_b32_e32 v168, 0xffff0000, v250
	v_lshlrev_b32_e32 v169, 16, v251
	v_and_b32_e32 v170, 0xffff0000, v251
	v_add_f32_e32 v212, v212, v167
	v_add_f32_e32 v213, v213, v168
	v_add_f32_e32 v214, v214, v169
	v_add_f32_e32 v215, v215, v170
	v_fma_f32 v171, v212, v212, v171
	v_fma_f32 v171, v213, v213, v171
	v_fma_f32 v171, v214, v214, v171
	v_fma_f32 v171, v215, v215, v171
	v_cvt_pk_bf16_f32 v212, v212, v213
	v_cvt_pk_bf16_f32 v213, v214, v215
	global_store_dwordx2 v164, v[212:213], s[20:21] offset:3104
	v_lshlrev_b32_e32 v167, 16, v156
	v_and_b32_e32 v168, 0xffff0000, v156
	v_lshlrev_b32_e32 v169, 16, v157
	v_and_b32_e32 v170, 0xffff0000, v157
	v_add_f32_e32 v216, v216, v167
	v_add_f32_e32 v217, v217, v168
	v_add_f32_e32 v218, v218, v169
	v_add_f32_e32 v219, v219, v170
	v_fma_f32 v171, v216, v216, v171
	v_fma_f32 v171, v217, v217, v171
	v_fma_f32 v171, v218, v218, v171
	v_fma_f32 v171, v219, v219, v171
	v_cvt_pk_bf16_f32 v216, v216, v217
	v_cvt_pk_bf16_f32 v217, v218, v219
	global_store_dwordx2 v122, v[216:217], s[20:21] offset:3072
	v_lshlrev_b32_e32 v167, 16, v158
	v_and_b32_e32 v168, 0xffff0000, v158
	v_lshlrev_b32_e32 v169, 16, v159
	v_and_b32_e32 v170, 0xffff0000, v159
	v_add_f32_e32 v220, v220, v167
	v_add_f32_e32 v221, v221, v168
	v_add_f32_e32 v222, v222, v169
	v_add_f32_e32 v223, v223, v170
	v_fma_f32 v171, v220, v220, v171
	v_fma_f32 v171, v221, v221, v171
	v_fma_f32 v171, v222, v222, v171
	v_fma_f32 v171, v223, v223, v171
	v_cvt_pk_bf16_f32 v220, v220, v221
	v_cvt_pk_bf16_f32 v221, v222, v223
	global_store_dwordx2 v122, v[220:221], s[20:21] offset:3104
	v_mov_b32_e32 v167, v171
	s_nop 1
	v_permlane32_swap_b32_e32 v171, v167
	v_add_f32_e32 v171, v171, v167
	ds_swizzle_b32 v167, v171 offset:0x401f
	s_waitcnt lgkmcnt(0)
	v_add_f32_e32 v171, v171, v167
	v_cmp_gt_u32_e32 vcc, 16, v160
	s_and_saveexec_b64 s[98:99], vcc
	global_store_dword v166, v171, s[14:15] offset:3080
	s_or_b64 exec, exec, s[98:99]
	s_branch .LBB1_254

; #define BLOAD(A_, B_, kt) do { _Pragma("unroll") for (int i = 0; i < 4; ++i) { \
;     A_[i] = *(const u32x4*)((const char*)Ap + (aoff + (unsigned)(32 * i * lda + (kt) * 64) * 2u)); B_[i] = *(const u32x4*)((const char*)Wt + (woff + (unsigned)(32 * i * K + (kt) * 64) * 2u)); } } while (0)
; #define BLOAD(A_, B_, kt) do { _Pragma("unroll") for (int i = 0; i < 4; ++i) { \
;     A_[i] = *(const u32x4*)((const char*)Ap + (aoff + (unsigned)(32 * i * lda + (kt) * 64) * 2u)); B_[i] = *(const u32x4*)((const char*)Wt + (woff + (unsigned)(32 * i * K + (kt) * 64) * 2u)); } } while (0)
; #define BSTORE(A_, B_, buf) do { _Pragma("unroll") for (int i = 0; i < 4; ++i) { \
;     *(u32x4*)&As[(buf) * GBUF + (srow + 32 * i) * LDT + sc8] = A_[i]; \
;     *(u32x4*)&Bs[(buf) * GBUF + (srow + 32 * i) * LDT + sc8] = B_[i]; } } while (0)
; template <bool ROWNORM, int NK>
; DI void gemm_main_bf(const u16* __restrict__ Ap, int lda, const u16* __restrict__ Wt, f32x16 (&acc)[2][2], char* smem, float* rinv_s) {
;     ...
;   __builtin_amdgcn_s_setprio(0);
;   BLOAD(a0, b0, 0); BLOAD(a1, b1, 1);
;   __syncthreads();
;   BSTORE(a0, b0, 0);
;   BLOAD(a0, b0, 2);
;   __syncthreads();
; #pragma unroll
;   for (int kt = 0; kt < nk; kt += 2) {
;     BCOMP(0);
;     BSTORE(a1, b1, 1);
;     if (kt + 3 < nk) BLOAD(a1, b1, kt + 3);
;     __syncthreads();
;     BCOMP(1);
;     if (kt + 2 < nk) { BSTORE(a0, b0, 0); if (kt + 4 < nk) BLOAD(a0, b0, kt + 4); }
;     __syncthreads();
.Lbr_gate_k:
	s_waitcnt vmcnt(8)
	s_barrier
	ds_read_b128 v[208:211], v240 offset:0
	ds_read_b128 v[224:227], v241 offset:0
	ds_read_b128 v[228:231], v241 offset:1024
	ds_read_b128 v[232:235], v241 offset:2048
	ds_read_b128 v[236:239], v241 offset:3072
	s_add_u32 m0, s52, 0xc000
	s_add_u32 s28, s28, 0x100000
	s_addc_u32 s29, s29, 0
	global_load_lds_dwordx4 v251, s[28:29]
	global_load_lds_dwordx4 v251, s[28:29] offset:1024
	s_add_u32 m0, s53, 0xc000
	s_add_u32 s30, s30, 0x30000
	s_addc_u32 s31, s31, 0
	global_load_lds_dwordx4 v251, s[30:31]
	global_load_lds_dwordx4 v251, s[30:31] offset:1024
	ds_read_b128 v[212:215], v240 offset:1024
	ds_read_b128 v[216:219], v240 offset:2048
	ds_read_b128 v[220:223], v240 offset:3072
	s_waitcnt lgkmcnt(3)
	v_mfma_f32_16x16x32_bf16 v[2:5], v[224:227], v[208:211], v[2:5]
	v_mfma_f32_16x16x32_bf16 v[6:9], v[228:231], v[208:211], v[6:9]
	v_mfma_f32_16x16x32_bf16 v[10:13], v[232:235], v[208:211], v[10:13]
	v_mfma_f32_16x16x32_bf16 v[14:17], v[236:239], v[208:211], v[14:17]
	s_waitcnt lgkmcnt(0)
	v_mfma_f32_16x16x32_bf16 v[18:21], v[224:227], v[212:215], v[18:21]
	v_mfma_f32_16x16x32_bf16 v[22:25], v[228:231], v[212:215], v[22:25]
	v_mfma_f32_16x16x32_bf16 v[26:29], v[232:235], v[212:215], v[26:29]
	v_mfma_f32_16x16x32_bf16 v[30:33], v[236:239], v[212:215], v[30:33]
	v_mfma_f32_16x16x32_bf16 v[34:37], v[224:227], v[216:219], v[34:37]
	v_mfma_f32_16x16x32_bf16 v[38:41], v[228:231], v[216:219], v[38:41]
	v_mfma_f32_16x16x32_bf16 v[42:45], v[232:235], v[216:219], v[42:45]
	v_mfma_f32_16x16x32_bf16 v[46:49], v[236:239], v[216:219], v[46:49]
	v_mfma_f32_16x16x32_bf16 v[50:53], v[224:227], v[220:223], v[50:53]
	v_mfma_f32_16x16x32_bf16 v[54:57], v[228:231], v[220:223], v[54:57]
	v_mfma_f32_16x16x32_bf16 v[58:61], v[232:235], v[220:223], v[58:61]
	v_mfma_f32_16x16x32_bf16 v[62:65], v[236:239], v[220:223], v[62:65]
	s_waitcnt vmcnt(8)
	s_barrier
	ds_read_b128 v[208:211], v240 offset:16384
	ds_read_b128 v[224:227], v241 offset:16384
	ds_read_b128 v[228:231], v241 offset:17408
	ds_read_b128 v[232:235], v241 offset:18432
	ds_read_b128 v[236:239], v241 offset:19456
	s_add_u32 m0, s52, 0x0
	s_add_u32 s28, s28, 0x100000
	s_addc_u32 s29, s29, 0
	global_load_lds_dwordx4 v251, s[28:29]
	global_load_lds_dwordx4 v251, s[28:29] offset:1024
	s_add_u32 m0, s53, 0x0
	s_add_u32 s30, s30, 0x30000
	s_addc_u32 s31, s31, 0
	global_load_lds_dwordx4 v251, s[30:31]
	global_load_lds_dwordx4 v251, s[30:31] offset:1024
	ds_read_b128 v[212:215], v240 offset:17408
	ds_read_b128 v[216:219], v240 offset:18432
	ds_read_b128 v[220:223], v240 offset:19456
	s_waitcnt lgkmcnt(3)
	v_mfma_f32_16x16x32_bf16 v[2:5], v[224:227], v[208:211], v[2:5]
	v_mfma_f32_16x16x32_bf16 v[6:9], v[228:231], v[208:211], v[6:9]
	v_mfma_f32_16x16x32_bf16 v[10:13], v[232:235], v[208:211], v[10:13]
	v_mfma_f32_16x16x32_bf16 v[14:17], v[236:239], v[208:211], v[14:17]
	s_waitcnt lgkmcnt(0)
	v_mfma_f32_16x16x32_bf16 v[18:21], v[224:227], v[212:215], v[18:21]
	v_mfma_f32_16x16x32_bf16 v[22:25], v[228:231], v[212:215], v[22:25]
	v_mfma_f32_16x16x32_bf16 v[26:29], v[232:235], v[212:215], v[26:29]
	v_mfma_f32_16x16x32_bf16 v[30:33], v[236:239], v[212:215], v[30:33]
	v_mfma_f32_16x16x32_bf16 v[34:37], v[224:227], v[216:219], v[34:37]
	v_mfma_f32_16x16x32_bf16 v[38:41], v[228:231], v[216:219], v[38:41]
	v_mfma_f32_16x16x32_bf16 v[42:45], v[232:235], v[216:219], v[42:45]
	v_mfma_f32_16x16x32_bf16 v[46:49], v[236:239], v[216:219], v[46:49]
	v_mfma_f32_16x16x32_bf16 v[50:53], v[224:227], v[220:223], v[50:53]
	v_mfma_f32_16x16x32_bf16 v[54:57], v[228:231], v[220:223], v[54:57]
	v_mfma_f32_16x16x32_bf16 v[58:61], v[232:235], v[220:223], v[58:61]
	v_mfma_f32_16x16x32_bf16 v[62:65], v[236:239], v[220:223], v[62:65]
	s_waitcnt vmcnt(8)
	s_barrier
	ds_read_b128 v[208:211], v240 offset:32768
	ds_read_b128 v[224:227], v241 offset:32768
	ds_read_b128 v[228:231], v241 offset:33792
	ds_read_b128 v[232:235], v241 offset:34816
	ds_read_b128 v[236:239], v241 offset:35840
	s_add_u32 m0, s52, 0x4000
	s_add_u32 s28, s28, 0x100000
	s_addc_u32 s29, s29, 0
	global_load_lds_dwordx4 v251, s[28:29]
	global_load_lds_dwordx4 v251, s[28:29] offset:1024
	s_add_u32 m0, s53, 0x4000
	s_add_u32 s30, s30, 0x30000
	s_addc_u32 s31, s31, 0
	global_load_lds_dwordx4 v251, s[30:31]
	global_load_lds_dwordx4 v251, s[30:31] offset:1024
	ds_read_b128 v[212:215], v240 offset:33792
	ds_read_b128 v[216:219], v240 offset:34816
	ds_read_b128 v[220:223], v240 offset:35840
	s_waitcnt lgkmcnt(3)
	v_mfma_f32_16x16x32_bf16 v[2:5], v[224:227], v[208:211], v[2:5]
	v_mfma_f32_16x16x32_bf16 v[6:9], v[228:231], v[208:211], v[6:9]
	v_mfma_f32_16x16x32_bf16 v[10:13], v[232:235], v[208:211], v[10:13]
	v_mfma_f32_16x16x32_bf16 v[14:17], v[236:239], v[208:211], v[14:17]
	s_waitcnt lgkmcnt(0)
	v_mfma_f32_16x16x32_bf16 v[18:21], v[224:227], v[212:215], v[18:21]
	v_mfma_f32_16x16x32_bf16 v[22:25], v[228:231], v[212:215], v[22:25]
	v_mfma_f32_16x16x32_bf16 v[26:29], v[232:235], v[212:215], v[26:29]
	v_mfma_f32_16x16x32_bf16 v[30:33], v[236:239], v[212:215], v[30:33]
	v_mfma_f32_16x16x32_bf16 v[34:37], v[224:227], v[216:219], v[34:37]
	v_mfma_f32_16x16x32_bf16 v[38:41], v[228:231], v[216:219], v[38:41]
	v_mfma_f32_16x16x32_bf16 v[42:45], v[232:235], v[216:219], v[42:45]
	v_mfma_f32_16x16x32_bf16 v[46:49], v[236:239], v[216:219], v[46:49]
	v_mfma_f32_16x16x32_bf16 v[50:53], v[224:227], v[220:223], v[50:53]
	v_mfma_f32_16x16x32_bf16 v[54:57], v[228:231], v[220:223], v[54:57]
	v_mfma_f32_16x16x32_bf16 v[58:61], v[232:235], v[220:223], v[58:61]
	v_mfma_f32_16x16x32_bf16 v[62:65], v[236:239], v[220:223], v[62:65]
	s_waitcnt vmcnt(8)
	s_barrier
; #define BLOAD(A_, B_, kt) do { _Pragma("unroll") for (int i = 0; i < 4; ++i) { \
;     A_[i] = *(const u32x4*)((const char*)Ap + (aoff + (unsigned)(32 * i * lda + (kt) * 64) * 2u)); B_[i] = *(const u32x4*)((const char*)Wt + (woff + (unsigned)(32 * i * K + (kt) * 64) * 2u)); } } while (0)
; #define BLOAD(A_, B_, kt) do { _Pragma("unroll") for (int i = 0; i < 4; ++i) { \
;     A_[i] = *(const u32x4*)((const char*)Ap + (aoff + (unsigned)(32 * i * lda + (kt) * 64) * 2u)); B_[i] = *(const u32x4*)((const char*)Wt + (woff + (unsigned)(32 * i * K + (kt) * 64) * 2u)); } } while (0)
; #define BSTORE(A_, B_, buf) do { _Pragma("unroll") for (int i = 0; i < 4; ++i) { \
;     *(u32x4*)&As[(buf) * GBUF + (srow + 32 * i) * LDT + sc8] = A_[i]; \
;     *(u32x4*)&Bs[(buf) * GBUF + (srow + 32 * i) * LDT + sc8] = B_[i]; } } while (0)
; template <bool ROWNORM, int NK>
; DI void gemm_main_bf(const u16* __restrict__ Ap, int lda, const u16* __restrict__ Wt, f32x16 (&acc)[2][2], char* smem, float* rinv_s) {
;     ...
;   __builtin_amdgcn_s_setprio(0);
;   BLOAD(a0, b0, 0); BLOAD(a1, b1, 1);
;   __syncthreads();
;   BSTORE(a0, b0, 0);
;   BLOAD(a0, b0, 2);
;   __syncthreads();
; #pragma unroll
;   for (int kt = 0; kt < nk; kt += 2) {
;     BCOMP(0);
;     BSTORE(a1, b1, 1);
;     if (kt + 3 < nk) BLOAD(a1, b1, kt + 3);
;     __syncthreads();
;     BCOMP(1);
;     if (kt + 2 < nk) { BSTORE(a0, b0, 0); if (kt + 4 < nk) BLOAD(a0, b0, kt + 4); }
;     __syncthreads();
	ds_read_b128 v[208:211], v240 offset:49152
	ds_read_b128 v[224:227], v241 offset:49152
	ds_read_b128 v[228:231], v241 offset:50176
	ds_read_b128 v[232:235], v241 offset:51200
	ds_read_b128 v[236:239], v241 offset:52224
	s_add_u32 m0, s52, 0x8000
	s_add_u32 s28, s28, 0x100000
	s_addc_u32 s29, s29, 0
	global_load_lds_dwordx4 v251, s[28:29]
	global_load_lds_dwordx4 v251, s[28:29] offset:1024
	s_add_u32 m0, s53, 0x8000
	s_add_u32 s30, s30, 0x30000
	s_addc_u32 s31, s31, 0
	global_load_lds_dwordx4 v251, s[30:31]
	global_load_lds_dwordx4 v251, s[30:31] offset:1024
	ds_read_b128 v[212:215], v240 offset:50176
	ds_read_b128 v[216:219], v240 offset:51200
	ds_read_b128 v[220:223], v240 offset:52224
	s_waitcnt lgkmcnt(3)
	v_mfma_f32_16x16x32_bf16 v[2:5], v[224:227], v[208:211], v[2:5]
	v_mfma_f32_16x16x32_bf16 v[6:9], v[228:231], v[208:211], v[6:9]
	v_mfma_f32_16x16x32_bf16 v[10:13], v[232:235], v[208:211], v[10:13]
	v_mfma_f32_16x16x32_bf16 v[14:17], v[236:239], v[208:211], v[14:17]
	s_waitcnt lgkmcnt(0)
	v_mfma_f32_16x16x32_bf16 v[18:21], v[224:227], v[212:215], v[18:21]
	v_mfma_f32_16x16x32_bf16 v[22:25], v[228:231], v[212:215], v[22:25]
	v_mfma_f32_16x16x32_bf16 v[26:29], v[232:235], v[212:215], v[26:29]
	v_mfma_f32_16x16x32_bf16 v[30:33], v[236:239], v[212:215], v[30:33]
	v_mfma_f32_16x16x32_bf16 v[34:37], v[224:227], v[216:219], v[34:37]
	v_mfma_f32_16x16x32_bf16 v[38:41], v[228:231], v[216:219], v[38:41]
	v_mfma_f32_16x16x32_bf16 v[42:45], v[232:235], v[216:219], v[42:45]
	v_mfma_f32_16x16x32_bf16 v[46:49], v[236:239], v[216:219], v[46:49]
	v_mfma_f32_16x16x32_bf16 v[50:53], v[224:227], v[220:223], v[50:53]
	v_mfma_f32_16x16x32_bf16 v[54:57], v[228:231], v[220:223], v[54:57]
	v_mfma_f32_16x16x32_bf16 v[58:61], v[232:235], v[220:223], v[58:61]
	v_mfma_f32_16x16x32_bf16 v[62:65], v[236:239], v[220:223], v[62:65]
	s_sub_u32 s74, s74, 1
	s_cmp_lg_u32 s74, 0
	s_cbranch_scc1 .Lbr_gate_k
	s_waitcnt vmcnt(8)
	s_barrier
	ds_read_b128 v[208:211], v240 offset:0
	ds_read_b128 v[224:227], v241 offset:0
	ds_read_b128 v[228:231], v241 offset:1024
	ds_read_b128 v[232:235], v241 offset:2048
	ds_read_b128 v[236:239], v241 offset:3072
	s_add_u32 m0, s52, 0xc000
	s_add_u32 s28, s28, 0x100000
	s_addc_u32 s29, s29, 0
	global_load_lds_dwordx4 v251, s[28:29]
	global_load_lds_dwordx4 v251, s[28:29] offset:1024
	s_add_u32 m0, s53, 0xc000
	s_add_u32 s30, s30, 0x30000
	s_addc_u32 s31, s31, 0
	global_load_lds_dwordx4 v251, s[30:31]
	global_load_lds_dwordx4 v251, s[30:31] offset:1024
	ds_read_b128 v[212:215], v240 offset:1024
	ds_read_b128 v[216:219], v240 offset:2048
	ds_read_b128 v[220:223], v240 offset:3072
	s_waitcnt lgkmcnt(3)
	v_mfma_f32_16x16x32_bf16 v[2:5], v[224:227], v[208:211], v[2:5]
	v_mfma_f32_16x16x32_bf16 v[6:9], v[228:231], v[208:211], v[6:9]
	v_mfma_f32_16x16x32_bf16 v[10:13], v[232:235], v[208:211], v[10:13]
	v_mfma_f32_16x16x32_bf16 v[14:17], v[236:239], v[208:211], v[14:17]
	s_waitcnt lgkmcnt(0)
	v_mfma_f32_16x16x32_bf16 v[18:21], v[224:227], v[212:215], v[18:21]
	v_mfma_f32_16x16x32_bf16 v[22:25], v[228:231], v[212:215], v[22:25]
	v_mfma_f32_16x16x32_bf16 v[26:29], v[232:235], v[212:215], v[26:29]
	v_mfma_f32_16x16x32_bf16 v[30:33], v[236:239], v[212:215], v[30:33]
	v_mfma_f32_16x16x32_bf16 v[34:37], v[224:227], v[216:219], v[34:37]
	v_mfma_f32_16x16x32_bf16 v[38:41], v[228:231], v[216:219], v[38:41]
	v_mfma_f32_16x16x32_bf16 v[42:45], v[232:235], v[216:219], v[42:45]
	v_mfma_f32_16x16x32_bf16 v[46:49], v[236:239], v[216:219], v[46:49]
	v_mfma_f32_16x16x32_bf16 v[50:53], v[224:227], v[220:223], v[50:53]
	v_mfma_f32_16x16x32_bf16 v[54:57], v[228:231], v[220:223], v[54:57]
	v_mfma_f32_16x16x32_bf16 v[58:61], v[232:235], v[220:223], v[58:61]
	v_mfma_f32_16x16x32_bf16 v[62:65], v[236:239], v[220:223], v[62:65]
	s_waitcnt vmcnt(8)
	s_barrier
	ds_read_b128 v[208:211], v240 offset:16384
	ds_read_b128 v[224:227], v241 offset:16384
	ds_read_b128 v[228:231], v241 offset:17408
	ds_read_b128 v[232:235], v241 offset:18432
	ds_read_b128 v[236:239], v241 offset:19456
	ds_read_b128 v[212:215], v240 offset:17408
	ds_read_b128 v[216:219], v240 offset:18432
	ds_read_b128 v[220:223], v240 offset:19456
	s_waitcnt lgkmcnt(3)
	v_mfma_f32_16x16x32_bf16 v[2:5], v[224:227], v[208:211], v[2:5]
	v_mfma_f32_16x16x32_bf16 v[6:9], v[228:231], v[208:211], v[6:9]
	v_mfma_f32_16x16x32_bf16 v[10:13], v[232:235], v[208:211], v[10:13]
	v_mfma_f32_16x16x32_bf16 v[14:17], v[236:239], v[208:211], v[14:17]
	s_waitcnt lgkmcnt(0)
	v_mfma_f32_16x16x32_bf16 v[18:21], v[224:227], v[212:215], v[18:21]
	v_mfma_f32_16x16x32_bf16 v[22:25], v[228:231], v[212:215], v[22:25]
	v_mfma_f32_16x16x32_bf16 v[26:29], v[232:235], v[212:215], v[26:29]
	v_mfma_f32_16x16x32_bf16 v[30:33], v[236:239], v[212:215], v[30:33]
	v_mfma_f32_16x16x32_bf16 v[34:37], v[224:227], v[216:219], v[34:37]
	v_mfma_f32_16x16x32_bf16 v[38:41], v[228:231], v[216:219], v[38:41]
	v_mfma_f32_16x16x32_bf16 v[42:45], v[232:235], v[216:219], v[42:45]
	v_mfma_f32_16x16x32_bf16 v[46:49], v[236:239], v[216:219], v[46:49]
	v_mfma_f32_16x16x32_bf16 v[50:53], v[224:227], v[220:223], v[50:53]
	v_mfma_f32_16x16x32_bf16 v[54:57], v[228:231], v[220:223], v[54:57]
	v_mfma_f32_16x16x32_bf16 v[58:61], v[232:235], v[220:223], v[58:61]
	v_mfma_f32_16x16x32_bf16 v[62:65], v[236:239], v[220:223], v[62:65]
	s_waitcnt vmcnt(4)
	s_barrier
; DI unsigned pk2(float a, float b) { f2_t v = {a, b}; bf2_t r = __builtin_convertvector(v, bf2_t); return __builtin_bit_cast(unsigned, r); }
; #define BLOAD(A_, B_, kt) do { _Pragma("unroll") for (int i = 0; i < 4; ++i) { \
;     A_[i] = *(const u32x4*)((const char*)Ap + (aoff + (unsigned)(32 * i * lda + (kt) * 64) * 2u)); B_[i] = *(const u32x4*)((const char*)Wt + (woff + (unsigned)(32 * i * K + (kt) * 64) * 2u)); } } while (0)
; #define BLOAD(A_, B_, kt) do { _Pragma("unroll") for (int i = 0; i < 4; ++i) { \
;     A_[i] = *(const u32x4*)((const char*)Ap + (aoff + (unsigned)(32 * i * lda + (kt) * 64) * 2u)); B_[i] = *(const u32x4*)((const char*)Wt + (woff + (unsigned)(32 * i * K + (kt) * 64) * 2u)); } } while (0)
; #define BSTORE(A_, B_, buf) do { _Pragma("unroll") for (int i = 0; i < 4; ++i) { \
;     *(u32x4*)&As[(buf) * GBUF + (srow + 32 * i) * LDT + sc8] = A_[i]; \
;     *(u32x4*)&Bs[(buf) * GBUF + (srow + 32 * i) * LDT + sc8] = B_[i]; } } while (0)
; template <bool ROWNORM, int NK>
; DI void gemm_main_bf(const u16* __restrict__ Ap, int lda, const u16* __restrict__ Wt, f32x16 (&acc)[2][2], char* smem, float* rinv_s) {
;     ...
;   __builtin_amdgcn_s_setprio(0);
;   BLOAD(a0, b0, 0); BLOAD(a1, b1, 1);
;   __syncthreads();
;   BSTORE(a0, b0, 0);
;   BLOAD(a0, b0, 2);
;   __syncthreads();
; #pragma unroll
;   for (int kt = 0; kt < nk; kt += 2) {
;     BCOMP(0);
;     BSTORE(a1, b1, 1);
;     if (kt + 3 < nk) BLOAD(a1, b1, kt + 3);
;     __syncthreads();
;     BCOMP(1);
;     if (kt + 2 < nk) { BSTORE(a0, b0, 0); if (kt + 4 < nk) BLOAD(a0, b0, kt + 4); }
;     __syncthreads();
; DI void tile_branch(const Params& p, int l, int tile, char* smem) {
;     ...
;       __syncthreads();
; #pragma unroll
;       for (int mt = 0; mt < 2; ++mt)
; #pragma unroll
;         for (int g4 = 0; g4 < 4; ++g4) {
;           const f32x4 r4 = *(const f32x4*)&rinv_s[wm * 64 + mt * 32 + 8 * g4 + 4 * hi];
; #pragma unroll
;           for (int nt = 0; nt < 2; ++nt) {
;             const float s0 = 1.f / (1.f + __expf(-accg[mt][nt][4 * g4 + 0] * r4[0])), s1 = 1.f / (1.f + __expf(-accg[mt][nt][4 * g4 + 1] * r4[1]));
;             const float s2 = 1.f / (1.f + __expf(-accg[mt][nt][4 * g4 + 2] * r4[2])), s3 = 1.f / (1.f + __expf(-accg[mt][nt][4 * g4 + 3] * r4[3]));
;             gpk[mt][nt][2 * g4] = pk2(s0, s1); gpk[mt][nt][2 * g4 + 1] = pk2(s2, s3);
;           }
;         }
	ds_read_b128 v[208:211], v240 offset:32768
	ds_read_b128 v[224:227], v241 offset:32768
	ds_read_b128 v[228:231], v241 offset:33792
	ds_read_b128 v[232:235], v241 offset:34816
	ds_read_b128 v[236:239], v241 offset:35840
	ds_read_b128 v[212:215], v240 offset:33792
	ds_read_b128 v[216:219], v240 offset:34816
	ds_read_b128 v[220:223], v240 offset:35840
	s_waitcnt lgkmcnt(3)
	v_mfma_f32_16x16x32_bf16 v[2:5], v[224:227], v[208:211], v[2:5]
	v_mfma_f32_16x16x32_bf16 v[6:9], v[228:231], v[208:211], v[6:9]
	v_mfma_f32_16x16x32_bf16 v[10:13], v[232:235], v[208:211], v[10:13]
	v_mfma_f32_16x16x32_bf16 v[14:17], v[236:239], v[208:211], v[14:17]
	s_waitcnt lgkmcnt(0)
	v_mfma_f32_16x16x32_bf16 v[18:21], v[224:227], v[212:215], v[18:21]
	v_mfma_f32_16x16x32_bf16 v[22:25], v[228:231], v[212:215], v[22:25]
	v_mfma_f32_16x16x32_bf16 v[26:29], v[232:235], v[212:215], v[26:29]
	v_mfma_f32_16x16x32_bf16 v[30:33], v[236:239], v[212:215], v[30:33]
	v_mfma_f32_16x16x32_bf16 v[34:37], v[224:227], v[216:219], v[34:37]
	v_mfma_f32_16x16x32_bf16 v[38:41], v[228:231], v[216:219], v[38:41]
	v_mfma_f32_16x16x32_bf16 v[42:45], v[232:235], v[216:219], v[42:45]
	v_mfma_f32_16x16x32_bf16 v[46:49], v[236:239], v[216:219], v[46:49]
	v_mfma_f32_16x16x32_bf16 v[50:53], v[224:227], v[220:223], v[50:53]
	v_mfma_f32_16x16x32_bf16 v[54:57], v[228:231], v[220:223], v[54:57]
	v_mfma_f32_16x16x32_bf16 v[58:61], v[232:235], v[220:223], v[58:61]
	v_mfma_f32_16x16x32_bf16 v[62:65], v[236:239], v[220:223], v[62:65]
	s_waitcnt vmcnt(0)
	s_barrier
	ds_read_b128 v[208:211], v240 offset:49152
	ds_read_b128 v[224:227], v241 offset:49152
	ds_read_b128 v[228:231], v241 offset:50176
	ds_read_b128 v[232:235], v241 offset:51200
	ds_read_b128 v[236:239], v241 offset:52224
	ds_read_b128 v[212:215], v240 offset:50176
	ds_read_b128 v[216:219], v240 offset:51200
	ds_read_b128 v[220:223], v240 offset:52224
	s_waitcnt lgkmcnt(3)
	v_mfma_f32_16x16x32_bf16 v[2:5], v[224:227], v[208:211], v[2:5]
	v_mfma_f32_16x16x32_bf16 v[6:9], v[228:231], v[208:211], v[6:9]
	v_mfma_f32_16x16x32_bf16 v[10:13], v[232:235], v[208:211], v[10:13]
	v_mfma_f32_16x16x32_bf16 v[14:17], v[236:239], v[208:211], v[14:17]
	s_waitcnt lgkmcnt(0)
	v_mfma_f32_16x16x32_bf16 v[18:21], v[224:227], v[212:215], v[18:21]
	v_mfma_f32_16x16x32_bf16 v[22:25], v[228:231], v[212:215], v[22:25]
	v_mfma_f32_16x16x32_bf16 v[26:29], v[232:235], v[212:215], v[26:29]
	v_mfma_f32_16x16x32_bf16 v[30:33], v[236:239], v[212:215], v[30:33]
	v_mfma_f32_16x16x32_bf16 v[34:37], v[224:227], v[216:219], v[34:37]
	v_mfma_f32_16x16x32_bf16 v[38:41], v[228:231], v[216:219], v[38:41]
	v_mfma_f32_16x16x32_bf16 v[42:45], v[232:235], v[216:219], v[42:45]
	v_mfma_f32_16x16x32_bf16 v[46:49], v[236:239], v[216:219], v[46:49]
	v_mfma_f32_16x16x32_bf16 v[50:53], v[224:227], v[220:223], v[50:53]
	v_mfma_f32_16x16x32_bf16 v[54:57], v[228:231], v[220:223], v[54:57]
	v_mfma_f32_16x16x32_bf16 v[58:61], v[232:235], v[220:223], v[58:61]
	v_mfma_f32_16x16x32_bf16 v[62:65], v[236:239], v[220:223], v[62:65]
	s_mov_b64 s[28:29], s[48:49]
	s_mov_b64 s[30:31], s[50:51]
	ds_read_b32 v162, v250 offset:0
	ds_read_b32 v163, v250 offset:64
	ds_read_b32 v164, v250 offset:128
	ds_read_b32 v165, v250 offset:192
	s_waitcnt lgkmcnt(0)
	v_mul_f32_e32 v162, 0xbfb8aa3b, v162
	v_mul_f32_e32 v163, 0xbfb8aa3b, v163
	v_mul_f32_e32 v164, 0xbfb8aa3b, v164
	v_mul_f32_e32 v165, 0xbfb8aa3b, v165
	v_mul_f32_e32 v166, v162, v2
	v_mul_f32_e32 v167, v162, v3
	v_mul_f32_e32 v168, v162, v4
	v_mul_f32_e32 v169, v162, v5
	v_exp_f32_e32 v166, v166
	v_exp_f32_e32 v167, v167
	v_exp_f32_e32 v168, v168
	v_exp_f32_e32 v169, v169
	v_add_f32_e32 v166, 1.0, v166
	v_add_f32_e32 v167, 1.0, v167
	v_add_f32_e32 v168, 1.0, v168
	v_add_f32_e32 v169, 1.0, v169
	v_rcp_f32_e32 v166, v166
	v_rcp_f32_e32 v167, v167
	v_rcp_f32_e32 v168, v168
	v_rcp_f32_e32 v169, v169
	v_cvt_pk_bf16_f32 v130, v166, v167
	v_cvt_pk_bf16_f32 v131, v168, v169
	v_mul_f32_e32 v166, v162, v6
	v_mul_f32_e32 v167, v162, v7
	v_mul_f32_e32 v168, v162, v8
	v_mul_f32_e32 v169, v162, v9
	v_exp_f32_e32 v166, v166
	v_exp_f32_e32 v167, v167
	v_exp_f32_e32 v168, v168
	v_exp_f32_e32 v169, v169
	v_add_f32_e32 v166, 1.0, v166
	v_add_f32_e32 v167, 1.0, v167
	v_add_f32_e32 v168, 1.0, v168
	v_add_f32_e32 v169, 1.0, v169
	v_rcp_f32_e32 v166, v166
	v_rcp_f32_e32 v167, v167
	v_rcp_f32_e32 v168, v168
	v_rcp_f32_e32 v169, v169
	v_cvt_pk_bf16_f32 v132, v166, v167
	v_cvt_pk_bf16_f32 v133, v168, v169
	v_mul_f32_e32 v166, v162, v10
	v_mul_f32_e32 v167, v162, v11
	v_mul_f32_e32 v168, v162, v12
	v_mul_f32_e32 v169, v162, v13
	v_exp_f32_e32 v166, v166
	v_exp_f32_e32 v167, v167
	v_exp_f32_e32 v168, v168
	v_exp_f32_e32 v169, v169
	v_add_f32_e32 v166, 1.0, v166
	v_add_f32_e32 v167, 1.0, v167
	v_add_f32_e32 v168, 1.0, v168
	v_add_f32_e32 v169, 1.0, v169
	v_rcp_f32_e32 v166, v166
	v_rcp_f32_e32 v167, v167
	v_rcp_f32_e32 v168, v168
	v_rcp_f32_e32 v169, v169
	v_cvt_pk_bf16_f32 v134, v166, v167
	v_cvt_pk_bf16_f32 v135, v168, v169
	v_mul_f32_e32 v166, v162, v14
	v_mul_f32_e32 v167, v162, v15
	v_mul_f32_e32 v168, v162, v16
	v_mul_f32_e32 v169, v162, v17
	v_exp_f32_e32 v166, v166
	v_exp_f32_e32 v167, v167
	v_exp_f32_e32 v168, v168
	v_exp_f32_e32 v169, v169
	v_add_f32_e32 v166, 1.0, v166
	v_add_f32_e32 v167, 1.0, v167
	v_add_f32_e32 v168, 1.0, v168
	v_add_f32_e32 v169, 1.0, v169
	v_rcp_f32_e32 v166, v166
	v_rcp_f32_e32 v167, v167
	v_rcp_f32_e32 v168, v168
	v_rcp_f32_e32 v169, v169
	v_cvt_pk_bf16_f32 v136, v166, v167
	v_cvt_pk_bf16_f32 v137, v168, v169
	v_mul_f32_e32 v166, v163, v18
	v_mul_f32_e32 v167, v163, v19
	v_mul_f32_e32 v168, v163, v20
	v_mul_f32_e32 v169, v163, v21
	v_exp_f32_e32 v166, v166
; DI unsigned pk2(float a, float b) { f2_t v = {a, b}; bf2_t r = __builtin_convertvector(v, bf2_t); return __builtin_bit_cast(unsigned, r); }
; DI void tile_branch(const Params& p, int l, int tile, char* smem) {
;     ...
; #pragma unroll
;       for (int mt = 0; mt < 2; ++mt)
; #pragma unroll
;         for (int g4 = 0; g4 < 4; ++g4) {
;           const f32x4 r4 = *(const f32x4*)&rinv_s[wm * 64 + mt * 32 + 8 * g4 + 4 * hi];
; #pragma unroll
;           for (int nt = 0; nt < 2; ++nt) {
;             const float s0 = 1.f / (1.f + __expf(-accg[mt][nt][4 * g4 + 0] * r4[0])), s1 = 1.f / (1.f + __expf(-accg[mt][nt][4 * g4 + 1] * r4[1]));
;             const float s2 = 1.f / (1.f + __expf(-accg[mt][nt][4 * g4 + 2] * r4[2])), s3 = 1.f / (1.f + __expf(-accg[mt][nt][4 * g4 + 3] * r4[3]));
;             gpk[mt][nt][2 * g4] = pk2(s0, s1); gpk[mt][nt][2 * g4 + 1] = pk2(s2, s3);
;           }
;         }
	v_exp_f32_e32 v167, v167
	v_exp_f32_e32 v168, v168
	v_exp_f32_e32 v169, v169
	v_add_f32_e32 v166, 1.0, v166
	v_add_f32_e32 v167, 1.0, v167
	v_add_f32_e32 v168, 1.0, v168
	v_add_f32_e32 v169, 1.0, v169
	v_rcp_f32_e32 v166, v166
	v_rcp_f32_e32 v167, v167
	v_rcp_f32_e32 v168, v168
	v_rcp_f32_e32 v169, v169
	v_cvt_pk_bf16_f32 v138, v166, v167
	v_cvt_pk_bf16_f32 v139, v168, v169
	v_mul_f32_e32 v166, v163, v22
	v_mul_f32_e32 v167, v163, v23
	v_mul_f32_e32 v168, v163, v24
	v_mul_f32_e32 v169, v163, v25
	v_exp_f32_e32 v166, v166
	v_exp_f32_e32 v167, v167
	v_exp_f32_e32 v168, v168
	v_exp_f32_e32 v169, v169
	v_add_f32_e32 v166, 1.0, v166
	v_add_f32_e32 v167, 1.0, v167
	v_add_f32_e32 v168, 1.0, v168
	v_add_f32_e32 v169, 1.0, v169
	v_rcp_f32_e32 v166, v166
	v_rcp_f32_e32 v167, v167
	v_rcp_f32_e32 v168, v168
	v_rcp_f32_e32 v169, v169
	v_cvt_pk_bf16_f32 v140, v166, v167
	v_cvt_pk_bf16_f32 v141, v168, v169
	v_mul_f32_e32 v166, v163, v26
	v_mul_f32_e32 v167, v163, v27
	v_mul_f32_e32 v168, v163, v28
	v_mul_f32_e32 v169, v163, v29
	v_exp_f32_e32 v166, v166
	v_exp_f32_e32 v167, v167
	v_exp_f32_e32 v168, v168
	v_exp_f32_e32 v169, v169
	v_add_f32_e32 v166, 1.0, v166
	v_add_f32_e32 v167, 1.0, v167
	v_add_f32_e32 v168, 1.0, v168
	v_add_f32_e32 v169, 1.0, v169
	v_rcp_f32_e32 v166, v166
	v_rcp_f32_e32 v167, v167
	v_rcp_f32_e32 v168, v168
	v_rcp_f32_e32 v169, v169
	v_cvt_pk_bf16_f32 v142, v166, v167
	v_cvt_pk_bf16_f32 v143, v168, v169
	v_mul_f32_e32 v166, v163, v30
	v_mul_f32_e32 v167, v163, v31
	v_mul_f32_e32 v168, v163, v32
	v_mul_f32_e32 v169, v163, v33
	v_exp_f32_e32 v166, v166
	v_exp_f32_e32 v167, v167
	v_exp_f32_e32 v168, v168
	v_exp_f32_e32 v169, v169
	v_add_f32_e32 v166, 1.0, v166
	v_add_f32_e32 v167, 1.0, v167
	v_add_f32_e32 v168, 1.0, v168
	v_add_f32_e32 v169, 1.0, v169
	v_rcp_f32_e32 v166, v166
	v_rcp_f32_e32 v167, v167
	v_rcp_f32_e32 v168, v168
	v_rcp_f32_e32 v169, v169
	v_cvt_pk_bf16_f32 v144, v166, v167
	v_cvt_pk_bf16_f32 v145, v168, v169
	v_mul_f32_e32 v166, v164, v34
	v_mul_f32_e32 v167, v164, v35
	v_mul_f32_e32 v168, v164, v36
	v_mul_f32_e32 v169, v164, v37
	v_exp_f32_e32 v166, v166
	v_exp_f32_e32 v167, v167
	v_exp_f32_e32 v168, v168
	v_exp_f32_e32 v169, v169
	v_add_f32_e32 v166, 1.0, v166
	v_add_f32_e32 v167, 1.0, v167
	v_add_f32_e32 v168, 1.0, v168
	v_add_f32_e32 v169, 1.0, v169
	v_rcp_f32_e32 v166, v166
	v_rcp_f32_e32 v167, v167
	v_rcp_f32_e32 v168, v168
	v_rcp_f32_e32 v169, v169
	v_cvt_pk_bf16_f32 v146, v166, v167
	v_cvt_pk_bf16_f32 v147, v168, v169
	v_mul_f32_e32 v166, v164, v38
	v_mul_f32_e32 v167, v164, v39
	v_mul_f32_e32 v168, v164, v40
	v_mul_f32_e32 v169, v164, v41
	v_exp_f32_e32 v166, v166
	v_exp_f32_e32 v167, v167
	v_exp_f32_e32 v168, v168
	v_exp_f32_e32 v169, v169
	v_add_f32_e32 v166, 1.0, v166
	v_add_f32_e32 v167, 1.0, v167
	v_add_f32_e32 v168, 1.0, v168
	v_add_f32_e32 v169, 1.0, v169
	v_rcp_f32_e32 v166, v166
	v_rcp_f32_e32 v167, v167
	v_rcp_f32_e32 v168, v168
	v_rcp_f32_e32 v169, v169
	v_cvt_pk_bf16_f32 v148, v166, v167
	v_cvt_pk_bf16_f32 v149, v168, v169
	v_mul_f32_e32 v166, v164, v42
	v_mul_f32_e32 v167, v164, v43
	v_mul_f32_e32 v168, v164, v44
	v_mul_f32_e32 v169, v164, v45
	v_exp_f32_e32 v166, v166
	v_exp_f32_e32 v167, v167
	v_exp_f32_e32 v168, v168
	v_exp_f32_e32 v169, v169
	v_add_f32_e32 v166, 1.0, v166
	v_add_f32_e32 v167, 1.0, v167
	v_add_f32_e32 v168, 1.0, v168
	v_add_f32_e32 v169, 1.0, v169
	v_rcp_f32_e32 v166, v166
	v_rcp_f32_e32 v167, v167
	v_rcp_f32_e32 v168, v168
	v_rcp_f32_e32 v169, v169
	v_cvt_pk_bf16_f32 v150, v166, v167
	v_cvt_pk_bf16_f32 v151, v168, v169
	v_mul_f32_e32 v166, v164, v46
	v_mul_f32_e32 v167, v164, v47
	v_mul_f32_e32 v168, v164, v48
	v_mul_f32_e32 v169, v164, v49
	v_exp_f32_e32 v166, v166
	v_exp_f32_e32 v167, v167
	v_exp_f32_e32 v168, v168
	v_exp_f32_e32 v169, v169
	v_add_f32_e32 v166, 1.0, v166
	v_add_f32_e32 v167, 1.0, v167
	v_add_f32_e32 v168, 1.0, v168
	v_add_f32_e32 v169, 1.0, v169
	v_rcp_f32_e32 v166, v166
	v_rcp_f32_e32 v167, v167
	v_rcp_f32_e32 v168, v168
	v_rcp_f32_e32 v169, v169
	v_cvt_pk_bf16_f32 v152, v166, v167
	v_cvt_pk_bf16_f32 v153, v168, v169
	v_mul_f32_e32 v166, v165, v50
	v_mul_f32_e32 v167, v165, v51
	v_mul_f32_e32 v168, v165, v52
	v_mul_f32_e32 v169, v165, v53
	v_exp_f32_e32 v166, v166
	v_exp_f32_e32 v167, v167
	v_exp_f32_e32 v168, v168
	v_exp_f32_e32 v169, v169
	v_add_f32_e32 v166, 1.0, v166
	v_add_f32_e32 v167, 1.0, v167
	v_add_f32_e32 v168, 1.0, v168
	v_add_f32_e32 v169, 1.0, v169
	v_rcp_f32_e32 v166, v166
	v_rcp_f32_e32 v167, v167
	v_rcp_f32_e32 v168, v168
	v_rcp_f32_e32 v169, v169
	v_cvt_pk_bf16_f32 v154, v166, v167
	v_cvt_pk_bf16_f32 v155, v168, v169
	v_mul_f32_e32 v166, v165, v54
	v_mul_f32_e32 v167, v165, v55
	v_mul_f32_e32 v168, v165, v56
	v_mul_f32_e32 v169, v165, v57
	v_exp_f32_e32 v166, v166
	v_exp_f32_e32 v167, v167
	v_exp_f32_e32 v168, v168
	v_exp_f32_e32 v169, v169
	v_add_f32_e32 v166, 1.0, v166
	v_add_f32_e32 v167, 1.0, v167
	v_add_f32_e32 v168, 1.0, v168
	v_add_f32_e32 v169, 1.0, v169
	v_rcp_f32_e32 v166, v166
	v_rcp_f32_e32 v167, v167
	v_rcp_f32_e32 v168, v168
	v_rcp_f32_e32 v169, v169
	v_cvt_pk_bf16_f32 v156, v166, v167
	v_cvt_pk_bf16_f32 v157, v168, v169
	v_mul_f32_e32 v166, v165, v58
	v_mul_f32_e32 v167, v165, v59
	v_mul_f32_e32 v168, v165, v60
	v_mul_f32_e32 v169, v165, v61
	v_exp_f32_e32 v166, v166
	v_exp_f32_e32 v167, v167
	v_exp_f32_e32 v168, v168
	v_exp_f32_e32 v169, v169
	v_add_f32_e32 v166, 1.0, v166
	v_add_f32_e32 v167, 1.0, v167
	v_add_f32_e32 v168, 1.0, v168
	v_add_f32_e32 v169, 1.0, v169
	v_rcp_f32_e32 v166, v166
	v_rcp_f32_e32 v167, v167
	v_rcp_f32_e32 v168, v168
	v_rcp_f32_e32 v169, v169
	v_cvt_pk_bf16_f32 v158, v166, v167
; DI unsigned pk2(float a, float b) { f2_t v = {a, b}; bf2_t r = __builtin_convertvector(v, bf2_t); return __builtin_bit_cast(unsigned, r); }
; #define BLOAD(A_, B_, kt) do { _Pragma("unroll") for (int i = 0; i < 4; ++i) { \
;     A_[i] = *(const u32x4*)((const char*)Ap + (aoff + (unsigned)(32 * i * lda + (kt) * 64) * 2u)); B_[i] = *(const u32x4*)((const char*)Wt + (woff + (unsigned)(32 * i * K + (kt) * 64) * 2u)); } } while (0)
; #define BLOAD(A_, B_, kt) do { _Pragma("unroll") for (int i = 0; i < 4; ++i) { \
;     A_[i] = *(const u32x4*)((const char*)Ap + (aoff + (unsigned)(32 * i * lda + (kt) * 64) * 2u)); B_[i] = *(const u32x4*)((const char*)Wt + (woff + (unsigned)(32 * i * K + (kt) * 64) * 2u)); } } while (0)
; #define BSTORE(A_, B_, buf) do { _Pragma("unroll") for (int i = 0; i < 4; ++i) { \
;     *(u32x4*)&As[(buf) * GBUF + (srow + 32 * i) * LDT + sc8] = A_[i]; \
;     *(u32x4*)&Bs[(buf) * GBUF + (srow + 32 * i) * LDT + sc8] = B_[i]; } } while (0)
; template <bool ROWNORM, int NK>
; DI void gemm_main_bf(const u16* __restrict__ Ap, int lda, const u16* __restrict__ Wt, f32x16 (&acc)[2][2], char* smem, float* rinv_s) {
;     ...
;   __builtin_amdgcn_s_setprio(0);
;   BLOAD(a0, b0, 0); BLOAD(a1, b1, 1);
;   __syncthreads();
;   BSTORE(a0, b0, 0);
;   BLOAD(a0, b0, 2);
;   __syncthreads();
; #pragma unroll
;   for (int kt = 0; kt < nk; kt += 2) {
;     BCOMP(0);
;     BSTORE(a1, b1, 1);
;     if (kt + 3 < nk) BLOAD(a1, b1, kt + 3);
;     __syncthreads();
;     BCOMP(1);
;     if (kt + 2 < nk) { BSTORE(a0, b0, 0); if (kt + 4 < nk) BLOAD(a0, b0, kt + 4); }
;     __syncthreads();
; DI void tile_branch(const Params& p, int l, int tile, char* smem) {
;     ...
;             gpk[mt][nt][2 * g4] = pk2(s0, s1); gpk[mt][nt][2 * g4 + 1] = pk2(s2, s3);
;           }
;         }
;     }
;     f32x16 acc[2][2]; zero_acc(acc);
;     gemm_main_bf<false, 8>((const u16*)(p.ws + OFF_BR) + (size_t)(br * CT + m0) * 512, 512,
	v_cvt_pk_bf16_f32 v159, v168, v169
	v_mul_f32_e32 v166, v165, v62
	v_mul_f32_e32 v167, v165, v63
	v_mul_f32_e32 v168, v165, v64
	v_mul_f32_e32 v169, v165, v65
	v_exp_f32_e32 v166, v166
	v_exp_f32_e32 v167, v167
	v_exp_f32_e32 v168, v168
	v_exp_f32_e32 v169, v169
	v_add_f32_e32 v166, 1.0, v166
	v_add_f32_e32 v167, 1.0, v167
	v_add_f32_e32 v168, 1.0, v168
	v_add_f32_e32 v169, 1.0, v169
	v_rcp_f32_e32 v166, v166
	v_rcp_f32_e32 v167, v167
	v_rcp_f32_e32 v168, v168
	v_rcp_f32_e32 v169, v169
	v_cvt_pk_bf16_f32 v160, v166, v167
	v_cvt_pk_bf16_f32 v161, v168, v169
	s_add_u32 m0, s52, 0x0
	s_nop 0
	global_load_lds_dwordx4 v244, s[28:29]
	global_load_lds_dwordx4 v245, s[28:29] offset:1024
	s_add_u32 m0, s53, 0x0
	s_nop 0
	global_load_lds_dwordx4 v251, s[30:31]
	global_load_lds_dwordx4 v251, s[30:31] offset:1024
	s_add_u32 m0, s52, 0x4000
	s_add_u32 s28, s28, 0x40
	s_addc_u32 s29, s29, 0
	global_load_lds_dwordx4 v244, s[28:29]
	global_load_lds_dwordx4 v245, s[28:29] offset:1024
	s_add_u32 m0, s53, 0x4000
	s_add_u32 s30, s30, 0x10000
	s_addc_u32 s31, s31, 0
	global_load_lds_dwordx4 v251, s[30:31]
	global_load_lds_dwordx4 v251, s[30:31] offset:1024
	s_add_u32 m0, s52, 0x8000
	s_add_u32 s28, s28, 0x40
	s_addc_u32 s29, s29, 0
	global_load_lds_dwordx4 v244, s[28:29]
	global_load_lds_dwordx4 v245, s[28:29] offset:1024
	s_add_u32 m0, s53, 0x8000
	s_add_u32 s30, s30, 0x10000
	s_addc_u32 s31, s31, 0
	global_load_lds_dwordx4 v251, s[30:31]
	global_load_lds_dwordx4 v251, s[30:31] offset:1024
	v_mov_b32_e32 v2, 0
	v_mov_b32_e32 v3, 0
	v_mov_b32_e32 v4, 0
	v_mov_b32_e32 v5, 0
	v_mov_b32_e32 v6, 0
	v_mov_b32_e32 v7, 0
	v_mov_b32_e32 v8, 0
	v_mov_b32_e32 v9, 0
	v_mov_b32_e32 v10, 0
	v_mov_b32_e32 v11, 0
	v_mov_b32_e32 v12, 0
	v_mov_b32_e32 v13, 0
	v_mov_b32_e32 v14, 0
	v_mov_b32_e32 v15, 0
	v_mov_b32_e32 v16, 0
	v_mov_b32_e32 v17, 0
	v_mov_b32_e32 v18, 0
	v_mov_b32_e32 v19, 0
	v_mov_b32_e32 v20, 0
	v_mov_b32_e32 v21, 0
	v_mov_b32_e32 v22, 0
	v_mov_b32_e32 v23, 0
	v_mov_b32_e32 v24, 0
	v_mov_b32_e32 v25, 0
	v_mov_b32_e32 v26, 0
	v_mov_b32_e32 v27, 0
	v_mov_b32_e32 v28, 0
	v_mov_b32_e32 v29, 0
	v_mov_b32_e32 v30, 0
	v_mov_b32_e32 v31, 0
	v_mov_b32_e32 v32, 0
	v_mov_b32_e32 v33, 0
	v_mov_b32_e32 v34, 0
	v_mov_b32_e32 v35, 0
	v_mov_b32_e32 v36, 0
	v_mov_b32_e32 v37, 0
	v_mov_b32_e32 v38, 0
	v_mov_b32_e32 v39, 0
	v_mov_b32_e32 v40, 0
	v_mov_b32_e32 v41, 0
	v_mov_b32_e32 v42, 0
	v_mov_b32_e32 v43, 0
	v_mov_b32_e32 v44, 0
	v_mov_b32_e32 v45, 0
	v_mov_b32_e32 v46, 0
	v_mov_b32_e32 v47, 0
	v_mov_b32_e32 v48, 0
	v_mov_b32_e32 v49, 0
	v_mov_b32_e32 v50, 0
	v_mov_b32_e32 v51, 0
	v_mov_b32_e32 v52, 0
	v_mov_b32_e32 v53, 0
	v_mov_b32_e32 v54, 0
	v_mov_b32_e32 v55, 0
	v_mov_b32_e32 v56, 0
	v_mov_b32_e32 v57, 0
	v_mov_b32_e32 v58, 0
	v_mov_b32_e32 v59, 0
	v_mov_b32_e32 v60, 0
	v_mov_b32_e32 v61, 0
	v_mov_b32_e32 v62, 0
	v_mov_b32_e32 v63, 0
	v_mov_b32_e32 v64, 0
	v_mov_b32_e32 v65, 0
	s_mov_b32 s74, 3
.Lbr_proj_k:
	s_waitcnt vmcnt(8)
	s_barrier
	ds_read_b128 v[208:211], v240 offset:0
	ds_read_b128 v[224:227], v241 offset:0
	ds_read_b128 v[228:231], v241 offset:1024
	ds_read_b128 v[232:235], v241 offset:2048
	ds_read_b128 v[236:239], v241 offset:3072
	s_add_u32 m0, s52, 0xc000
	s_add_u32 s28, s28, 0x40
	s_addc_u32 s29, s29, 0
	global_load_lds_dwordx4 v244, s[28:29]
	global_load_lds_dwordx4 v245, s[28:29] offset:1024
	s_add_u32 m0, s53, 0xc000
	s_add_u32 s30, s30, 0x10000
	s_addc_u32 s31, s31, 0
	global_load_lds_dwordx4 v251, s[30:31]
	global_load_lds_dwordx4 v251, s[30:31] offset:1024
	ds_read_b128 v[212:215], v240 offset:1024
	ds_read_b128 v[216:219], v240 offset:2048
	ds_read_b128 v[220:223], v240 offset:3072
	s_waitcnt lgkmcnt(3)
	v_mfma_f32_16x16x32_bf16 v[2:5], v[224:227], v[208:211], v[2:5]
	v_mfma_f32_16x16x32_bf16 v[6:9], v[228:231], v[208:211], v[6:9]
	v_mfma_f32_16x16x32_bf16 v[10:13], v[232:235], v[208:211], v[10:13]
	v_mfma_f32_16x16x32_bf16 v[14:17], v[236:239], v[208:211], v[14:17]
	s_waitcnt lgkmcnt(0)
	v_mfma_f32_16x16x32_bf16 v[18:21], v[224:227], v[212:215], v[18:21]
	v_mfma_f32_16x16x32_bf16 v[22:25], v[228:231], v[212:215], v[22:25]
	v_mfma_f32_16x16x32_bf16 v[26:29], v[232:235], v[212:215], v[26:29]
	v_mfma_f32_16x16x32_bf16 v[30:33], v[236:239], v[212:215], v[30:33]
	v_mfma_f32_16x16x32_bf16 v[34:37], v[224:227], v[216:219], v[34:37]
	v_mfma_f32_16x16x32_bf16 v[38:41], v[228:231], v[216:219], v[38:41]
	v_mfma_f32_16x16x32_bf16 v[42:45], v[232:235], v[216:219], v[42:45]
	v_mfma_f32_16x16x32_bf16 v[46:49], v[236:239], v[216:219], v[46:49]
	v_mfma_f32_16x16x32_bf16 v[50:53], v[224:227], v[220:223], v[50:53]
	v_mfma_f32_16x16x32_bf16 v[54:57], v[228:231], v[220:223], v[54:57]
	v_mfma_f32_16x16x32_bf16 v[58:61], v[232:235], v[220:223], v[58:61]
	v_mfma_f32_16x16x32_bf16 v[62:65], v[236:239], v[220:223], v[62:65]
	s_waitcnt vmcnt(8)
	s_barrier
; #define BLOAD(A_, B_, kt) do { _Pragma("unroll") for (int i = 0; i < 4; ++i) { \
;     A_[i] = *(const u32x4*)((const char*)Ap + (aoff + (unsigned)(32 * i * lda + (kt) * 64) * 2u)); B_[i] = *(const u32x4*)((const char*)Wt + (woff + (unsigned)(32 * i * K + (kt) * 64) * 2u)); } } while (0)
; #define BLOAD(A_, B_, kt) do { _Pragma("unroll") for (int i = 0; i < 4; ++i) { \
;     A_[i] = *(const u32x4*)((const char*)Ap + (aoff + (unsigned)(32 * i * lda + (kt) * 64) * 2u)); B_[i] = *(const u32x4*)((const char*)Wt + (woff + (unsigned)(32 * i * K + (kt) * 64) * 2u)); } } while (0)
; #define BSTORE(A_, B_, buf) do { _Pragma("unroll") for (int i = 0; i < 4; ++i) { \
;     *(u32x4*)&As[(buf) * GBUF + (srow + 32 * i) * LDT + sc8] = A_[i]; \
;     *(u32x4*)&Bs[(buf) * GBUF + (srow + 32 * i) * LDT + sc8] = B_[i]; } } while (0)
; template <bool ROWNORM, int NK>
; DI void gemm_main_bf(const u16* __restrict__ Ap, int lda, const u16* __restrict__ Wt, f32x16 (&acc)[2][2], char* smem, float* rinv_s) {
;     ...
;   __builtin_amdgcn_s_setprio(0);
;   BLOAD(a0, b0, 0); BLOAD(a1, b1, 1);
;   __syncthreads();
;   BSTORE(a0, b0, 0);
;   BLOAD(a0, b0, 2);
;   __syncthreads();
; #pragma unroll
;   for (int kt = 0; kt < nk; kt += 2) {
;     BCOMP(0);
;     BSTORE(a1, b1, 1);
;     if (kt + 3 < nk) BLOAD(a1, b1, kt + 3);
;     __syncthreads();
;     BCOMP(1);
;     if (kt + 2 < nk) { BSTORE(a0, b0, 0); if (kt + 4 < nk) BLOAD(a0, b0, kt + 4); }
;     __syncthreads();
	ds_read_b128 v[208:211], v240 offset:16384
	ds_read_b128 v[224:227], v241 offset:16384
	ds_read_b128 v[228:231], v241 offset:17408
	ds_read_b128 v[232:235], v241 offset:18432
	ds_read_b128 v[236:239], v241 offset:19456
	s_add_u32 m0, s52, 0x0
	s_add_u32 s28, s28, 0x40
	s_addc_u32 s29, s29, 0
	global_load_lds_dwordx4 v244, s[28:29]
	global_load_lds_dwordx4 v245, s[28:29] offset:1024
	s_add_u32 m0, s53, 0x0
	s_add_u32 s30, s30, 0x10000
	s_addc_u32 s31, s31, 0
	global_load_lds_dwordx4 v251, s[30:31]
	global_load_lds_dwordx4 v251, s[30:31] offset:1024
	ds_read_b128 v[212:215], v240 offset:17408
	ds_read_b128 v[216:219], v240 offset:18432
	ds_read_b128 v[220:223], v240 offset:19456
	s_waitcnt lgkmcnt(3)
	v_mfma_f32_16x16x32_bf16 v[2:5], v[224:227], v[208:211], v[2:5]
	v_mfma_f32_16x16x32_bf16 v[6:9], v[228:231], v[208:211], v[6:9]
	v_mfma_f32_16x16x32_bf16 v[10:13], v[232:235], v[208:211], v[10:13]
	v_mfma_f32_16x16x32_bf16 v[14:17], v[236:239], v[208:211], v[14:17]
	s_waitcnt lgkmcnt(0)
	v_mfma_f32_16x16x32_bf16 v[18:21], v[224:227], v[212:215], v[18:21]
	v_mfma_f32_16x16x32_bf16 v[22:25], v[228:231], v[212:215], v[22:25]
	v_mfma_f32_16x16x32_bf16 v[26:29], v[232:235], v[212:215], v[26:29]
	v_mfma_f32_16x16x32_bf16 v[30:33], v[236:239], v[212:215], v[30:33]
	v_mfma_f32_16x16x32_bf16 v[34:37], v[224:227], v[216:219], v[34:37]
	v_mfma_f32_16x16x32_bf16 v[38:41], v[228:231], v[216:219], v[38:41]
	v_mfma_f32_16x16x32_bf16 v[42:45], v[232:235], v[216:219], v[42:45]
	v_mfma_f32_16x16x32_bf16 v[46:49], v[236:239], v[216:219], v[46:49]
	v_mfma_f32_16x16x32_bf16 v[50:53], v[224:227], v[220:223], v[50:53]
	v_mfma_f32_16x16x32_bf16 v[54:57], v[228:231], v[220:223], v[54:57]
	v_mfma_f32_16x16x32_bf16 v[58:61], v[232:235], v[220:223], v[58:61]
	v_mfma_f32_16x16x32_bf16 v[62:65], v[236:239], v[220:223], v[62:65]
	s_waitcnt vmcnt(8)
	s_barrier
	ds_read_b128 v[208:211], v240 offset:32768
	ds_read_b128 v[224:227], v241 offset:32768
	ds_read_b128 v[228:231], v241 offset:33792
	ds_read_b128 v[232:235], v241 offset:34816
	ds_read_b128 v[236:239], v241 offset:35840
	s_add_u32 m0, s52, 0x4000
	s_add_u32 s28, s28, 0x40
	s_addc_u32 s29, s29, 0
	global_load_lds_dwordx4 v244, s[28:29]
	global_load_lds_dwordx4 v245, s[28:29] offset:1024
	s_add_u32 m0, s53, 0x4000
	s_add_u32 s30, s30, 0x10000
	s_addc_u32 s31, s31, 0
	global_load_lds_dwordx4 v251, s[30:31]
	global_load_lds_dwordx4 v251, s[30:31] offset:1024
	ds_read_b128 v[212:215], v240 offset:33792
	ds_read_b128 v[216:219], v240 offset:34816
	ds_read_b128 v[220:223], v240 offset:35840
	s_waitcnt lgkmcnt(3)
	v_mfma_f32_16x16x32_bf16 v[2:5], v[224:227], v[208:211], v[2:5]
	v_mfma_f32_16x16x32_bf16 v[6:9], v[228:231], v[208:211], v[6:9]
	v_mfma_f32_16x16x32_bf16 v[10:13], v[232:235], v[208:211], v[10:13]
	v_mfma_f32_16x16x32_bf16 v[14:17], v[236:239], v[208:211], v[14:17]
	s_waitcnt lgkmcnt(0)
	v_mfma_f32_16x16x32_bf16 v[18:21], v[224:227], v[212:215], v[18:21]
	v_mfma_f32_16x16x32_bf16 v[22:25], v[228:231], v[212:215], v[22:25]
	v_mfma_f32_16x16x32_bf16 v[26:29], v[232:235], v[212:215], v[26:29]
	v_mfma_f32_16x16x32_bf16 v[30:33], v[236:239], v[212:215], v[30:33]
	v_mfma_f32_16x16x32_bf16 v[34:37], v[224:227], v[216:219], v[34:37]
	v_mfma_f32_16x16x32_bf16 v[38:41], v[228:231], v[216:219], v[38:41]
	v_mfma_f32_16x16x32_bf16 v[42:45], v[232:235], v[216:219], v[42:45]
	v_mfma_f32_16x16x32_bf16 v[46:49], v[236:239], v[216:219], v[46:49]
	v_mfma_f32_16x16x32_bf16 v[50:53], v[224:227], v[220:223], v[50:53]
	v_mfma_f32_16x16x32_bf16 v[54:57], v[228:231], v[220:223], v[54:57]
	v_mfma_f32_16x16x32_bf16 v[58:61], v[232:235], v[220:223], v[58:61]
	v_mfma_f32_16x16x32_bf16 v[62:65], v[236:239], v[220:223], v[62:65]
	s_waitcnt vmcnt(8)
	s_barrier
	ds_read_b128 v[208:211], v240 offset:49152
	ds_read_b128 v[224:227], v241 offset:49152
	ds_read_b128 v[228:231], v241 offset:50176
	ds_read_b128 v[232:235], v241 offset:51200
	ds_read_b128 v[236:239], v241 offset:52224
	s_add_u32 m0, s52, 0x8000
	s_add_u32 s28, s28, 0x40
	s_addc_u32 s29, s29, 0
	global_load_lds_dwordx4 v244, s[28:29]
	global_load_lds_dwordx4 v245, s[28:29] offset:1024
	s_add_u32 m0, s53, 0x8000
	s_add_u32 s30, s30, 0x10000
	s_addc_u32 s31, s31, 0
	global_load_lds_dwordx4 v251, s[30:31]
	global_load_lds_dwordx4 v251, s[30:31] offset:1024
	ds_read_b128 v[212:215], v240 offset:50176
	ds_read_b128 v[216:219], v240 offset:51200
	ds_read_b128 v[220:223], v240 offset:52224
	s_waitcnt lgkmcnt(3)
	v_mfma_f32_16x16x32_bf16 v[2:5], v[224:227], v[208:211], v[2:5]
	v_mfma_f32_16x16x32_bf16 v[6:9], v[228:231], v[208:211], v[6:9]
	v_mfma_f32_16x16x32_bf16 v[10:13], v[232:235], v[208:211], v[10:13]
	v_mfma_f32_16x16x32_bf16 v[14:17], v[236:239], v[208:211], v[14:17]
	s_waitcnt lgkmcnt(0)
	v_mfma_f32_16x16x32_bf16 v[18:21], v[224:227], v[212:215], v[18:21]
	v_mfma_f32_16x16x32_bf16 v[22:25], v[228:231], v[212:215], v[22:25]
	v_mfma_f32_16x16x32_bf16 v[26:29], v[232:235], v[212:215], v[26:29]
	v_mfma_f32_16x16x32_bf16 v[30:33], v[236:239], v[212:215], v[30:33]
	v_mfma_f32_16x16x32_bf16 v[34:37], v[224:227], v[216:219], v[34:37]
	v_mfma_f32_16x16x32_bf16 v[38:41], v[228:231], v[216:219], v[38:41]
	v_mfma_f32_16x16x32_bf16 v[42:45], v[232:235], v[216:219], v[42:45]
	v_mfma_f32_16x16x32_bf16 v[46:49], v[236:239], v[216:219], v[46:49]
	v_mfma_f32_16x16x32_bf16 v[50:53], v[224:227], v[220:223], v[50:53]
	v_mfma_f32_16x16x32_bf16 v[54:57], v[228:231], v[220:223], v[54:57]
	v_mfma_f32_16x16x32_bf16 v[58:61], v[232:235], v[220:223], v[58:61]
	v_mfma_f32_16x16x32_bf16 v[62:65], v[236:239], v[220:223], v[62:65]
	s_sub_u32 s74, s74, 1
	s_cmp_lg_u32 s74, 0
	s_cbranch_scc1 .Lbr_proj_k
; #define BLOAD(A_, B_, kt) do { _Pragma("unroll") for (int i = 0; i < 4; ++i) { \
;     A_[i] = *(const u32x4*)((const char*)Ap + (aoff + (unsigned)(32 * i * lda + (kt) * 64) * 2u)); B_[i] = *(const u32x4*)((const char*)Wt + (woff + (unsigned)(32 * i * K + (kt) * 64) * 2u)); } } while (0)
; #define BLOAD(A_, B_, kt) do { _Pragma("unroll") for (int i = 0; i < 4; ++i) { \
;     A_[i] = *(const u32x4*)((const char*)Ap + (aoff + (unsigned)(32 * i * lda + (kt) * 64) * 2u)); B_[i] = *(const u32x4*)((const char*)Wt + (woff + (unsigned)(32 * i * K + (kt) * 64) * 2u)); } } while (0)
; #define BSTORE(A_, B_, buf) do { _Pragma("unroll") for (int i = 0; i < 4; ++i) { \
;     *(u32x4*)&As[(buf) * GBUF + (srow + 32 * i) * LDT + sc8] = A_[i]; \
;     *(u32x4*)&Bs[(buf) * GBUF + (srow + 32 * i) * LDT + sc8] = B_[i]; } } while (0)
; template <bool ROWNORM, int NK>
; DI void gemm_main_bf(const u16* __restrict__ Ap, int lda, const u16* __restrict__ Wt, f32x16 (&acc)[2][2], char* smem, float* rinv_s) {
;     ...
;   __builtin_amdgcn_s_setprio(0);
;   BLOAD(a0, b0, 0); BLOAD(a1, b1, 1);
;   __syncthreads();
;   BSTORE(a0, b0, 0);
;   BLOAD(a0, b0, 2);
;   __syncthreads();
; #pragma unroll
;   for (int kt = 0; kt < nk; kt += 2) {
;     BCOMP(0);
;     BSTORE(a1, b1, 1);
;     if (kt + 3 < nk) BLOAD(a1, b1, kt + 3);
;     __syncthreads();
;     BCOMP(1);
;     if (kt + 2 < nk) { BSTORE(a0, b0, 0); if (kt + 4 < nk) BLOAD(a0, b0, kt + 4); }
;     __syncthreads();
	s_waitcnt vmcnt(8)
	s_barrier
	ds_read_b128 v[208:211], v240 offset:0
	ds_read_b128 v[224:227], v241 offset:0
	ds_read_b128 v[228:231], v241 offset:1024
	ds_read_b128 v[232:235], v241 offset:2048
	ds_read_b128 v[236:239], v241 offset:3072
	s_add_u32 m0, s52, 0xc000
	s_add_u32 s28, s28, 0x40
	s_addc_u32 s29, s29, 0
	global_load_lds_dwordx4 v244, s[28:29]
	global_load_lds_dwordx4 v245, s[28:29] offset:1024
	s_add_u32 m0, s53, 0xc000
	s_add_u32 s30, s30, 0x10000
	s_addc_u32 s31, s31, 0
	global_load_lds_dwordx4 v251, s[30:31]
	global_load_lds_dwordx4 v251, s[30:31] offset:1024
	ds_read_b128 v[212:215], v240 offset:1024
	ds_read_b128 v[216:219], v240 offset:2048
	ds_read_b128 v[220:223], v240 offset:3072
	s_waitcnt lgkmcnt(3)
	v_mfma_f32_16x16x32_bf16 v[2:5], v[224:227], v[208:211], v[2:5]
	v_mfma_f32_16x16x32_bf16 v[6:9], v[228:231], v[208:211], v[6:9]
	v_mfma_f32_16x16x32_bf16 v[10:13], v[232:235], v[208:211], v[10:13]
	v_mfma_f32_16x16x32_bf16 v[14:17], v[236:239], v[208:211], v[14:17]
	s_waitcnt lgkmcnt(0)
	v_mfma_f32_16x16x32_bf16 v[18:21], v[224:227], v[212:215], v[18:21]
	v_mfma_f32_16x16x32_bf16 v[22:25], v[228:231], v[212:215], v[22:25]
	v_mfma_f32_16x16x32_bf16 v[26:29], v[232:235], v[212:215], v[26:29]
	v_mfma_f32_16x16x32_bf16 v[30:33], v[236:239], v[212:215], v[30:33]
	v_mfma_f32_16x16x32_bf16 v[34:37], v[224:227], v[216:219], v[34:37]
	v_mfma_f32_16x16x32_bf16 v[38:41], v[228:231], v[216:219], v[38:41]
	v_mfma_f32_16x16x32_bf16 v[42:45], v[232:235], v[216:219], v[42:45]
	v_mfma_f32_16x16x32_bf16 v[46:49], v[236:239], v[216:219], v[46:49]
	v_mfma_f32_16x16x32_bf16 v[50:53], v[224:227], v[220:223], v[50:53]
	v_mfma_f32_16x16x32_bf16 v[54:57], v[228:231], v[220:223], v[54:57]
	v_mfma_f32_16x16x32_bf16 v[58:61], v[232:235], v[220:223], v[58:61]
	v_mfma_f32_16x16x32_bf16 v[62:65], v[236:239], v[220:223], v[62:65]
	s_waitcnt vmcnt(8)
	s_barrier
	ds_read_b128 v[208:211], v240 offset:16384
	ds_read_b128 v[224:227], v241 offset:16384
	ds_read_b128 v[228:231], v241 offset:17408
	ds_read_b128 v[232:235], v241 offset:18432
	ds_read_b128 v[236:239], v241 offset:19456
	ds_read_b128 v[212:215], v240 offset:17408
	ds_read_b128 v[216:219], v240 offset:18432
	ds_read_b128 v[220:223], v240 offset:19456
	s_waitcnt lgkmcnt(3)
	v_mfma_f32_16x16x32_bf16 v[2:5], v[224:227], v[208:211], v[2:5]
	v_mfma_f32_16x16x32_bf16 v[6:9], v[228:231], v[208:211], v[6:9]
	v_mfma_f32_16x16x32_bf16 v[10:13], v[232:235], v[208:211], v[10:13]
	v_mfma_f32_16x16x32_bf16 v[14:17], v[236:239], v[208:211], v[14:17]
	s_waitcnt lgkmcnt(0)
	v_mfma_f32_16x16x32_bf16 v[18:21], v[224:227], v[212:215], v[18:21]
	v_mfma_f32_16x16x32_bf16 v[22:25], v[228:231], v[212:215], v[22:25]
	v_mfma_f32_16x16x32_bf16 v[26:29], v[232:235], v[212:215], v[26:29]
	v_mfma_f32_16x16x32_bf16 v[30:33], v[236:239], v[212:215], v[30:33]
	v_mfma_f32_16x16x32_bf16 v[34:37], v[224:227], v[216:219], v[34:37]
	v_mfma_f32_16x16x32_bf16 v[38:41], v[228:231], v[216:219], v[38:41]
	v_mfma_f32_16x16x32_bf16 v[42:45], v[232:235], v[216:219], v[42:45]
	v_mfma_f32_16x16x32_bf16 v[46:49], v[236:239], v[216:219], v[46:49]
	v_mfma_f32_16x16x32_bf16 v[50:53], v[224:227], v[220:223], v[50:53]
	v_mfma_f32_16x16x32_bf16 v[54:57], v[228:231], v[220:223], v[54:57]
	v_mfma_f32_16x16x32_bf16 v[58:61], v[232:235], v[220:223], v[58:61]
	v_mfma_f32_16x16x32_bf16 v[62:65], v[236:239], v[220:223], v[62:65]
	s_waitcnt vmcnt(4)
	s_barrier
	ds_read_b128 v[208:211], v240 offset:32768
	ds_read_b128 v[224:227], v241 offset:32768
	ds_read_b128 v[228:231], v241 offset:33792
	ds_read_b128 v[232:235], v241 offset:34816
	ds_read_b128 v[236:239], v241 offset:35840
	ds_read_b128 v[212:215], v240 offset:33792
	ds_read_b128 v[216:219], v240 offset:34816
	ds_read_b128 v[220:223], v240 offset:35840
	s_waitcnt lgkmcnt(3)
	v_mfma_f32_16x16x32_bf16 v[2:5], v[224:227], v[208:211], v[2:5]
	v_mfma_f32_16x16x32_bf16 v[6:9], v[228:231], v[208:211], v[6:9]
	v_mfma_f32_16x16x32_bf16 v[10:13], v[232:235], v[208:211], v[10:13]
	v_mfma_f32_16x16x32_bf16 v[14:17], v[236:239], v[208:211], v[14:17]
	s_waitcnt lgkmcnt(0)
	v_mfma_f32_16x16x32_bf16 v[18:21], v[224:227], v[212:215], v[18:21]
	v_mfma_f32_16x16x32_bf16 v[22:25], v[228:231], v[212:215], v[22:25]
	v_mfma_f32_16x16x32_bf16 v[26:29], v[232:235], v[212:215], v[26:29]
	v_mfma_f32_16x16x32_bf16 v[30:33], v[236:239], v[212:215], v[30:33]
	v_mfma_f32_16x16x32_bf16 v[34:37], v[224:227], v[216:219], v[34:37]
	v_mfma_f32_16x16x32_bf16 v[38:41], v[228:231], v[216:219], v[38:41]
	v_mfma_f32_16x16x32_bf16 v[42:45], v[232:235], v[216:219], v[42:45]
	v_mfma_f32_16x16x32_bf16 v[46:49], v[236:239], v[216:219], v[46:49]
	v_mfma_f32_16x16x32_bf16 v[50:53], v[224:227], v[220:223], v[50:53]
	v_mfma_f32_16x16x32_bf16 v[54:57], v[228:231], v[220:223], v[54:57]
	v_mfma_f32_16x16x32_bf16 v[58:61], v[232:235], v[220:223], v[58:61]
	v_mfma_f32_16x16x32_bf16 v[62:65], v[236:239], v[220:223], v[62:65]
	s_waitcnt vmcnt(0)
	s_barrier
; DI unsigned pk2(float a, float b) { f2_t v = {a, b}; bf2_t r = __builtin_convertvector(v, bf2_t); return __builtin_bit_cast(unsigned, r); }
; #define BLOAD(A_, B_, kt) do { _Pragma("unroll") for (int i = 0; i < 4; ++i) { \
;     A_[i] = *(const u32x4*)((const char*)Ap + (aoff + (unsigned)(32 * i * lda + (kt) * 64) * 2u)); B_[i] = *(const u32x4*)((const char*)Wt + (woff + (unsigned)(32 * i * K + (kt) * 64) * 2u)); } } while (0)
; #define BLOAD(A_, B_, kt) do { _Pragma("unroll") for (int i = 0; i < 4; ++i) { \
;     A_[i] = *(const u32x4*)((const char*)Ap + (aoff + (unsigned)(32 * i * lda + (kt) * 64) * 2u)); B_[i] = *(const u32x4*)((const char*)Wt + (woff + (unsigned)(32 * i * K + (kt) * 64) * 2u)); } } while (0)
; #define BSTORE(A_, B_, buf) do { _Pragma("unroll") for (int i = 0; i < 4; ++i) { \
;     *(u32x4*)&As[(buf) * GBUF + (srow + 32 * i) * LDT + sc8] = A_[i]; \
;     *(u32x4*)&Bs[(buf) * GBUF + (srow + 32 * i) * LDT + sc8] = B_[i]; } } while (0)
; template <bool ROWNORM, int NK>
; DI void gemm_main_bf(const u16* __restrict__ Ap, int lda, const u16* __restrict__ Wt, f32x16 (&acc)[2][2], char* smem, float* rinv_s) {
;     ...
;   __builtin_amdgcn_s_setprio(0);
;   BLOAD(a0, b0, 0); BLOAD(a1, b1, 1);
;   __syncthreads();
;   BSTORE(a0, b0, 0);
;   BLOAD(a0, b0, 2);
;   __syncthreads();
; #pragma unroll
;   for (int kt = 0; kt < nk; kt += 2) {
;     BCOMP(0);
;     BSTORE(a1, b1, 1);
;     if (kt + 3 < nk) BLOAD(a1, b1, kt + 3);
;     __syncthreads();
;     BCOMP(1);
;     if (kt + 2 < nk) { BSTORE(a0, b0, 0); if (kt + 4 < nk) BLOAD(a0, b0, kt + 4); }
;     __syncthreads();
; DI void tile_branch(const Params& p, int l, int tile, char* smem) {
;     ...
; #pragma unroll
;     for (int mt = 0; mt < 2; ++mt)
; #pragma unroll
;       for (int nt = 0; nt < 2; ++nt)
; #pragma unroll
;         for (int i = 0; i < 8; ++i) {
;           const float g0 = __uint_as_float(gpk[mt][nt][i] << 16), g1 = __uint_as_float(gpk[mt][nt][i] & 0xffff0000u);
;           const float a = __uint_as_float(upk[mt][nt][i] << 16) + g0 * acc[mt][nt][2 * i];
;           const float b = __uint_as_float(upk[mt][nt][i] & 0xffff0000u) + g1 * acc[mt][nt][2 * i + 1];
;           upk[mt][nt][i] = pk2(a, b);
;         }
	ds_read_b128 v[208:211], v240 offset:49152
	ds_read_b128 v[224:227], v241 offset:49152
	ds_read_b128 v[228:231], v241 offset:50176
	ds_read_b128 v[232:235], v241 offset:51200
	ds_read_b128 v[236:239], v241 offset:52224
	ds_read_b128 v[212:215], v240 offset:50176
	ds_read_b128 v[216:219], v240 offset:51200
	ds_read_b128 v[220:223], v240 offset:52224
	s_waitcnt lgkmcnt(3)
	v_mfma_f32_16x16x32_bf16 v[2:5], v[224:227], v[208:211], v[2:5]
	v_mfma_f32_16x16x32_bf16 v[6:9], v[228:231], v[208:211], v[6:9]
	v_mfma_f32_16x16x32_bf16 v[10:13], v[232:235], v[208:211], v[10:13]
	v_mfma_f32_16x16x32_bf16 v[14:17], v[236:239], v[208:211], v[14:17]
	s_waitcnt lgkmcnt(0)
	v_mfma_f32_16x16x32_bf16 v[18:21], v[224:227], v[212:215], v[18:21]
	v_mfma_f32_16x16x32_bf16 v[22:25], v[228:231], v[212:215], v[22:25]
	v_mfma_f32_16x16x32_bf16 v[26:29], v[232:235], v[212:215], v[26:29]
	v_mfma_f32_16x16x32_bf16 v[30:33], v[236:239], v[212:215], v[30:33]
	v_mfma_f32_16x16x32_bf16 v[34:37], v[224:227], v[216:219], v[34:37]
	v_mfma_f32_16x16x32_bf16 v[38:41], v[228:231], v[216:219], v[38:41]
	v_mfma_f32_16x16x32_bf16 v[42:45], v[232:235], v[216:219], v[42:45]
	v_mfma_f32_16x16x32_bf16 v[46:49], v[236:239], v[216:219], v[46:49]
	v_mfma_f32_16x16x32_bf16 v[50:53], v[224:227], v[220:223], v[50:53]
	v_mfma_f32_16x16x32_bf16 v[54:57], v[228:231], v[220:223], v[54:57]
	v_mfma_f32_16x16x32_bf16 v[58:61], v[232:235], v[220:223], v[58:61]
	v_mfma_f32_16x16x32_bf16 v[62:65], v[236:239], v[220:223], v[62:65]
	s_add_u32 s46, s46, 0x10000
	s_addc_u32 s47, s47, 0
	s_add_u32 s48, s48, 0x1000000
	s_addc_u32 s49, s49, 0
	s_add_u32 s50, s50, 0x100000
	s_addc_u32 s51, s51, 0
	v_lshlrev_b32_e32 v166, 16, v130
	v_and_b32_e32 v167, 0xffff0000, v130
	v_lshlrev_b32_e32 v168, 16, v131
	v_and_b32_e32 v169, 0xffff0000, v131
	v_fmac_f32_e32 v66, v166, v2
	v_fmac_f32_e32 v67, v167, v3
	v_fmac_f32_e32 v68, v168, v4
	v_fmac_f32_e32 v69, v169, v5
	v_lshlrev_b32_e32 v166, 16, v132
	v_and_b32_e32 v167, 0xffff0000, v132
	v_lshlrev_b32_e32 v168, 16, v133
	v_and_b32_e32 v169, 0xffff0000, v133
	v_fmac_f32_e32 v70, v166, v6
	v_fmac_f32_e32 v71, v167, v7
	v_fmac_f32_e32 v72, v168, v8
	v_fmac_f32_e32 v73, v169, v9
	v_lshlrev_b32_e32 v166, 16, v134
	v_and_b32_e32 v167, 0xffff0000, v134
	v_lshlrev_b32_e32 v168, 16, v135
	v_and_b32_e32 v169, 0xffff0000, v135
	v_fmac_f32_e32 v74, v166, v10
	v_fmac_f32_e32 v75, v167, v11
	v_fmac_f32_e32 v76, v168, v12
	v_fmac_f32_e32 v77, v169, v13
	v_lshlrev_b32_e32 v166, 16, v136
	v_and_b32_e32 v167, 0xffff0000, v136
	v_lshlrev_b32_e32 v168, 16, v137
	v_and_b32_e32 v169, 0xffff0000, v137
	v_fmac_f32_e32 v78, v166, v14
	v_fmac_f32_e32 v79, v167, v15
	v_fmac_f32_e32 v80, v168, v16
	v_fmac_f32_e32 v81, v169, v17
	v_lshlrev_b32_e32 v166, 16, v138
	v_and_b32_e32 v167, 0xffff0000, v138
	v_lshlrev_b32_e32 v168, 16, v139
	v_and_b32_e32 v169, 0xffff0000, v139
	v_fmac_f32_e32 v82, v166, v18
	v_fmac_f32_e32 v83, v167, v19
	v_fmac_f32_e32 v84, v168, v20
	v_fmac_f32_e32 v85, v169, v21
	v_lshlrev_b32_e32 v166, 16, v140
	v_and_b32_e32 v167, 0xffff0000, v140
	v_lshlrev_b32_e32 v168, 16, v141
	v_and_b32_e32 v169, 0xffff0000, v141
	v_fmac_f32_e32 v86, v166, v22
	v_fmac_f32_e32 v87, v167, v23
	v_fmac_f32_e32 v88, v168, v24
	v_fmac_f32_e32 v89, v169, v25
	v_lshlrev_b32_e32 v166, 16, v142
	v_and_b32_e32 v167, 0xffff0000, v142
	v_lshlrev_b32_e32 v168, 16, v143
	v_and_b32_e32 v169, 0xffff0000, v143
	v_fmac_f32_e32 v90, v166, v26
	v_fmac_f32_e32 v91, v167, v27
	v_fmac_f32_e32 v92, v168, v28
	v_fmac_f32_e32 v93, v169, v29
	v_lshlrev_b32_e32 v166, 16, v144
	v_and_b32_e32 v167, 0xffff0000, v144
	v_lshlrev_b32_e32 v168, 16, v145
	v_and_b32_e32 v169, 0xffff0000, v145
	v_fmac_f32_e32 v94, v166, v30
	v_fmac_f32_e32 v95, v167, v31
	v_fmac_f32_e32 v96, v168, v32
	v_fmac_f32_e32 v97, v169, v33
	v_lshlrev_b32_e32 v166, 16, v146
	v_and_b32_e32 v167, 0xffff0000, v146
	v_lshlrev_b32_e32 v168, 16, v147
	v_and_b32_e32 v169, 0xffff0000, v147
	v_fmac_f32_e32 v98, v166, v34
	v_fmac_f32_e32 v99, v167, v35
	v_fmac_f32_e32 v100, v168, v36
	v_fmac_f32_e32 v101, v169, v37
	v_lshlrev_b32_e32 v166, 16, v148
	v_and_b32_e32 v167, 0xffff0000, v148
	v_lshlrev_b32_e32 v168, 16, v149
	v_and_b32_e32 v169, 0xffff0000, v149
	v_fmac_f32_e32 v102, v166, v38
	v_fmac_f32_e32 v103, v167, v39
	v_fmac_f32_e32 v104, v168, v40
	v_fmac_f32_e32 v105, v169, v41
	v_lshlrev_b32_e32 v166, 16, v150
	v_and_b32_e32 v167, 0xffff0000, v150
	v_lshlrev_b32_e32 v168, 16, v151
	v_and_b32_e32 v169, 0xffff0000, v151
	v_fmac_f32_e32 v106, v166, v42
	v_fmac_f32_e32 v107, v167, v43
	v_fmac_f32_e32 v108, v168, v44
	v_fmac_f32_e32 v109, v169, v45
	v_lshlrev_b32_e32 v166, 16, v152
	v_and_b32_e32 v167, 0xffff0000, v152
	v_lshlrev_b32_e32 v168, 16, v153
	v_and_b32_e32 v169, 0xffff0000, v153
	v_fmac_f32_e32 v110, v166, v46
	v_fmac_f32_e32 v111, v167, v47
	v_fmac_f32_e32 v112, v168, v48
	v_fmac_f32_e32 v113, v169, v49
	v_lshlrev_b32_e32 v166, 16, v154
	v_and_b32_e32 v167, 0xffff0000, v154
	v_lshlrev_b32_e32 v168, 16, v155
	v_and_b32_e32 v169, 0xffff0000, v155
	v_fmac_f32_e32 v114, v166, v50
	v_fmac_f32_e32 v115, v167, v51
	v_fmac_f32_e32 v116, v168, v52
	v_fmac_f32_e32 v117, v169, v53
	v_lshlrev_b32_e32 v166, 16, v156
	v_and_b32_e32 v167, 0xffff0000, v156
	v_lshlrev_b32_e32 v168, 16, v157
	v_and_b32_e32 v169, 0xffff0000, v157
	v_fmac_f32_e32 v118, v166, v54
	v_fmac_f32_e32 v119, v167, v55
	v_fmac_f32_e32 v120, v168, v56
	v_fmac_f32_e32 v121, v169, v57
	v_lshlrev_b32_e32 v166, 16, v158
	v_and_b32_e32 v167, 0xffff0000, v158
	v_lshlrev_b32_e32 v168, 16, v159
	v_and_b32_e32 v169, 0xffff0000, v159
	v_fmac_f32_e32 v122, v166, v58
	v_fmac_f32_e32 v123, v167, v59
	v_fmac_f32_e32 v124, v168, v60
	v_fmac_f32_e32 v125, v169, v61
	v_lshlrev_b32_e32 v166, 16, v160
	v_and_b32_e32 v167, 0xffff0000, v160
	v_lshlrev_b32_e32 v168, 16, v161
	v_and_b32_e32 v169, 0xffff0000, v161
	v_fmac_f32_e32 v126, v166, v62
	v_fmac_f32_e32 v127, v167, v63
	v_fmac_f32_e32 v128, v168, v64
	v_fmac_f32_e32 v129, v169, v65
	s_cmp_eq_u32 s75, 2
	s_cbranch_scc1 .Lbr_noprol
	s_mov_b64 s[28:29], s[44:45]
	s_mov_b64 s[30:31], s[46:47]
	s_add_u32 m0, s52, 0x0
	s_nop 0
	global_load_lds_dwordx4 v251, s[28:29]
	global_load_lds_dwordx4 v251, s[28:29] offset:1024
	s_add_u32 m0, s53, 0x0
	s_nop 0
	global_load_lds_dwordx4 v251, s[30:31]
	global_load_lds_dwordx4 v251, s[30:31] offset:1024
	s_add_u32 m0, s52, 0x4000
	s_add_u32 s28, s28, 0x100000
	s_addc_u32 s29, s29, 0
	global_load_lds_dwordx4 v251, s[28:29]
	global_load_lds_dwordx4 v251, s[28:29] offset:1024
	s_add_u32 m0, s53, 0x4000
	s_add_u32 s30, s30, 0x30000
	s_addc_u32 s31, s31, 0
	global_load_lds_dwordx4 v251, s[30:31]
	global_load_lds_dwordx4 v251, s[30:31] offset:1024
	s_add_u32 m0, s52, 0x8000
	s_add_u32 s28, s28, 0x100000
	s_addc_u32 s29, s29, 0
	global_load_lds_dwordx4 v251, s[28:29]
	global_load_lds_dwordx4 v251, s[28:29] offset:1024
	s_add_u32 m0, s53, 0x8000
	s_add_u32 s30, s30, 0x30000
	s_addc_u32 s31, s31, 0
	global_load_lds_dwordx4 v251, s[30:31]
	global_load_lds_dwordx4 v251, s[30:31] offset:1024

; #define BLOAD(A_, B_, kt) do { _Pragma("unroll") for (int i = 0; i < 4; ++i) { \
;     A_[i] = *(const u32x4*)((const char*)Ap + (aoff + (unsigned)(32 * i * lda + (kt) * 64) * 2u)); B_[i] = *(const u32x4*)((const char*)Wt + (woff + (unsigned)(32 * i * K + (kt) * 64) * 2u)); } } while (0)
; #define BLOAD(A_, B_, kt) do { _Pragma("unroll") for (int i = 0; i < 4; ++i) { \
;     A_[i] = *(const u32x4*)((const char*)Ap + (aoff + (unsigned)(32 * i * lda + (kt) * 64) * 2u)); B_[i] = *(const u32x4*)((const char*)Wt + (woff + (unsigned)(32 * i * K + (kt) * 64) * 2u)); } } while (0)
; #define BSTORE(A_, B_, buf) do { _Pragma("unroll") for (int i = 0; i < 4; ++i) { \
;     *(u32x4*)&As[(buf) * GBUF + (srow + 32 * i) * LDT + sc8] = A_[i]; \
;     *(u32x4*)&Bs[(buf) * GBUF + (srow + 32 * i) * LDT + sc8] = B_[i]; } } while (0)
; template <int NK>
; DI void gemm_run(PF& pf, const u16* __restrict__ Ap, int lda, const u16* __restrict__ Wt, f32x16 (&acc)[2][2], char* smem) {
;     ...
;   __builtin_amdgcn_s_setprio(0);
;   __syncthreads();
;   BSTORE(pf.a0, pf.b0, 0);
;   BLOAD(pf.a0, pf.b0, 2);
;   __syncthreads();
; #pragma unroll
;   for (int kt = 0; kt < nk; kt += 2) {
;     BCOMP(0);
;     BSTORE(pf.a1, pf.b1, 1);
;     if (kt + 3 < nk) BLOAD(pf.a1, pf.b1, kt + 3);
;     __syncthreads();
;     BCOMP(1);
;     if (kt + 2 < nk) { BSTORE(pf.a0, pf.b0, 0); if (kt + 4 < nk) BLOAD(pf.a0, pf.b0, kt + 4); }
;     __syncthreads();
.Linp_kloop:
	s_waitcnt vmcnt(6)
	s_barrier
	ds_read_b128 v[224:227], v126 offset:0
	ds_read_b128 v[240:243], v128 offset:0
	ds_read_b128 v[244:247], v128 offset:1024
	ds_read_b128 v[248:251], v128 offset:2048
	ds_read_b128 v[156:159], v128 offset:3072
	s_add_u32 m0, s46, 0xc000
	s_add_u32 s48, s48, 0x100000
	s_addc_u32 s49, s49, 0
	global_load_lds_dwordx4 v138, s[48:49]
	global_load_lds_dwordx4 v139, s[48:49] offset:1024
	s_add_u32 m0, s47, 0xc000
	s_add_u32 s50, s50, s13
	s_addc_u32 s51, s51, 0
	global_load_lds_dwordx4 v140, s[50:51]
	global_load_lds_dwordx4 v141, s[50:51] offset:1024
	global_load_lds_dwordx4 v142, s[50:51] offset:2048
	global_load_lds_dwordx4 v143, s[50:51] offset:3072
	ds_read_b128 v[228:231], v126 offset:1024
	ds_read_b128 v[232:235], v126 offset:2048
	ds_read_b128 v[236:239], v126 offset:3072
	ds_read_b128 v[160:163], v128 offset:8192
	ds_read_b128 v[164:167], v128 offset:9216
	ds_read_b128 v[168:171], v128 offset:10240
	ds_read_b128 v[122:125], v128 offset:11264
	s_waitcnt lgkmcnt(7)
	v_mfma_f32_16x16x32_bf16 v[2:5], v[224:227], v[240:243], v[2:5]
	v_mfma_f32_16x16x32_bf16 v[6:9], v[224:227], v[244:247], v[6:9]
	v_mfma_f32_16x16x32_bf16 v[10:13], v[224:227], v[248:251], v[10:13]
	v_mfma_f32_16x16x32_bf16 v[14:17], v[224:227], v[156:159], v[14:17]
	s_waitcnt lgkmcnt(4)
	v_mfma_f32_16x16x32_bf16 v[18:21], v[228:231], v[240:243], v[18:21]
	v_mfma_f32_16x16x32_bf16 v[22:25], v[228:231], v[244:247], v[22:25]
	v_mfma_f32_16x16x32_bf16 v[26:29], v[228:231], v[248:251], v[26:29]
	v_mfma_f32_16x16x32_bf16 v[30:33], v[228:231], v[156:159], v[30:33]
	v_mfma_f32_16x16x32_bf16 v[34:37], v[232:235], v[240:243], v[34:37]
	v_mfma_f32_16x16x32_bf16 v[38:41], v[232:235], v[244:247], v[38:41]
	v_mfma_f32_16x16x32_bf16 v[42:45], v[232:235], v[248:251], v[42:45]
	v_mfma_f32_16x16x32_bf16 v[46:49], v[232:235], v[156:159], v[46:49]
	v_mfma_f32_16x16x32_bf16 v[50:53], v[236:239], v[240:243], v[50:53]
	v_mfma_f32_16x16x32_bf16 v[54:57], v[236:239], v[244:247], v[54:57]
	v_mfma_f32_16x16x32_bf16 v[58:61], v[236:239], v[248:251], v[58:61]
	v_mfma_f32_16x16x32_bf16 v[62:65], v[236:239], v[156:159], v[62:65]
	s_waitcnt lgkmcnt(0)
	v_mfma_f32_16x16x32_bf16 v[74:77], v[224:227], v[160:163], v[74:77]
	v_mfma_f32_16x16x32_bf16 v[78:81], v[224:227], v[164:167], v[78:81]
	v_mfma_f32_16x16x32_bf16 v[82:85], v[224:227], v[168:171], v[82:85]
	v_mfma_f32_16x16x32_bf16 v[86:89], v[224:227], v[122:125], v[86:89]
	v_mfma_f32_16x16x32_bf16 v[90:93], v[228:231], v[160:163], v[90:93]
	v_mfma_f32_16x16x32_bf16 v[94:97], v[228:231], v[164:167], v[94:97]
	v_mfma_f32_16x16x32_bf16 v[98:101], v[228:231], v[168:171], v[98:101]
	v_mfma_f32_16x16x32_bf16 v[102:105], v[228:231], v[122:125], v[102:105]
	v_mfma_f32_16x16x32_bf16 v[106:109], v[232:235], v[160:163], v[106:109]
	v_mfma_f32_16x16x32_bf16 v[110:113], v[232:235], v[164:167], v[110:113]
	v_mfma_f32_16x16x32_bf16 v[114:117], v[232:235], v[168:171], v[114:117]
	v_mfma_f32_16x16x32_bf16 v[118:121], v[232:235], v[122:125], v[118:121]
	v_mfma_f32_16x16x32_bf16 v[208:211], v[236:239], v[160:163], v[208:211]
	v_mfma_f32_16x16x32_bf16 v[212:215], v[236:239], v[164:167], v[212:215]
	v_mfma_f32_16x16x32_bf16 v[216:219], v[236:239], v[168:171], v[216:219]
	v_mfma_f32_16x16x32_bf16 v[220:223], v[236:239], v[122:125], v[220:223]
	s_waitcnt vmcnt(6)
	s_barrier
	ds_read_b128 v[224:227], v126 offset:24576
	ds_read_b128 v[240:243], v128 offset:24576
	ds_read_b128 v[244:247], v128 offset:25600
	ds_read_b128 v[248:251], v128 offset:26624
	ds_read_b128 v[156:159], v128 offset:27648
	s_add_u32 m0, s46, 0x0
	s_add_u32 s48, s48, 0x100000
	s_addc_u32 s49, s49, 0
	global_load_lds_dwordx4 v138, s[48:49]
	global_load_lds_dwordx4 v139, s[48:49] offset:1024
	s_add_u32 m0, s47, 0x0
	s_add_u32 s50, s50, s13
	s_addc_u32 s51, s51, 0
	global_load_lds_dwordx4 v140, s[50:51]
	global_load_lds_dwordx4 v141, s[50:51] offset:1024
	global_load_lds_dwordx4 v142, s[50:51] offset:2048
	global_load_lds_dwordx4 v143, s[50:51] offset:3072
	ds_read_b128 v[228:231], v126 offset:25600
	ds_read_b128 v[232:235], v126 offset:26624
	ds_read_b128 v[236:239], v126 offset:27648
	ds_read_b128 v[160:163], v128 offset:32768
	ds_read_b128 v[164:167], v128 offset:33792
	ds_read_b128 v[168:171], v128 offset:34816
	ds_read_b128 v[122:125], v128 offset:35840
	s_waitcnt lgkmcnt(7)
	v_mfma_f32_16x16x32_bf16 v[2:5], v[224:227], v[240:243], v[2:5]
	v_mfma_f32_16x16x32_bf16 v[6:9], v[224:227], v[244:247], v[6:9]
	v_mfma_f32_16x16x32_bf16 v[10:13], v[224:227], v[248:251], v[10:13]
	v_mfma_f32_16x16x32_bf16 v[14:17], v[224:227], v[156:159], v[14:17]
	s_waitcnt lgkmcnt(4)
	v_mfma_f32_16x16x32_bf16 v[18:21], v[228:231], v[240:243], v[18:21]
	v_mfma_f32_16x16x32_bf16 v[22:25], v[228:231], v[244:247], v[22:25]
	v_mfma_f32_16x16x32_bf16 v[26:29], v[228:231], v[248:251], v[26:29]
	v_mfma_f32_16x16x32_bf16 v[30:33], v[228:231], v[156:159], v[30:33]
	v_mfma_f32_16x16x32_bf16 v[34:37], v[232:235], v[240:243], v[34:37]
	v_mfma_f32_16x16x32_bf16 v[38:41], v[232:235], v[244:247], v[38:41]
	v_mfma_f32_16x16x32_bf16 v[42:45], v[232:235], v[248:251], v[42:45]
	v_mfma_f32_16x16x32_bf16 v[46:49], v[232:235], v[156:159], v[46:49]
	v_mfma_f32_16x16x32_bf16 v[50:53], v[236:239], v[240:243], v[50:53]
	v_mfma_f32_16x16x32_bf16 v[54:57], v[236:239], v[244:247], v[54:57]
	v_mfma_f32_16x16x32_bf16 v[58:61], v[236:239], v[248:251], v[58:61]
	v_mfma_f32_16x16x32_bf16 v[62:65], v[236:239], v[156:159], v[62:65]
	s_waitcnt lgkmcnt(0)
	v_mfma_f32_16x16x32_bf16 v[74:77], v[224:227], v[160:163], v[74:77]
	v_mfma_f32_16x16x32_bf16 v[78:81], v[224:227], v[164:167], v[78:81]
	v_mfma_f32_16x16x32_bf16 v[82:85], v[224:227], v[168:171], v[82:85]
	v_mfma_f32_16x16x32_bf16 v[86:89], v[224:227], v[122:125], v[86:89]
	v_mfma_f32_16x16x32_bf16 v[90:93], v[228:231], v[160:163], v[90:93]
	v_mfma_f32_16x16x32_bf16 v[94:97], v[228:231], v[164:167], v[94:97]
	v_mfma_f32_16x16x32_bf16 v[98:101], v[228:231], v[168:171], v[98:101]
	v_mfma_f32_16x16x32_bf16 v[102:105], v[228:231], v[122:125], v[102:105]
	v_mfma_f32_16x16x32_bf16 v[106:109], v[232:235], v[160:163], v[106:109]
	v_mfma_f32_16x16x32_bf16 v[110:113], v[232:235], v[164:167], v[110:113]
	v_mfma_f32_16x16x32_bf16 v[114:117], v[232:235], v[168:171], v[114:117]
	v_mfma_f32_16x16x32_bf16 v[118:121], v[232:235], v[122:125], v[118:121]
	v_mfma_f32_16x16x32_bf16 v[208:211], v[236:239], v[160:163], v[208:211]
	v_mfma_f32_16x16x32_bf16 v[212:215], v[236:239], v[164:167], v[212:215]
	v_mfma_f32_16x16x32_bf16 v[216:219], v[236:239], v[168:171], v[216:219]
	v_mfma_f32_16x16x32_bf16 v[220:223], v[236:239], v[122:125], v[220:223]
	s_waitcnt vmcnt(6)
	s_barrier
; #define BLOAD(A_, B_, kt) do { _Pragma("unroll") for (int i = 0; i < 4; ++i) { \
;     A_[i] = *(const u32x4*)((const char*)Ap + (aoff + (unsigned)(32 * i * lda + (kt) * 64) * 2u)); B_[i] = *(const u32x4*)((const char*)Wt + (woff + (unsigned)(32 * i * K + (kt) * 64) * 2u)); } } while (0)
; #define BLOAD(A_, B_, kt) do { _Pragma("unroll") for (int i = 0; i < 4; ++i) { \
;     A_[i] = *(const u32x4*)((const char*)Ap + (aoff + (unsigned)(32 * i * lda + (kt) * 64) * 2u)); B_[i] = *(const u32x4*)((const char*)Wt + (woff + (unsigned)(32 * i * K + (kt) * 64) * 2u)); } } while (0)
; #define BSTORE(A_, B_, buf) do { _Pragma("unroll") for (int i = 0; i < 4; ++i) { \
;     *(u32x4*)&As[(buf) * GBUF + (srow + 32 * i) * LDT + sc8] = A_[i]; \
;     *(u32x4*)&Bs[(buf) * GBUF + (srow + 32 * i) * LDT + sc8] = B_[i]; } } while (0)
; template <int NK>
; DI void gemm_run(PF& pf, const u16* __restrict__ Ap, int lda, const u16* __restrict__ Wt, f32x16 (&acc)[2][2], char* smem) {
;     ...
;   __builtin_amdgcn_s_setprio(0);
;   __syncthreads();
;   BSTORE(pf.a0, pf.b0, 0);
;   BLOAD(pf.a0, pf.b0, 2);
;   __syncthreads();
; #pragma unroll
;   for (int kt = 0; kt < nk; kt += 2) {
;     BCOMP(0);
;     BSTORE(pf.a1, pf.b1, 1);
;     if (kt + 3 < nk) BLOAD(pf.a1, pf.b1, kt + 3);
;     __syncthreads();
;     BCOMP(1);
;     if (kt + 2 < nk) { BSTORE(pf.a0, pf.b0, 0); if (kt + 4 < nk) BLOAD(pf.a0, pf.b0, kt + 4); }
;     __syncthreads();
	ds_read_b128 v[224:227], v126 offset:49152
	ds_read_b128 v[240:243], v128 offset:49152
	ds_read_b128 v[244:247], v128 offset:50176
	ds_read_b128 v[248:251], v128 offset:51200
	ds_read_b128 v[156:159], v128 offset:52224
	s_add_u32 m0, s46, 0x6000
	s_add_u32 s48, s48, 0x100000
	s_addc_u32 s49, s49, 0
	global_load_lds_dwordx4 v138, s[48:49]
	global_load_lds_dwordx4 v139, s[48:49] offset:1024
	s_add_u32 m0, s47, 0x6000
	s_add_u32 s50, s50, s13
	s_addc_u32 s51, s51, 0
	global_load_lds_dwordx4 v140, s[50:51]
	global_load_lds_dwordx4 v141, s[50:51] offset:1024
	global_load_lds_dwordx4 v142, s[50:51] offset:2048
	global_load_lds_dwordx4 v143, s[50:51] offset:3072
	ds_read_b128 v[228:231], v126 offset:50176
	ds_read_b128 v[232:235], v126 offset:51200
	ds_read_b128 v[236:239], v126 offset:52224
	ds_read_b128 v[160:163], v128 offset:57344
	ds_read_b128 v[164:167], v128 offset:58368
	ds_read_b128 v[168:171], v128 offset:59392
	ds_read_b128 v[122:125], v128 offset:60416
	s_waitcnt lgkmcnt(7)
	v_mfma_f32_16x16x32_bf16 v[2:5], v[224:227], v[240:243], v[2:5]
	v_mfma_f32_16x16x32_bf16 v[6:9], v[224:227], v[244:247], v[6:9]
	v_mfma_f32_16x16x32_bf16 v[10:13], v[224:227], v[248:251], v[10:13]
	v_mfma_f32_16x16x32_bf16 v[14:17], v[224:227], v[156:159], v[14:17]
	s_waitcnt lgkmcnt(4)
	v_mfma_f32_16x16x32_bf16 v[18:21], v[228:231], v[240:243], v[18:21]
	v_mfma_f32_16x16x32_bf16 v[22:25], v[228:231], v[244:247], v[22:25]
	v_mfma_f32_16x16x32_bf16 v[26:29], v[228:231], v[248:251], v[26:29]
	v_mfma_f32_16x16x32_bf16 v[30:33], v[228:231], v[156:159], v[30:33]
	v_mfma_f32_16x16x32_bf16 v[34:37], v[232:235], v[240:243], v[34:37]
	v_mfma_f32_16x16x32_bf16 v[38:41], v[232:235], v[244:247], v[38:41]
	v_mfma_f32_16x16x32_bf16 v[42:45], v[232:235], v[248:251], v[42:45]
	v_mfma_f32_16x16x32_bf16 v[46:49], v[232:235], v[156:159], v[46:49]
	v_mfma_f32_16x16x32_bf16 v[50:53], v[236:239], v[240:243], v[50:53]
	v_mfma_f32_16x16x32_bf16 v[54:57], v[236:239], v[244:247], v[54:57]
	v_mfma_f32_16x16x32_bf16 v[58:61], v[236:239], v[248:251], v[58:61]
	v_mfma_f32_16x16x32_bf16 v[62:65], v[236:239], v[156:159], v[62:65]
	s_waitcnt lgkmcnt(0)
	v_mfma_f32_16x16x32_bf16 v[74:77], v[224:227], v[160:163], v[74:77]
	v_mfma_f32_16x16x32_bf16 v[78:81], v[224:227], v[164:167], v[78:81]
	v_mfma_f32_16x16x32_bf16 v[82:85], v[224:227], v[168:171], v[82:85]
	v_mfma_f32_16x16x32_bf16 v[86:89], v[224:227], v[122:125], v[86:89]
	v_mfma_f32_16x16x32_bf16 v[90:93], v[228:231], v[160:163], v[90:93]
	v_mfma_f32_16x16x32_bf16 v[94:97], v[228:231], v[164:167], v[94:97]
	v_mfma_f32_16x16x32_bf16 v[98:101], v[228:231], v[168:171], v[98:101]
	v_mfma_f32_16x16x32_bf16 v[102:105], v[228:231], v[122:125], v[102:105]
	v_mfma_f32_16x16x32_bf16 v[106:109], v[232:235], v[160:163], v[106:109]
	v_mfma_f32_16x16x32_bf16 v[110:113], v[232:235], v[164:167], v[110:113]
	v_mfma_f32_16x16x32_bf16 v[114:117], v[232:235], v[168:171], v[114:117]
	v_mfma_f32_16x16x32_bf16 v[118:121], v[232:235], v[122:125], v[118:121]
	v_mfma_f32_16x16x32_bf16 v[208:211], v[236:239], v[160:163], v[208:211]
	v_mfma_f32_16x16x32_bf16 v[212:215], v[236:239], v[164:167], v[212:215]
	v_mfma_f32_16x16x32_bf16 v[216:219], v[236:239], v[168:171], v[216:219]
	v_mfma_f32_16x16x32_bf16 v[220:223], v[236:239], v[122:125], v[220:223]
	s_sub_u32 s12, s12, 1
	s_cmp_lg_u32 s12, 0
	s_cbranch_scc1 .Linp_kloop
	s_waitcnt vmcnt(6)
	s_barrier
; #define BLOAD(A_, B_, kt) do { _Pragma("unroll") for (int i = 0; i < 4; ++i) { \
;     A_[i] = *(const u32x4*)((const char*)Ap + (aoff + (unsigned)(32 * i * lda + (kt) * 64) * 2u)); B_[i] = *(const u32x4*)((const char*)Wt + (woff + (unsigned)(32 * i * K + (kt) * 64) * 2u)); } } while (0)
; #define BLOAD(A_, B_, kt) do { _Pragma("unroll") for (int i = 0; i < 4; ++i) { \
;     A_[i] = *(const u32x4*)((const char*)Ap + (aoff + (unsigned)(32 * i * lda + (kt) * 64) * 2u)); B_[i] = *(const u32x4*)((const char*)Wt + (woff + (unsigned)(32 * i * K + (kt) * 64) * 2u)); } } while (0)
; #define BSTORE(A_, B_, buf) do { _Pragma("unroll") for (int i = 0; i < 4; ++i) { \
;     *(u32x4*)&As[(buf) * GBUF + (srow + 32 * i) * LDT + sc8] = A_[i]; \
;     *(u32x4*)&Bs[(buf) * GBUF + (srow + 32 * i) * LDT + sc8] = B_[i]; } } while (0)
; template <int NK>
; DI void gemm_run(PF& pf, const u16* __restrict__ Ap, int lda, const u16* __restrict__ Wt, f32x16 (&acc)[2][2], char* smem) {
;     ...
; #pragma unroll
;   for (int kt = 0; kt < nk; kt += 2) {
;     BCOMP(0);
;     BSTORE(pf.a1, pf.b1, 1);
;     if (kt + 3 < nk) BLOAD(pf.a1, pf.b1, kt + 3);
;     __syncthreads();
;     BCOMP(1);
;     if (kt + 2 < nk) { BSTORE(pf.a0, pf.b0, 0); if (kt + 4 < nk) BLOAD(pf.a0, pf.b0, kt + 4); }
;     __syncthreads();
;   }
	ds_read_b128 v[224:227], v126 offset:0
	ds_read_b128 v[240:243], v128 offset:0
	ds_read_b128 v[244:247], v128 offset:1024
	ds_read_b128 v[248:251], v128 offset:2048
	ds_read_b128 v[156:159], v128 offset:3072
	ds_read_b128 v[228:231], v126 offset:1024
	ds_read_b128 v[232:235], v126 offset:2048
	ds_read_b128 v[236:239], v126 offset:3072
	ds_read_b128 v[160:163], v128 offset:8192
	ds_read_b128 v[164:167], v128 offset:9216
	ds_read_b128 v[168:171], v128 offset:10240
	ds_read_b128 v[122:125], v128 offset:11264
	s_waitcnt lgkmcnt(7)
	v_mfma_f32_16x16x32_bf16 v[2:5], v[224:227], v[240:243], v[2:5]
	v_mfma_f32_16x16x32_bf16 v[6:9], v[224:227], v[244:247], v[6:9]
	v_mfma_f32_16x16x32_bf16 v[10:13], v[224:227], v[248:251], v[10:13]
	v_mfma_f32_16x16x32_bf16 v[14:17], v[224:227], v[156:159], v[14:17]
	s_waitcnt lgkmcnt(4)
	v_mfma_f32_16x16x32_bf16 v[18:21], v[228:231], v[240:243], v[18:21]
	v_mfma_f32_16x16x32_bf16 v[22:25], v[228:231], v[244:247], v[22:25]
	v_mfma_f32_16x16x32_bf16 v[26:29], v[228:231], v[248:251], v[26:29]
	v_mfma_f32_16x16x32_bf16 v[30:33], v[228:231], v[156:159], v[30:33]
	v_mfma_f32_16x16x32_bf16 v[34:37], v[232:235], v[240:243], v[34:37]
	v_mfma_f32_16x16x32_bf16 v[38:41], v[232:235], v[244:247], v[38:41]
	v_mfma_f32_16x16x32_bf16 v[42:45], v[232:235], v[248:251], v[42:45]
	v_mfma_f32_16x16x32_bf16 v[46:49], v[232:235], v[156:159], v[46:49]
	v_mfma_f32_16x16x32_bf16 v[50:53], v[236:239], v[240:243], v[50:53]
	v_mfma_f32_16x16x32_bf16 v[54:57], v[236:239], v[244:247], v[54:57]
	v_mfma_f32_16x16x32_bf16 v[58:61], v[236:239], v[248:251], v[58:61]
	v_mfma_f32_16x16x32_bf16 v[62:65], v[236:239], v[156:159], v[62:65]
	s_waitcnt lgkmcnt(0)
	v_mfma_f32_16x16x32_bf16 v[74:77], v[224:227], v[160:163], v[74:77]
	v_mfma_f32_16x16x32_bf16 v[78:81], v[224:227], v[164:167], v[78:81]
	v_mfma_f32_16x16x32_bf16 v[82:85], v[224:227], v[168:171], v[82:85]
	v_mfma_f32_16x16x32_bf16 v[86:89], v[224:227], v[122:125], v[86:89]
	v_mfma_f32_16x16x32_bf16 v[90:93], v[228:231], v[160:163], v[90:93]
	v_mfma_f32_16x16x32_bf16 v[94:97], v[228:231], v[164:167], v[94:97]
	v_mfma_f32_16x16x32_bf16 v[98:101], v[228:231], v[168:171], v[98:101]
	v_mfma_f32_16x16x32_bf16 v[102:105], v[228:231], v[122:125], v[102:105]
	v_mfma_f32_16x16x32_bf16 v[106:109], v[232:235], v[160:163], v[106:109]
	v_mfma_f32_16x16x32_bf16 v[110:113], v[232:235], v[164:167], v[110:113]
	v_mfma_f32_16x16x32_bf16 v[114:117], v[232:235], v[168:171], v[114:117]
	v_mfma_f32_16x16x32_bf16 v[118:121], v[232:235], v[122:125], v[118:121]
	v_mfma_f32_16x16x32_bf16 v[208:211], v[236:239], v[160:163], v[208:211]
	v_mfma_f32_16x16x32_bf16 v[212:215], v[236:239], v[164:167], v[212:215]
	v_mfma_f32_16x16x32_bf16 v[216:219], v[236:239], v[168:171], v[216:219]
	v_mfma_f32_16x16x32_bf16 v[220:223], v[236:239], v[122:125], v[220:223]
	s_waitcnt vmcnt(0)
	s_barrier
	ds_read_b128 v[224:227], v126 offset:24576
	ds_read_b128 v[240:243], v128 offset:24576
	ds_read_b128 v[244:247], v128 offset:25600
	ds_read_b128 v[248:251], v128 offset:26624
	ds_read_b128 v[156:159], v128 offset:27648
	ds_read_b128 v[228:231], v126 offset:25600
	ds_read_b128 v[232:235], v126 offset:26624
	ds_read_b128 v[236:239], v126 offset:27648
	ds_read_b128 v[160:163], v128 offset:32768
	ds_read_b128 v[164:167], v128 offset:33792
	ds_read_b128 v[168:171], v128 offset:34816
	ds_read_b128 v[122:125], v128 offset:35840
	s_waitcnt lgkmcnt(7)
	v_mfma_f32_16x16x32_bf16 v[2:5], v[224:227], v[240:243], v[2:5]
	v_mfma_f32_16x16x32_bf16 v[6:9], v[224:227], v[244:247], v[6:9]
	v_mfma_f32_16x16x32_bf16 v[10:13], v[224:227], v[248:251], v[10:13]
	v_mfma_f32_16x16x32_bf16 v[14:17], v[224:227], v[156:159], v[14:17]
	s_waitcnt lgkmcnt(4)
	v_mfma_f32_16x16x32_bf16 v[18:21], v[228:231], v[240:243], v[18:21]
	v_mfma_f32_16x16x32_bf16 v[22:25], v[228:231], v[244:247], v[22:25]
	v_mfma_f32_16x16x32_bf16 v[26:29], v[228:231], v[248:251], v[26:29]
	v_mfma_f32_16x16x32_bf16 v[30:33], v[228:231], v[156:159], v[30:33]
	v_mfma_f32_16x16x32_bf16 v[34:37], v[232:235], v[240:243], v[34:37]
	v_mfma_f32_16x16x32_bf16 v[38:41], v[232:235], v[244:247], v[38:41]
	v_mfma_f32_16x16x32_bf16 v[42:45], v[232:235], v[248:251], v[42:45]
	v_mfma_f32_16x16x32_bf16 v[46:49], v[232:235], v[156:159], v[46:49]
	v_mfma_f32_16x16x32_bf16 v[50:53], v[236:239], v[240:243], v[50:53]
	v_mfma_f32_16x16x32_bf16 v[54:57], v[236:239], v[244:247], v[54:57]
	v_mfma_f32_16x16x32_bf16 v[58:61], v[236:239], v[248:251], v[58:61]
	v_mfma_f32_16x16x32_bf16 v[62:65], v[236:239], v[156:159], v[62:65]
	s_waitcnt lgkmcnt(0)
	v_mfma_f32_16x16x32_bf16 v[74:77], v[224:227], v[160:163], v[74:77]
	v_mfma_f32_16x16x32_bf16 v[78:81], v[224:227], v[164:167], v[78:81]
	v_mfma_f32_16x16x32_bf16 v[82:85], v[224:227], v[168:171], v[82:85]
	v_mfma_f32_16x16x32_bf16 v[86:89], v[224:227], v[122:125], v[86:89]
	v_mfma_f32_16x16x32_bf16 v[90:93], v[228:231], v[160:163], v[90:93]
	v_mfma_f32_16x16x32_bf16 v[94:97], v[228:231], v[164:167], v[94:97]
	v_mfma_f32_16x16x32_bf16 v[98:101], v[228:231], v[168:171], v[98:101]
	v_mfma_f32_16x16x32_bf16 v[102:105], v[228:231], v[122:125], v[102:105]
	v_mfma_f32_16x16x32_bf16 v[106:109], v[232:235], v[160:163], v[106:109]
	v_mfma_f32_16x16x32_bf16 v[110:113], v[232:235], v[164:167], v[110:113]
	v_mfma_f32_16x16x32_bf16 v[114:117], v[232:235], v[168:171], v[114:117]
	v_mfma_f32_16x16x32_bf16 v[118:121], v[232:235], v[122:125], v[118:121]
	v_mfma_f32_16x16x32_bf16 v[208:211], v[236:239], v[160:163], v[208:211]
	v_mfma_f32_16x16x32_bf16 v[212:215], v[236:239], v[164:167], v[212:215]
	v_mfma_f32_16x16x32_bf16 v[216:219], v[236:239], v[168:171], v[216:219]
	v_mfma_f32_16x16x32_bf16 v[220:223], v[236:239], v[122:125], v[220:223]
	s_barrier
	s_branch .Linp_post

; #define BLOAD(A_, B_, kt) do { _Pragma("unroll") for (int i = 0; i < 4; ++i) { \
;     A_[i] = *(const u32x4*)((const char*)Ap + (aoff + (unsigned)(32 * i * lda + (kt) * 64) * 2u)); B_[i] = *(const u32x4*)((const char*)Wt + (woff + (unsigned)(32 * i * K + (kt) * 64) * 2u)); } } while (0)
; #define BLOAD(A_, B_, kt) do { _Pragma("unroll") for (int i = 0; i < 4; ++i) { \
;     A_[i] = *(const u32x4*)((const char*)Ap + (aoff + (unsigned)(32 * i * lda + (kt) * 64) * 2u)); B_[i] = *(const u32x4*)((const char*)Wt + (woff + (unsigned)(32 * i * K + (kt) * 64) * 2u)); } } while (0)
; #define BSTORE(A_, B_, buf) do { _Pragma("unroll") for (int i = 0; i < 4; ++i) { \
;     *(u32x4*)&As[(buf) * GBUF + (srow + 32 * i) * LDT + sc8] = A_[i]; \
;     *(u32x4*)&Bs[(buf) * GBUF + (srow + 32 * i) * LDT + sc8] = B_[i]; } } while (0)
; template <int NK>
; DI void gemm_run(PF& pf, const u16* __restrict__ Ap, int lda, const u16* __restrict__ Wt, f32x16 (&acc)[2][2], char* smem) {
;     ...
;   __builtin_amdgcn_s_setprio(0);
;   __syncthreads();
;   BSTORE(pf.a0, pf.b0, 0);
;   BLOAD(pf.a0, pf.b0, 2);
;   __syncthreads();
; #pragma unroll
;   for (int kt = 0; kt < nk; kt += 2) {
;     BCOMP(0);
;     BSTORE(pf.a1, pf.b1, 1);
;     if (kt + 3 < nk) BLOAD(pf.a1, pf.b1, kt + 3);
;     __syncthreads();
;     BCOMP(1);
;     if (kt + 2 < nk) { BSTORE(pf.a0, pf.b0, 0); if (kt + 4 < nk) BLOAD(pf.a0, pf.b0, kt + 4); }
;     __syncthreads();
.Linpd_kloop:
	s_waitcnt vmcnt(6)
	s_barrier
	ds_read_b128 v[224:227], v126 offset:0
	ds_read_b128 v[240:243], v128 offset:0
	ds_read_b128 v[244:247], v128 offset:1024
	ds_read_b128 v[248:251], v128 offset:2048
	ds_read_b128 v[156:159], v128 offset:3072
	s_add_u32 m0, s46, 0xc000
	s_add_u32 s48, s48, 0x100000
	s_addc_u32 s49, s49, 0
	global_load_lds_dwordx4 v138, s[48:49]
	global_load_lds_dwordx4 v139, s[48:49] offset:1024
	s_add_u32 m0, s47, 0xc000
	s_add_u32 s50, s50, s13
	s_addc_u32 s51, s51, 0
	global_load_lds_dwordx4 v140, s[50:51]
	global_load_lds_dwordx4 v141, s[50:51] offset:1024
	global_load_lds_dwordx4 v142, s[50:51] offset:2048
	global_load_lds_dwordx4 v143, s[50:51] offset:3072
	ds_read_b128 v[228:231], v126 offset:1024
	ds_read_b128 v[232:235], v126 offset:2048
	ds_read_b128 v[236:239], v126 offset:3072
	ds_read_b128 v[160:163], v128 offset:8192
	ds_read_b128 v[164:167], v128 offset:9216
	ds_read_b128 v[168:171], v128 offset:10240
	ds_read_b128 v[122:125], v128 offset:11264
	s_waitcnt lgkmcnt(7)
	v_mfma_f32_16x16x32_bf16 v[2:5], v[240:243], v[224:227], v[2:5]
	v_mfma_f32_16x16x32_bf16 v[6:9], v[244:247], v[224:227], v[6:9]
	v_mfma_f32_16x16x32_bf16 v[10:13], v[248:251], v[224:227], v[10:13]
	v_mfma_f32_16x16x32_bf16 v[14:17], v[156:159], v[224:227], v[14:17]
	s_waitcnt lgkmcnt(4)
	v_mfma_f32_16x16x32_bf16 v[18:21], v[240:243], v[228:231], v[18:21]
	v_mfma_f32_16x16x32_bf16 v[22:25], v[244:247], v[228:231], v[22:25]
	v_mfma_f32_16x16x32_bf16 v[26:29], v[248:251], v[228:231], v[26:29]
	v_mfma_f32_16x16x32_bf16 v[30:33], v[156:159], v[228:231], v[30:33]
	v_mfma_f32_16x16x32_bf16 v[34:37], v[240:243], v[232:235], v[34:37]
	v_mfma_f32_16x16x32_bf16 v[38:41], v[244:247], v[232:235], v[38:41]
	v_mfma_f32_16x16x32_bf16 v[42:45], v[248:251], v[232:235], v[42:45]
	v_mfma_f32_16x16x32_bf16 v[46:49], v[156:159], v[232:235], v[46:49]
	v_mfma_f32_16x16x32_bf16 v[50:53], v[240:243], v[236:239], v[50:53]
	v_mfma_f32_16x16x32_bf16 v[54:57], v[244:247], v[236:239], v[54:57]
	v_mfma_f32_16x16x32_bf16 v[58:61], v[248:251], v[236:239], v[58:61]
	v_mfma_f32_16x16x32_bf16 v[62:65], v[156:159], v[236:239], v[62:65]
	s_waitcnt lgkmcnt(0)
	v_mfma_f32_16x16x32_bf16 v[74:77], v[160:163], v[224:227], v[74:77]
	v_mfma_f32_16x16x32_bf16 v[78:81], v[164:167], v[224:227], v[78:81]
	v_mfma_f32_16x16x32_bf16 v[82:85], v[168:171], v[224:227], v[82:85]
	v_mfma_f32_16x16x32_bf16 v[86:89], v[122:125], v[224:227], v[86:89]
	v_mfma_f32_16x16x32_bf16 v[90:93], v[160:163], v[228:231], v[90:93]
	v_mfma_f32_16x16x32_bf16 v[94:97], v[164:167], v[228:231], v[94:97]
	v_mfma_f32_16x16x32_bf16 v[98:101], v[168:171], v[228:231], v[98:101]
	v_mfma_f32_16x16x32_bf16 v[102:105], v[122:125], v[228:231], v[102:105]
	v_mfma_f32_16x16x32_bf16 v[106:109], v[160:163], v[232:235], v[106:109]
	v_mfma_f32_16x16x32_bf16 v[110:113], v[164:167], v[232:235], v[110:113]
	v_mfma_f32_16x16x32_bf16 v[114:117], v[168:171], v[232:235], v[114:117]
	v_mfma_f32_16x16x32_bf16 v[118:121], v[122:125], v[232:235], v[118:121]
	v_mfma_f32_16x16x32_bf16 v[208:211], v[160:163], v[236:239], v[208:211]
	v_mfma_f32_16x16x32_bf16 v[212:215], v[164:167], v[236:239], v[212:215]
	v_mfma_f32_16x16x32_bf16 v[216:219], v[168:171], v[236:239], v[216:219]
	v_mfma_f32_16x16x32_bf16 v[220:223], v[122:125], v[236:239], v[220:223]
	s_waitcnt vmcnt(6)
	s_barrier
	ds_read_b128 v[224:227], v126 offset:24576
	ds_read_b128 v[240:243], v128 offset:24576
	ds_read_b128 v[244:247], v128 offset:25600
	ds_read_b128 v[248:251], v128 offset:26624
	ds_read_b128 v[156:159], v128 offset:27648
	s_add_u32 m0, s46, 0x0
	s_add_u32 s48, s48, 0x100000
	s_addc_u32 s49, s49, 0
	global_load_lds_dwordx4 v138, s[48:49]
	global_load_lds_dwordx4 v139, s[48:49] offset:1024
	s_add_u32 m0, s47, 0x0
	s_add_u32 s50, s50, s13
	s_addc_u32 s51, s51, 0
	global_load_lds_dwordx4 v140, s[50:51]
	global_load_lds_dwordx4 v141, s[50:51] offset:1024
	global_load_lds_dwordx4 v142, s[50:51] offset:2048
	global_load_lds_dwordx4 v143, s[50:51] offset:3072
	ds_read_b128 v[228:231], v126 offset:25600
	ds_read_b128 v[232:235], v126 offset:26624
	ds_read_b128 v[236:239], v126 offset:27648
	ds_read_b128 v[160:163], v128 offset:32768
	ds_read_b128 v[164:167], v128 offset:33792
	ds_read_b128 v[168:171], v128 offset:34816
	ds_read_b128 v[122:125], v128 offset:35840
	s_waitcnt lgkmcnt(7)
	v_mfma_f32_16x16x32_bf16 v[2:5], v[240:243], v[224:227], v[2:5]
	v_mfma_f32_16x16x32_bf16 v[6:9], v[244:247], v[224:227], v[6:9]
	v_mfma_f32_16x16x32_bf16 v[10:13], v[248:251], v[224:227], v[10:13]
	v_mfma_f32_16x16x32_bf16 v[14:17], v[156:159], v[224:227], v[14:17]
	s_waitcnt lgkmcnt(4)
	v_mfma_f32_16x16x32_bf16 v[18:21], v[240:243], v[228:231], v[18:21]
	v_mfma_f32_16x16x32_bf16 v[22:25], v[244:247], v[228:231], v[22:25]
	v_mfma_f32_16x16x32_bf16 v[26:29], v[248:251], v[228:231], v[26:29]
	v_mfma_f32_16x16x32_bf16 v[30:33], v[156:159], v[228:231], v[30:33]
	v_mfma_f32_16x16x32_bf16 v[34:37], v[240:243], v[232:235], v[34:37]
	v_mfma_f32_16x16x32_bf16 v[38:41], v[244:247], v[232:235], v[38:41]
	v_mfma_f32_16x16x32_bf16 v[42:45], v[248:251], v[232:235], v[42:45]
	v_mfma_f32_16x16x32_bf16 v[46:49], v[156:159], v[232:235], v[46:49]
	v_mfma_f32_16x16x32_bf16 v[50:53], v[240:243], v[236:239], v[50:53]
	v_mfma_f32_16x16x32_bf16 v[54:57], v[244:247], v[236:239], v[54:57]
	v_mfma_f32_16x16x32_bf16 v[58:61], v[248:251], v[236:239], v[58:61]
	v_mfma_f32_16x16x32_bf16 v[62:65], v[156:159], v[236:239], v[62:65]
	s_waitcnt lgkmcnt(0)
	v_mfma_f32_16x16x32_bf16 v[74:77], v[160:163], v[224:227], v[74:77]
	v_mfma_f32_16x16x32_bf16 v[78:81], v[164:167], v[224:227], v[78:81]
	v_mfma_f32_16x16x32_bf16 v[82:85], v[168:171], v[224:227], v[82:85]
	v_mfma_f32_16x16x32_bf16 v[86:89], v[122:125], v[224:227], v[86:89]
	v_mfma_f32_16x16x32_bf16 v[90:93], v[160:163], v[228:231], v[90:93]
	v_mfma_f32_16x16x32_bf16 v[94:97], v[164:167], v[228:231], v[94:97]
	v_mfma_f32_16x16x32_bf16 v[98:101], v[168:171], v[228:231], v[98:101]
	v_mfma_f32_16x16x32_bf16 v[102:105], v[122:125], v[228:231], v[102:105]
	v_mfma_f32_16x16x32_bf16 v[106:109], v[160:163], v[232:235], v[106:109]
	v_mfma_f32_16x16x32_bf16 v[110:113], v[164:167], v[232:235], v[110:113]
	v_mfma_f32_16x16x32_bf16 v[114:117], v[168:171], v[232:235], v[114:117]
	v_mfma_f32_16x16x32_bf16 v[118:121], v[122:125], v[232:235], v[118:121]
	v_mfma_f32_16x16x32_bf16 v[208:211], v[160:163], v[236:239], v[208:211]
	v_mfma_f32_16x16x32_bf16 v[212:215], v[164:167], v[236:239], v[212:215]
	v_mfma_f32_16x16x32_bf16 v[216:219], v[168:171], v[236:239], v[216:219]
	v_mfma_f32_16x16x32_bf16 v[220:223], v[122:125], v[236:239], v[220:223]
	s_waitcnt vmcnt(6)
	s_barrier
; #define BLOAD(A_, B_, kt) do { _Pragma("unroll") for (int i = 0; i < 4; ++i) { \
;     A_[i] = *(const u32x4*)((const char*)Ap + (aoff + (unsigned)(32 * i * lda + (kt) * 64) * 2u)); B_[i] = *(const u32x4*)((const char*)Wt + (woff + (unsigned)(32 * i * K + (kt) * 64) * 2u)); } } while (0)
; #define BLOAD(A_, B_, kt) do { _Pragma("unroll") for (int i = 0; i < 4; ++i) { \
;     A_[i] = *(const u32x4*)((const char*)Ap + (aoff + (unsigned)(32 * i * lda + (kt) * 64) * 2u)); B_[i] = *(const u32x4*)((const char*)Wt + (woff + (unsigned)(32 * i * K + (kt) * 64) * 2u)); } } while (0)
; #define BSTORE(A_, B_, buf) do { _Pragma("unroll") for (int i = 0; i < 4; ++i) { \
;     *(u32x4*)&As[(buf) * GBUF + (srow + 32 * i) * LDT + sc8] = A_[i]; \
;     *(u32x4*)&Bs[(buf) * GBUF + (srow + 32 * i) * LDT + sc8] = B_[i]; } } while (0)
; template <int NK>
; DI void gemm_run(PF& pf, const u16* __restrict__ Ap, int lda, const u16* __restrict__ Wt, f32x16 (&acc)[2][2], char* smem) {
;     ...
;   __builtin_amdgcn_s_setprio(0);
;   __syncthreads();
;   BSTORE(pf.a0, pf.b0, 0);
;   BLOAD(pf.a0, pf.b0, 2);
;   __syncthreads();
; #pragma unroll
;   for (int kt = 0; kt < nk; kt += 2) {
;     BCOMP(0);
;     BSTORE(pf.a1, pf.b1, 1);
;     if (kt + 3 < nk) BLOAD(pf.a1, pf.b1, kt + 3);
;     __syncthreads();
;     BCOMP(1);
;     if (kt + 2 < nk) { BSTORE(pf.a0, pf.b0, 0); if (kt + 4 < nk) BLOAD(pf.a0, pf.b0, kt + 4); }
;     __syncthreads();
	ds_read_b128 v[224:227], v126 offset:49152
	ds_read_b128 v[240:243], v128 offset:49152
	ds_read_b128 v[244:247], v128 offset:50176
	ds_read_b128 v[248:251], v128 offset:51200
	ds_read_b128 v[156:159], v128 offset:52224
	s_add_u32 m0, s46, 0x6000
	s_add_u32 s48, s48, 0x100000
	s_addc_u32 s49, s49, 0
	global_load_lds_dwordx4 v138, s[48:49]
	global_load_lds_dwordx4 v139, s[48:49] offset:1024
	s_add_u32 m0, s47, 0x6000
	s_add_u32 s50, s50, s13
	s_addc_u32 s51, s51, 0
	global_load_lds_dwordx4 v140, s[50:51]
	global_load_lds_dwordx4 v141, s[50:51] offset:1024
	global_load_lds_dwordx4 v142, s[50:51] offset:2048
	global_load_lds_dwordx4 v143, s[50:51] offset:3072
	ds_read_b128 v[228:231], v126 offset:50176
	ds_read_b128 v[232:235], v126 offset:51200
	ds_read_b128 v[236:239], v126 offset:52224
	ds_read_b128 v[160:163], v128 offset:57344
	ds_read_b128 v[164:167], v128 offset:58368
	ds_read_b128 v[168:171], v128 offset:59392
	ds_read_b128 v[122:125], v128 offset:60416
	s_waitcnt lgkmcnt(7)
	v_mfma_f32_16x16x32_bf16 v[2:5], v[240:243], v[224:227], v[2:5]
	v_mfma_f32_16x16x32_bf16 v[6:9], v[244:247], v[224:227], v[6:9]
	v_mfma_f32_16x16x32_bf16 v[10:13], v[248:251], v[224:227], v[10:13]
	v_mfma_f32_16x16x32_bf16 v[14:17], v[156:159], v[224:227], v[14:17]
	s_waitcnt lgkmcnt(4)
	v_mfma_f32_16x16x32_bf16 v[18:21], v[240:243], v[228:231], v[18:21]
	v_mfma_f32_16x16x32_bf16 v[22:25], v[244:247], v[228:231], v[22:25]
	v_mfma_f32_16x16x32_bf16 v[26:29], v[248:251], v[228:231], v[26:29]
	v_mfma_f32_16x16x32_bf16 v[30:33], v[156:159], v[228:231], v[30:33]
	v_mfma_f32_16x16x32_bf16 v[34:37], v[240:243], v[232:235], v[34:37]
	v_mfma_f32_16x16x32_bf16 v[38:41], v[244:247], v[232:235], v[38:41]
	v_mfma_f32_16x16x32_bf16 v[42:45], v[248:251], v[232:235], v[42:45]
	v_mfma_f32_16x16x32_bf16 v[46:49], v[156:159], v[232:235], v[46:49]
	v_mfma_f32_16x16x32_bf16 v[50:53], v[240:243], v[236:239], v[50:53]
	v_mfma_f32_16x16x32_bf16 v[54:57], v[244:247], v[236:239], v[54:57]
	v_mfma_f32_16x16x32_bf16 v[58:61], v[248:251], v[236:239], v[58:61]
	v_mfma_f32_16x16x32_bf16 v[62:65], v[156:159], v[236:239], v[62:65]
	s_waitcnt lgkmcnt(0)
	v_mfma_f32_16x16x32_bf16 v[74:77], v[160:163], v[224:227], v[74:77]
	v_mfma_f32_16x16x32_bf16 v[78:81], v[164:167], v[224:227], v[78:81]
	v_mfma_f32_16x16x32_bf16 v[82:85], v[168:171], v[224:227], v[82:85]
	v_mfma_f32_16x16x32_bf16 v[86:89], v[122:125], v[224:227], v[86:89]
	v_mfma_f32_16x16x32_bf16 v[90:93], v[160:163], v[228:231], v[90:93]
	v_mfma_f32_16x16x32_bf16 v[94:97], v[164:167], v[228:231], v[94:97]
	v_mfma_f32_16x16x32_bf16 v[98:101], v[168:171], v[228:231], v[98:101]
	v_mfma_f32_16x16x32_bf16 v[102:105], v[122:125], v[228:231], v[102:105]
	v_mfma_f32_16x16x32_bf16 v[106:109], v[160:163], v[232:235], v[106:109]
	v_mfma_f32_16x16x32_bf16 v[110:113], v[164:167], v[232:235], v[110:113]
	v_mfma_f32_16x16x32_bf16 v[114:117], v[168:171], v[232:235], v[114:117]
	v_mfma_f32_16x16x32_bf16 v[118:121], v[122:125], v[232:235], v[118:121]
	v_mfma_f32_16x16x32_bf16 v[208:211], v[160:163], v[236:239], v[208:211]
	v_mfma_f32_16x16x32_bf16 v[212:215], v[164:167], v[236:239], v[212:215]
	v_mfma_f32_16x16x32_bf16 v[216:219], v[168:171], v[236:239], v[216:219]
	v_mfma_f32_16x16x32_bf16 v[220:223], v[122:125], v[236:239], v[220:223]
	s_sub_u32 s12, s12, 1
	s_cmp_lg_u32 s12, 0
	s_cbranch_scc1 .Linpd_kloop
	s_waitcnt vmcnt(6)
	s_barrier
; #define BLOAD(A_, B_, kt) do { _Pragma("unroll") for (int i = 0; i < 4; ++i) { \
;     A_[i] = *(const u32x4*)((const char*)Ap + (aoff + (unsigned)(32 * i * lda + (kt) * 64) * 2u)); B_[i] = *(const u32x4*)((const char*)Wt + (woff + (unsigned)(32 * i * K + (kt) * 64) * 2u)); } } while (0)
; #define BLOAD(A_, B_, kt) do { _Pragma("unroll") for (int i = 0; i < 4; ++i) { \
;     A_[i] = *(const u32x4*)((const char*)Ap + (aoff + (unsigned)(32 * i * lda + (kt) * 64) * 2u)); B_[i] = *(const u32x4*)((const char*)Wt + (woff + (unsigned)(32 * i * K + (kt) * 64) * 2u)); } } while (0)
; #define BSTORE(A_, B_, buf) do { _Pragma("unroll") for (int i = 0; i < 4; ++i) { \
;     *(u32x4*)&As[(buf) * GBUF + (srow + 32 * i) * LDT + sc8] = A_[i]; \
;     *(u32x4*)&Bs[(buf) * GBUF + (srow + 32 * i) * LDT + sc8] = B_[i]; } } while (0)
; template <int NK>
; DI void gemm_run(PF& pf, const u16* __restrict__ Ap, int lda, const u16* __restrict__ Wt, f32x16 (&acc)[2][2], char* smem) {
;     ...
; #pragma unroll
;   for (int kt = 0; kt < nk; kt += 2) {
;     BCOMP(0);
;     BSTORE(pf.a1, pf.b1, 1);
;     if (kt + 3 < nk) BLOAD(pf.a1, pf.b1, kt + 3);
;     __syncthreads();
;     BCOMP(1);
;     if (kt + 2 < nk) { BSTORE(pf.a0, pf.b0, 0); if (kt + 4 < nk) BLOAD(pf.a0, pf.b0, kt + 4); }
;     __syncthreads();
;   }
	ds_read_b128 v[224:227], v126 offset:0
	ds_read_b128 v[240:243], v128 offset:0
	ds_read_b128 v[244:247], v128 offset:1024
	ds_read_b128 v[248:251], v128 offset:2048
	ds_read_b128 v[156:159], v128 offset:3072
	ds_read_b128 v[228:231], v126 offset:1024
	ds_read_b128 v[232:235], v126 offset:2048
	ds_read_b128 v[236:239], v126 offset:3072
	ds_read_b128 v[160:163], v128 offset:8192
	ds_read_b128 v[164:167], v128 offset:9216
	ds_read_b128 v[168:171], v128 offset:10240
	ds_read_b128 v[122:125], v128 offset:11264
	s_waitcnt lgkmcnt(7)
	v_mfma_f32_16x16x32_bf16 v[2:5], v[240:243], v[224:227], v[2:5]
	v_mfma_f32_16x16x32_bf16 v[6:9], v[244:247], v[224:227], v[6:9]
	v_mfma_f32_16x16x32_bf16 v[10:13], v[248:251], v[224:227], v[10:13]
	v_mfma_f32_16x16x32_bf16 v[14:17], v[156:159], v[224:227], v[14:17]
	s_waitcnt lgkmcnt(4)
	v_mfma_f32_16x16x32_bf16 v[18:21], v[240:243], v[228:231], v[18:21]
	v_mfma_f32_16x16x32_bf16 v[22:25], v[244:247], v[228:231], v[22:25]
	v_mfma_f32_16x16x32_bf16 v[26:29], v[248:251], v[228:231], v[26:29]
	v_mfma_f32_16x16x32_bf16 v[30:33], v[156:159], v[228:231], v[30:33]
	v_mfma_f32_16x16x32_bf16 v[34:37], v[240:243], v[232:235], v[34:37]
	v_mfma_f32_16x16x32_bf16 v[38:41], v[244:247], v[232:235], v[38:41]
	v_mfma_f32_16x16x32_bf16 v[42:45], v[248:251], v[232:235], v[42:45]
	v_mfma_f32_16x16x32_bf16 v[46:49], v[156:159], v[232:235], v[46:49]
	v_mfma_f32_16x16x32_bf16 v[50:53], v[240:243], v[236:239], v[50:53]
	v_mfma_f32_16x16x32_bf16 v[54:57], v[244:247], v[236:239], v[54:57]
	v_mfma_f32_16x16x32_bf16 v[58:61], v[248:251], v[236:239], v[58:61]
	v_mfma_f32_16x16x32_bf16 v[62:65], v[156:159], v[236:239], v[62:65]
	s_waitcnt lgkmcnt(0)
	v_mfma_f32_16x16x32_bf16 v[74:77], v[160:163], v[224:227], v[74:77]
	v_mfma_f32_16x16x32_bf16 v[78:81], v[164:167], v[224:227], v[78:81]
	v_mfma_f32_16x16x32_bf16 v[82:85], v[168:171], v[224:227], v[82:85]
	v_mfma_f32_16x16x32_bf16 v[86:89], v[122:125], v[224:227], v[86:89]
	v_mfma_f32_16x16x32_bf16 v[90:93], v[160:163], v[228:231], v[90:93]
	v_mfma_f32_16x16x32_bf16 v[94:97], v[164:167], v[228:231], v[94:97]
	v_mfma_f32_16x16x32_bf16 v[98:101], v[168:171], v[228:231], v[98:101]
	v_mfma_f32_16x16x32_bf16 v[102:105], v[122:125], v[228:231], v[102:105]
	v_mfma_f32_16x16x32_bf16 v[106:109], v[160:163], v[232:235], v[106:109]
	v_mfma_f32_16x16x32_bf16 v[110:113], v[164:167], v[232:235], v[110:113]
	v_mfma_f32_16x16x32_bf16 v[114:117], v[168:171], v[232:235], v[114:117]
	v_mfma_f32_16x16x32_bf16 v[118:121], v[122:125], v[232:235], v[118:121]
	v_mfma_f32_16x16x32_bf16 v[208:211], v[160:163], v[236:239], v[208:211]
	v_mfma_f32_16x16x32_bf16 v[212:215], v[164:167], v[236:239], v[212:215]
	v_mfma_f32_16x16x32_bf16 v[216:219], v[168:171], v[236:239], v[216:219]
	v_mfma_f32_16x16x32_bf16 v[220:223], v[122:125], v[236:239], v[220:223]
	s_waitcnt vmcnt(0)
	s_barrier
	ds_read_b128 v[224:227], v126 offset:24576
	ds_read_b128 v[240:243], v128 offset:24576
	ds_read_b128 v[244:247], v128 offset:25600
	ds_read_b128 v[248:251], v128 offset:26624
	ds_read_b128 v[156:159], v128 offset:27648
	ds_read_b128 v[228:231], v126 offset:25600
	ds_read_b128 v[232:235], v126 offset:26624
	ds_read_b128 v[236:239], v126 offset:27648
	ds_read_b128 v[160:163], v128 offset:32768
	ds_read_b128 v[164:167], v128 offset:33792
	ds_read_b128 v[168:171], v128 offset:34816
	ds_read_b128 v[122:125], v128 offset:35840
	s_waitcnt lgkmcnt(7)
	v_mfma_f32_16x16x32_bf16 v[2:5], v[240:243], v[224:227], v[2:5]
	v_mfma_f32_16x16x32_bf16 v[6:9], v[244:247], v[224:227], v[6:9]
	v_mfma_f32_16x16x32_bf16 v[10:13], v[248:251], v[224:227], v[10:13]
	v_mfma_f32_16x16x32_bf16 v[14:17], v[156:159], v[224:227], v[14:17]
	s_waitcnt lgkmcnt(4)
	v_mfma_f32_16x16x32_bf16 v[18:21], v[240:243], v[228:231], v[18:21]
	v_mfma_f32_16x16x32_bf16 v[22:25], v[244:247], v[228:231], v[22:25]
	v_mfma_f32_16x16x32_bf16 v[26:29], v[248:251], v[228:231], v[26:29]
	v_mfma_f32_16x16x32_bf16 v[30:33], v[156:159], v[228:231], v[30:33]
	v_mfma_f32_16x16x32_bf16 v[34:37], v[240:243], v[232:235], v[34:37]
	v_mfma_f32_16x16x32_bf16 v[38:41], v[244:247], v[232:235], v[38:41]
	v_mfma_f32_16x16x32_bf16 v[42:45], v[248:251], v[232:235], v[42:45]
	v_mfma_f32_16x16x32_bf16 v[46:49], v[156:159], v[232:235], v[46:49]
	v_mfma_f32_16x16x32_bf16 v[50:53], v[240:243], v[236:239], v[50:53]
	v_mfma_f32_16x16x32_bf16 v[54:57], v[244:247], v[236:239], v[54:57]
	v_mfma_f32_16x16x32_bf16 v[58:61], v[248:251], v[236:239], v[58:61]
	v_mfma_f32_16x16x32_bf16 v[62:65], v[156:159], v[236:239], v[62:65]
	s_waitcnt lgkmcnt(0)
	v_mfma_f32_16x16x32_bf16 v[74:77], v[160:163], v[224:227], v[74:77]
	v_mfma_f32_16x16x32_bf16 v[78:81], v[164:167], v[224:227], v[78:81]
	v_mfma_f32_16x16x32_bf16 v[82:85], v[168:171], v[224:227], v[82:85]
	v_mfma_f32_16x16x32_bf16 v[86:89], v[122:125], v[224:227], v[86:89]
	v_mfma_f32_16x16x32_bf16 v[90:93], v[160:163], v[228:231], v[90:93]
	v_mfma_f32_16x16x32_bf16 v[94:97], v[164:167], v[228:231], v[94:97]
	v_mfma_f32_16x16x32_bf16 v[98:101], v[168:171], v[228:231], v[98:101]
	v_mfma_f32_16x16x32_bf16 v[102:105], v[122:125], v[228:231], v[102:105]
	v_mfma_f32_16x16x32_bf16 v[106:109], v[160:163], v[232:235], v[106:109]
	v_mfma_f32_16x16x32_bf16 v[110:113], v[164:167], v[232:235], v[110:113]
	v_mfma_f32_16x16x32_bf16 v[114:117], v[168:171], v[232:235], v[114:117]
	v_mfma_f32_16x16x32_bf16 v[118:121], v[122:125], v[232:235], v[118:121]
	v_mfma_f32_16x16x32_bf16 v[208:211], v[160:163], v[236:239], v[208:211]
	v_mfma_f32_16x16x32_bf16 v[212:215], v[164:167], v[236:239], v[212:215]
	v_mfma_f32_16x16x32_bf16 v[216:219], v[168:171], v[236:239], v[216:219]
	v_mfma_f32_16x16x32_bf16 v[220:223], v[122:125], v[236:239], v[220:223]
	s_barrier
	s_branch .Linp_post
